# plus: GEMM wave groups no longer re-align before each tile epilogue (one group stores while the other still runs its last MFMA slot)
# speedup vs baseline: 1.0103x; 1.0012x over previous
; #define PG8_STAGE(bufoff, gbase, voff) do { _Pragma("unroll") for (int _i = 0; _i < 2; ++_i) \
;         __builtin_amdgcn_global_load_lds((const unsigned*)((const char*)(gbase) + (voff)[_i]), (LAS unsigned*)(lds + (bufoff) + ldsw + _i * 8192), 16, 0, 0); } while (0)
; #define PG8_LDA(dst, b, h) do { _Pragma("unroll") for (int m = 0; m < 4; ++m) _Pragma("unroll") for (int k = 0; k < 2; ++k) dst[m][k] = *(const LAS bf16x8*)(lds + PG8_SA(b, h) + aoff + m * 2048 + k * 1024); } while (0)
; #define PG8_LDB(dst, b, h) do { _Pragma("unroll") for (int n = 0; n < 2; ++n) _Pragma("unroll") for (int k = 0; k < 2; ++k) dst[n][k] = *(const LAS bf16x8*)(lds + PG8_SB(b, h) + boff + n * 2048 + k * 1024); } while (0)
; #define PG8_MMA(ai, bj, At, Bt) do { __builtin_amdgcn_s_setprio(1); _Pragma("unroll") for (int m = 0; m < 4; ++m) _Pragma("unroll") for (int n = 0; n < 2; ++n) _Pragma("unroll") for (int k = 0; k < 2; ++k) \
;         acc[ai][bj][m][n] = __builtin_amdgcn_mfma_f32_16x16x32_bf16(Bt[n][k], At[m][k], acc[ai][bj][m][n], 0, 0, 0); __builtin_amdgcn_s_setprio(0); } while (0)
; #define PG8_WAIT_V(n) asm volatile("s_waitcnt vmcnt(" #n ")" ::: "memory")
; #define PG8_WAIT_L(n) asm volatile("s_waitcnt lgkmcnt(" #n ")" ::: "memory")
; #define PG8_BAR __builtin_amdgcn_s_barrier()
; #define PG8_SCHED __builtin_amdgcn_sched_barrier(0)
; template <class Epi, class Sched, bool ALIGN_EPI = false, bool SP2 = false>
; __device__ __forceinline__ void gemm_phase(LAS unsigned char* lds, const Gemm g, const Sched& S, const Epi& E, const int tid_) {
;     ...
;             if constexpr (SP2) {
;             PG8_LDB(B0, 0, 0); PG8_LDB(B1, 0, 1); PG8_SCHED; PG8_LDA(At, 0, 0); PG8_STAGE(PG8_SA(1, 1), a1 + hstep, voffA);
;             PG8_WAIT_V(8); PG8_WAIT_L(0); PG8_BAR; PG8_MMA(0, 0, At, B0); PG8_MMA(0, 1, At, B1); PG8_BAR; PG8_SCHED;
;             PG8_LDA(At, 0, 1); PG8_STAGE(PG8_SB(0, 0), b2, voffB); PG8_STAGE(PG8_SB(0, 1), b2 + hstep, voffB); PG8_STAGE(PG8_SA(0, 0), a2, voffA);
;             PG8_WAIT_V(8); PG8_WAIT_L(0); PG8_BAR; PG8_MMA(1, 0, At, B0); PG8_MMA(1, 1, At, B1); PG8_BAR; PG8_SCHED;
.LBB0_34:
	s_add_u32 s48, s46, 0xfff80080
	s_addc_u32 s49, s47, -1
	s_add_i32 s68, 0, 0x10000
	s_cmp_eq_u32 s67, 28
	s_cselect_b32 s51, s17, s49
	s_cselect_b32 s50, s21, s48
	v_add_u32_e32 v140, s68, v143
	s_cselect_b32 s49, s15, s66
	s_cselect_b32 s48, s64, s65
	s_add_i32 s70, 0, 0x14000
	s_nop 0
	ds_read_b128 v[146:149], v140
	ds_read_b128 v[150:153], v140 offset:1024
	ds_read_b128 v[154:157], v140 offset:2048
	ds_read_b128 v[158:161], v140 offset:3072
	v_add_u32_e32 v140, s70, v143
	ds_read_b128 v[162:165], v140
	ds_read_b128 v[166:169], v140 offset:1024
	ds_read_b128 v[170:173], v140 offset:2048
	ds_read_b128 v[174:177], v140 offset:3072
	s_add_i32 m0, s45, 0xc000
	ds_read_b128 v[178:181], v145
	ds_read_b128 v[182:185], v145 offset:1024
	ds_read_b128 v[200:203], v145 offset:2048
	ds_read_b128 v[204:207], v145 offset:3072
	ds_read_b128 v[208:211], v145 offset:4096
	ds_read_b128 v[212:215], v145 offset:5120
	ds_read_b128 v[216:219], v145 offset:6144
	ds_read_b128 v[220:223], v145 offset:7168
	global_load_lds_dwordx4 v136, s[46:47]
	s_add_i32 m0, s45, 0xe000
	s_nop 0
	global_load_lds_dwordx4 v138, s[46:47]
	s_waitcnt vmcnt(8)
	s_waitcnt lgkmcnt(0)
	s_barrier
	s_setprio 1
	s_waitcnt lgkmcnt(0)
	v_mfma_f32_16x16x32_bf16 v[126:129], v[146:149], v[178:181], v[126:129]
	v_mfma_f32_16x16x32_bf16 v[122:125], v[154:157], v[178:181], v[122:125]
	v_mfma_f32_16x16x32_bf16 v[110:113], v[146:149], v[200:203], v[110:113]
	v_mfma_f32_16x16x32_bf16 v[106:109], v[154:157], v[200:203], v[106:109]
	v_mfma_f32_16x16x32_bf16 v[94:97], v[146:149], v[208:211], v[94:97]
	v_mfma_f32_16x16x32_bf16 v[90:93], v[154:157], v[208:211], v[90:93]
	v_mfma_f32_16x16x32_bf16 v[78:81], v[146:149], v[216:219], v[78:81]
	v_mfma_f32_16x16x32_bf16 v[74:77], v[154:157], v[216:219], v[74:77]
	v_mfma_f32_16x16x32_bf16 v[126:129], v[150:153], v[182:185], v[126:129]
	v_mfma_f32_16x16x32_bf16 v[122:125], v[158:161], v[182:185], v[122:125]
	v_mfma_f32_16x16x32_bf16 v[110:113], v[150:153], v[204:207], v[110:113]
	v_mfma_f32_16x16x32_bf16 v[106:109], v[158:161], v[204:207], v[106:109]
	v_mfma_f32_16x16x32_bf16 v[94:97], v[150:153], v[212:215], v[94:97]
	v_mfma_f32_16x16x32_bf16 v[90:93], v[158:161], v[212:215], v[90:93]
	v_mfma_f32_16x16x32_bf16 v[78:81], v[150:153], v[220:223], v[78:81]
	v_mfma_f32_16x16x32_bf16 v[74:77], v[158:161], v[220:223], v[74:77]
	s_setprio 0
	s_setprio 1
	v_mfma_f32_16x16x32_bf16 v[118:121], v[162:165], v[178:181], v[118:121]
	v_mfma_f32_16x16x32_bf16 v[114:117], v[170:173], v[178:181], v[114:117]
	v_mfma_f32_16x16x32_bf16 v[102:105], v[162:165], v[200:203], v[102:105]
	v_mfma_f32_16x16x32_bf16 v[98:101], v[170:173], v[200:203], v[98:101]
	v_mfma_f32_16x16x32_bf16 v[86:89], v[162:165], v[208:211], v[86:89]
	v_mfma_f32_16x16x32_bf16 v[82:85], v[170:173], v[208:211], v[82:85]
	v_mfma_f32_16x16x32_bf16 v[70:73], v[162:165], v[216:219], v[70:73]
	v_mfma_f32_16x16x32_bf16 v[66:69], v[170:173], v[216:219], v[66:69]
	v_mfma_f32_16x16x32_bf16 v[118:121], v[166:169], v[182:185], v[118:121]
	v_mfma_f32_16x16x32_bf16 v[114:117], v[174:177], v[182:185], v[114:117]
	v_mfma_f32_16x16x32_bf16 v[102:105], v[166:169], v[204:207], v[102:105]
	v_mfma_f32_16x16x32_bf16 v[98:101], v[174:177], v[204:207], v[98:101]
	v_mfma_f32_16x16x32_bf16 v[86:89], v[166:169], v[212:215], v[86:89]
	v_mfma_f32_16x16x32_bf16 v[82:85], v[174:177], v[212:215], v[82:85]
	v_mfma_f32_16x16x32_bf16 v[70:73], v[166:169], v[220:223], v[70:73]
	v_mfma_f32_16x16x32_bf16 v[66:69], v[174:177], v[220:223], v[66:69]
	s_setprio 0
	s_barrier
	s_add_i32 s68, s68, s55
	s_mov_b32 m0, s68
	ds_read_b128 v[178:181], v145 offset:16384
	ds_read_b128 v[182:185], v145 offset:17408
	ds_read_b128 v[200:203], v145 offset:18432
	ds_read_b128 v[204:207], v145 offset:19456
	ds_read_b128 v[208:211], v145 offset:20480
	ds_read_b128 v[212:215], v145 offset:21504
	ds_read_b128 v[216:219], v145 offset:22528
	ds_read_b128 v[220:223], v145 offset:23552
	global_load_lds_dwordx4 v0, s[48:49]
	s_add_i32 m0, s68, 0x2000
	s_add_u32 s68, s48, 0x80000
	v_lshl_add_u64 v[192:193], s[48:49], 0, v[134:135]
	s_addc_u32 s69, s49, 0
	s_add_i32 s70, s70, s55
	global_load_lds_dwordx4 v134, s[48:49]
	s_mov_b32 m0, s70
	v_lshl_add_u64 v[236:237], s[50:51], 0, v[132:133]
	global_load_lds_dwordx4 v0, s[68:69]
	s_add_i32 m0, s70, 0x2000
	s_nop 0
	global_load_lds_dwordx4 v134, s[68:69]
	v_lshl_add_u64 v[224:225], s[50:51], 0, v[130:131]
	s_mov_b32 m0, s45
	s_nop 0
	global_load_lds_dwordx4 v130, s[50:51]
	s_mov_b32 m0, s56
	s_nop 0
	global_load_lds_dwordx4 v132, s[50:51]
	s_waitcnt vmcnt(8)
	s_waitcnt lgkmcnt(0)
	s_barrier
; #define PG8_STAGE(bufoff, gbase, voff) do { _Pragma("unroll") for (int _i = 0; _i < 2; ++_i) \
;         __builtin_amdgcn_global_load_lds((const unsigned*)((const char*)(gbase) + (voff)[_i]), (LAS unsigned*)(lds + (bufoff) + ldsw + _i * 8192), 16, 0, 0); } while (0)
; #define PG8_LDA(dst, b, h) do { _Pragma("unroll") for (int m = 0; m < 4; ++m) _Pragma("unroll") for (int k = 0; k < 2; ++k) dst[m][k] = *(const LAS bf16x8*)(lds + PG8_SA(b, h) + aoff + m * 2048 + k * 1024); } while (0)
; #define PG8_LDB(dst, b, h) do { _Pragma("unroll") for (int n = 0; n < 2; ++n) _Pragma("unroll") for (int k = 0; k < 2; ++k) dst[n][k] = *(const LAS bf16x8*)(lds + PG8_SB(b, h) + boff + n * 2048 + k * 1024); } while (0)
; #define PG8_MMA(ai, bj, At, Bt) do { __builtin_amdgcn_s_setprio(1); _Pragma("unroll") for (int m = 0; m < 4; ++m) _Pragma("unroll") for (int n = 0; n < 2; ++n) _Pragma("unroll") for (int k = 0; k < 2; ++k) \
;         acc[ai][bj][m][n] = __builtin_amdgcn_mfma_f32_16x16x32_bf16(Bt[n][k], At[m][k], acc[ai][bj][m][n], 0, 0, 0); __builtin_amdgcn_s_setprio(0); } while (0)
; #define PG8_WAIT_V(n) asm volatile("s_waitcnt vmcnt(" #n ")" ::: "memory")
; #define PG8_WAIT_L(n) asm volatile("s_waitcnt lgkmcnt(" #n ")" ::: "memory")
; #define PG8_BAR __builtin_amdgcn_s_barrier()
; #define PG8_SCHED __builtin_amdgcn_sched_barrier(0)
; template <class Epi, class Sched, bool ALIGN_EPI = false, bool SP2 = false>
; __device__ __forceinline__ void gemm_phase(LAS unsigned char* lds, const Gemm g, const Sched& S, const Epi& E, const int tid_) {
;     ...
;             PG8_WAIT_V(8); PG8_WAIT_L(0); PG8_BAR; PG8_MMA(1, 0, At, B0); PG8_MMA(1, 1, At, B1); PG8_BAR; PG8_SCHED;
;             PG8_LDB(B0, 1, 0); PG8_LDB(B1, 1, 1); PG8_SCHED; PG8_LDA(At, 1, 0); PG8_STAGE(PG8_SA(0, 1), a2 + hstep, voffA);
;             PG8_WAIT_V(8); PG8_WAIT_L(0); PG8_BAR; PG8_MMA(0, 0, At, B0); PG8_MMA(0, 1, At, B1); PG8_BAR; PG8_SCHED;
	s_setprio 1
	s_waitcnt lgkmcnt(0)
	v_mfma_f32_16x16x32_bf16 v[62:65], v[146:149], v[178:181], v[62:65]
	v_mfma_f32_16x16x32_bf16 v[58:61], v[154:157], v[178:181], v[58:61]
	v_mfma_f32_16x16x32_bf16 v[46:49], v[146:149], v[200:203], v[46:49]
	v_mfma_f32_16x16x32_bf16 v[42:45], v[154:157], v[200:203], v[42:45]
	v_mfma_f32_16x16x32_bf16 v[30:33], v[146:149], v[208:211], v[30:33]
	v_mfma_f32_16x16x32_bf16 v[26:29], v[154:157], v[208:211], v[26:29]
	v_mfma_f32_16x16x32_bf16 v[14:17], v[146:149], v[216:219], v[14:17]
	v_mfma_f32_16x16x32_bf16 v[10:13], v[154:157], v[216:219], v[10:13]
	v_mfma_f32_16x16x32_bf16 v[62:65], v[150:153], v[182:185], v[62:65]
	v_mfma_f32_16x16x32_bf16 v[58:61], v[158:161], v[182:185], v[58:61]
	v_mfma_f32_16x16x32_bf16 v[46:49], v[150:153], v[204:207], v[46:49]
	v_mfma_f32_16x16x32_bf16 v[42:45], v[158:161], v[204:207], v[42:45]
	v_mfma_f32_16x16x32_bf16 v[30:33], v[150:153], v[212:215], v[30:33]
	v_mfma_f32_16x16x32_bf16 v[26:29], v[158:161], v[212:215], v[26:29]
	v_mfma_f32_16x16x32_bf16 v[14:17], v[150:153], v[220:223], v[14:17]
	v_mfma_f32_16x16x32_bf16 v[10:13], v[158:161], v[220:223], v[10:13]
	s_setprio 0
	s_setprio 1
	v_mfma_f32_16x16x32_bf16 v[54:57], v[162:165], v[178:181], v[54:57]
	v_mfma_f32_16x16x32_bf16 v[50:53], v[170:173], v[178:181], v[50:53]
	v_mfma_f32_16x16x32_bf16 v[38:41], v[162:165], v[200:203], v[38:41]
	v_mfma_f32_16x16x32_bf16 v[34:37], v[170:173], v[200:203], v[34:37]
	v_mfma_f32_16x16x32_bf16 v[22:25], v[162:165], v[208:211], v[22:25]
	v_mfma_f32_16x16x32_bf16 v[18:21], v[170:173], v[208:211], v[18:21]
	v_mfma_f32_16x16x32_bf16 v[6:9], v[162:165], v[216:219], v[6:9]
	v_mfma_f32_16x16x32_bf16 v[2:5], v[170:173], v[216:219], v[2:5]
	v_mfma_f32_16x16x32_bf16 v[54:57], v[166:169], v[182:185], v[54:57]
	v_mfma_f32_16x16x32_bf16 v[50:53], v[174:177], v[182:185], v[50:53]
	v_mfma_f32_16x16x32_bf16 v[38:41], v[166:169], v[204:207], v[38:41]
	v_mfma_f32_16x16x32_bf16 v[34:37], v[174:177], v[204:207], v[34:37]
	v_mfma_f32_16x16x32_bf16 v[22:25], v[166:169], v[212:215], v[22:25]
	v_mfma_f32_16x16x32_bf16 v[18:21], v[174:177], v[212:215], v[18:21]
	v_mfma_f32_16x16x32_bf16 v[6:9], v[166:169], v[220:223], v[6:9]
	v_mfma_f32_16x16x32_bf16 v[2:5], v[174:177], v[220:223], v[2:5]
	s_setprio 0
	s_barrier
	s_add_i32 s68, 0, 0x18000
	s_add_i32 s69, 0, 0x1c000
	v_add_u32_e32 v158, s68, v143
	v_add_u32_e32 v174, s69, v143
	ds_read_b128 v[146:149], v158
	ds_read_b128 v[150:153], v158 offset:1024
	ds_read_b128 v[154:157], v158 offset:2048
	ds_read_b128 v[158:161], v158 offset:3072
	ds_read_b128 v[162:165], v174
	ds_read_b128 v[166:169], v174 offset:1024
	ds_read_b128 v[170:173], v174 offset:2048
	ds_read_b128 v[174:177], v174 offset:3072
	s_add_u32 s50, s50, 0x80000
	s_addc_u32 s51, s51, 0
	s_mov_b32 m0, s57
	ds_read_b128 v[178:181], v145 offset:32768
	ds_read_b128 v[182:185], v145 offset:33792
	ds_read_b128 v[200:203], v145 offset:34816
	ds_read_b128 v[204:207], v145 offset:35840
	ds_read_b128 v[208:211], v145 offset:36864
	ds_read_b128 v[212:215], v145 offset:37888
	ds_read_b128 v[216:219], v145 offset:38912
	ds_read_b128 v[220:223], v145 offset:39936
	global_load_lds_dwordx4 v130, s[50:51]
	s_mov_b32 m0, s58
	s_nop 0
	global_load_lds_dwordx4 v132, s[50:51]
	s_waitcnt vmcnt(8)
	s_waitcnt lgkmcnt(0)
	s_barrier
	s_setprio 1
	s_waitcnt lgkmcnt(0)
	v_mfma_f32_16x16x32_bf16 v[126:129], v[146:149], v[178:181], v[126:129]
	v_mfma_f32_16x16x32_bf16 v[122:125], v[154:157], v[178:181], v[122:125]
	v_mfma_f32_16x16x32_bf16 v[110:113], v[146:149], v[200:203], v[110:113]
	v_mfma_f32_16x16x32_bf16 v[106:109], v[154:157], v[200:203], v[106:109]
	v_mfma_f32_16x16x32_bf16 v[94:97], v[146:149], v[208:211], v[94:97]
	v_mfma_f32_16x16x32_bf16 v[90:93], v[154:157], v[208:211], v[90:93]
	v_mfma_f32_16x16x32_bf16 v[78:81], v[146:149], v[216:219], v[78:81]
	v_mfma_f32_16x16x32_bf16 v[74:77], v[154:157], v[216:219], v[74:77]
	v_mfma_f32_16x16x32_bf16 v[126:129], v[150:153], v[182:185], v[126:129]
	v_mfma_f32_16x16x32_bf16 v[122:125], v[158:161], v[182:185], v[122:125]
	v_mfma_f32_16x16x32_bf16 v[110:113], v[150:153], v[204:207], v[110:113]
	v_mfma_f32_16x16x32_bf16 v[106:109], v[158:161], v[204:207], v[106:109]
	v_mfma_f32_16x16x32_bf16 v[94:97], v[150:153], v[212:215], v[94:97]
	v_mfma_f32_16x16x32_bf16 v[90:93], v[158:161], v[212:215], v[90:93]
	v_mfma_f32_16x16x32_bf16 v[78:81], v[150:153], v[220:223], v[78:81]
	v_mfma_f32_16x16x32_bf16 v[74:77], v[158:161], v[220:223], v[74:77]
	s_setprio 0
	s_setprio 1
	v_mfma_f32_16x16x32_bf16 v[118:121], v[162:165], v[178:181], v[118:121]
	v_mfma_f32_16x16x32_bf16 v[114:117], v[170:173], v[178:181], v[114:117]
	v_mfma_f32_16x16x32_bf16 v[102:105], v[162:165], v[200:203], v[102:105]
	v_mfma_f32_16x16x32_bf16 v[98:101], v[170:173], v[200:203], v[98:101]
	v_mfma_f32_16x16x32_bf16 v[86:89], v[162:165], v[208:211], v[86:89]
	v_mfma_f32_16x16x32_bf16 v[82:85], v[170:173], v[208:211], v[82:85]
	v_mfma_f32_16x16x32_bf16 v[70:73], v[162:165], v[216:219], v[70:73]
	v_mfma_f32_16x16x32_bf16 v[66:69], v[170:173], v[216:219], v[66:69]
	v_mfma_f32_16x16x32_bf16 v[118:121], v[166:169], v[182:185], v[118:121]
	v_mfma_f32_16x16x32_bf16 v[114:117], v[174:177], v[182:185], v[114:117]
	v_mfma_f32_16x16x32_bf16 v[102:105], v[166:169], v[204:207], v[102:105]
	v_mfma_f32_16x16x32_bf16 v[98:101], v[174:177], v[204:207], v[98:101]
	v_mfma_f32_16x16x32_bf16 v[86:89], v[166:169], v[212:215], v[86:89]
	v_mfma_f32_16x16x32_bf16 v[82:85], v[174:177], v[212:215], v[82:85]
	v_mfma_f32_16x16x32_bf16 v[70:73], v[166:169], v[220:223], v[70:73]
	v_mfma_f32_16x16x32_bf16 v[66:69], v[174:177], v[220:223], v[66:69]
	s_setprio 0
	s_barrier
; template <class Epi, class Sched, bool ALIGN_EPI = false, bool SP2 = false>
; __device__ __forceinline__ void gemm_phase(LAS unsigned char* lds, const Gemm g, const Sched& S, const Epi& E, const int tid_) {
;     ...
;             PG8_LDA(At, 1, 1); PG8_STAGE(PG8_SB(1, 0), b3, voffB); PG8_STAGE(PG8_SB(1, 1), b3 + hstep, voffB); PG8_STAGE(PG8_SA(1, 0), a3, voffA);
;             PG8_WAIT_V(8); PG8_WAIT_L(0); PG8_BAR; PG8_MMA(1, 0, At, B0); PG8_MMA(1, 1, At, B1); PG8_BAR; PG8_SCHED;
;             } else {
;             PG8_LDB(B0, 0, 0); PG8_SCHED; PG8_LDA(At, 0, 0); PG8_STAGE(PG8_SA(1, 1), a1 + hstep, voffA);
;             PG8_WAIT_L(8); PG8_BAR; PG8_WAIT_L(0); PG8_MMA(0, 0, At, B0); PG8_BAR; PG8_SCHED;
;             PG8_LDB(B1, 0, 1); PG8_STAGE(PG8_SB(0, 0), b2, voffB);
;             PG8_BAR; PG8_WAIT_L(0); PG8_MMA(0, 1, At, B1); PG8_BAR;
;             PG8_LDA(At, 0, 1); PG8_STAGE(PG8_SA(0, 0), a2, voffA);
;             PG8_BAR; PG8_WAIT_L(0); PG8_MMA(1, 0, At, B0); PG8_BAR; PG8_SCHED;
;             PG8_STAGE(PG8_SB(0, 1), b2 + hstep, voffB);
;             PG8_WAIT_V(6); PG8_BAR; PG8_MMA(1, 1, At, B1); PG8_BAR;
;             PG8_LDB(B0, 1, 0); PG8_SCHED; PG8_LDA(At, 1, 0); PG8_STAGE(PG8_SA(0, 1), a2 + hstep, voffA);
;             PG8_WAIT_L(8); PG8_BAR; PG8_WAIT_L(0); PG8_MMA(0, 0, At, B0); PG8_BAR; PG8_SCHED;
;             PG8_LDB(B1, 1, 1); PG8_STAGE(PG8_SB(1, 0), b3, voffB);
;             PG8_BAR; PG8_WAIT_L(0); PG8_MMA(0, 1, At, B1); PG8_BAR;
;             PG8_LDA(At, 1, 1); PG8_STAGE(PG8_SA(1, 0), a3, voffA);
;             PG8_BAR; PG8_WAIT_L(0); PG8_MMA(1, 0, At, B0); PG8_BAR; PG8_SCHED;
;             PG8_STAGE(PG8_SB(1, 1), b3 + hstep, voffB);
;             PG8_WAIT_V(6); PG8_BAR; PG8_MMA(1, 1, At, B1); PG8_BAR;
;             }
;         }
;         if constexpr (ALIGN_EPI) { if (wr == 0) PG8_BAR; }
;     __device__ __forceinline__ void operator()(const f32x4 (&acc)[2][2][4][2], const pg8::Unit& u, int wr, int wc, int fr, int fq) const {
;         const int row0 = u.pm * 256 + wr * 64 + fr, col0 = u.pn * 256 + wc * 32 + 8 * fq;
; #pragma unroll
;         for (int ai = 0; ai < 2; ++ai)
; #pragma unroll
;             for (int m = 0; m < 4; ++m) { bf16_t* rowp = O + (size_t)(row0 + ai * 128 + m * 16) * DFF + col0;
; #pragma unroll
;                 for (int bj = 0; bj < 2; ++bj) { f32x4 v0 = acc[ai][bj][m][0], v1 = acc[ai][bj][m][1];
; #pragma unroll
	s_add_i32 s50, s68, s55
	s_add_i32 m0, s50, 0xffffff80
	ds_read_b128 v[178:181], v145 offset:49152
	ds_read_b128 v[182:185], v145 offset:50176
	ds_read_b128 v[200:203], v145 offset:51200
	ds_read_b128 v[204:207], v145 offset:52224
	ds_read_b128 v[208:211], v145 offset:53248
	ds_read_b128 v[212:215], v145 offset:54272
	ds_read_b128 v[216:219], v145 offset:55296
	ds_read_b128 v[220:223], v145 offset:56320
	global_load_lds_dwordx4 v0, s[48:49] offset:128
	s_add_i32 m0, s50, 0x2000
	s_add_u32 s48, s48, 0x80080
	v_lshl_add_u64 v[140:141], v[192:193], 0, s[96:97]
	s_addc_u32 s49, s49, 0
	s_add_i32 s50, s69, s55
	global_load_lds_dwordx4 v[140:141], off
	s_mov_b32 m0, s50
	s_nop 0
	global_load_lds_dwordx4 v0, s[48:49]
	s_add_i32 m0, s50, 0x2000
	s_nop 0
	global_load_lds_dwordx4 v134, s[48:49]
	v_lshl_add_u64 v[140:141], v[224:225], 0, s[96:97]
	s_mov_b32 m0, s60
	s_nop 0
	global_load_lds_dwordx4 v[140:141], off
	v_lshl_add_u64 v[140:141], v[236:237], 0, s[96:97]
	s_mov_b32 m0, s61
	s_nop 0
	global_load_lds_dwordx4 v[140:141], off
	s_waitcnt vmcnt(8)
	s_waitcnt lgkmcnt(0)
	s_barrier
	s_setprio 1
	s_waitcnt lgkmcnt(0)
	v_mfma_f32_16x16x32_bf16 v[62:65], v[146:149], v[178:181], v[62:65]
	v_mfma_f32_16x16x32_bf16 v[58:61], v[154:157], v[178:181], v[58:61]
	v_mfma_f32_16x16x32_bf16 v[46:49], v[146:149], v[200:203], v[46:49]
	v_mfma_f32_16x16x32_bf16 v[42:45], v[154:157], v[200:203], v[42:45]
	v_mfma_f32_16x16x32_bf16 v[30:33], v[146:149], v[208:211], v[30:33]
	v_mfma_f32_16x16x32_bf16 v[26:29], v[154:157], v[208:211], v[26:29]
	v_mfma_f32_16x16x32_bf16 v[14:17], v[146:149], v[216:219], v[14:17]
	v_mfma_f32_16x16x32_bf16 v[10:13], v[154:157], v[216:219], v[10:13]
	v_mfma_f32_16x16x32_bf16 v[62:65], v[150:153], v[182:185], v[62:65]
	v_mfma_f32_16x16x32_bf16 v[58:61], v[158:161], v[182:185], v[58:61]
	v_mfma_f32_16x16x32_bf16 v[46:49], v[150:153], v[204:207], v[46:49]
	v_mfma_f32_16x16x32_bf16 v[42:45], v[158:161], v[204:207], v[42:45]
	v_mfma_f32_16x16x32_bf16 v[30:33], v[150:153], v[212:215], v[30:33]
	v_mfma_f32_16x16x32_bf16 v[26:29], v[158:161], v[212:215], v[26:29]
	v_mfma_f32_16x16x32_bf16 v[14:17], v[150:153], v[220:223], v[14:17]
	v_mfma_f32_16x16x32_bf16 v[10:13], v[158:161], v[220:223], v[10:13]
	s_setprio 0
	s_setprio 1
	v_mfma_f32_16x16x32_bf16 v[54:57], v[162:165], v[178:181], v[54:57]
	v_mfma_f32_16x16x32_bf16 v[50:53], v[170:173], v[178:181], v[50:53]
	v_mfma_f32_16x16x32_bf16 v[38:41], v[162:165], v[200:203], v[38:41]
	v_mfma_f32_16x16x32_bf16 v[34:37], v[170:173], v[200:203], v[34:37]
	v_mfma_f32_16x16x32_bf16 v[22:25], v[162:165], v[208:211], v[22:25]
	v_mfma_f32_16x16x32_bf16 v[18:21], v[170:173], v[208:211], v[18:21]
	v_mfma_f32_16x16x32_bf16 v[6:9], v[162:165], v[216:219], v[6:9]
	v_mfma_f32_16x16x32_bf16 v[2:5], v[170:173], v[216:219], v[2:5]
	v_mfma_f32_16x16x32_bf16 v[54:57], v[166:169], v[182:185], v[54:57]
	v_mfma_f32_16x16x32_bf16 v[50:53], v[174:177], v[182:185], v[50:53]
	v_mfma_f32_16x16x32_bf16 v[38:41], v[166:169], v[204:207], v[38:41]
	v_mfma_f32_16x16x32_bf16 v[34:37], v[174:177], v[204:207], v[34:37]
	v_mfma_f32_16x16x32_bf16 v[22:25], v[166:169], v[212:215], v[22:25]
	v_mfma_f32_16x16x32_bf16 v[18:21], v[174:177], v[212:215], v[18:21]
	v_mfma_f32_16x16x32_bf16 v[6:9], v[166:169], v[220:223], v[6:9]
	v_mfma_f32_16x16x32_bf16 v[2:5], v[174:177], v[220:223], v[2:5]
	s_setprio 0
	s_barrier
	s_add_i32 s67, s67, 2
	s_add_u32 s46, s46, 0x100
	s_addc_u32 s47, s47, 0
	s_add_u32 s65, s65, 0x100
	s_addc_u32 s66, s66, 0
	s_cmp_gt_u32 s67, 29
	s_cbranch_scc0 .LBB0_34
	s_andn2_b64 vcc, s[12:13], s[40:41]
	s_cbranch_vccz .LBB0_37
	s_barrier
.LBB0_37:
	v_lshl_add_u32 v146, s44, 8, v142
	v_lshl_or_b32 v140, s20, 8, v144
	v_ashrrev_i32_e32 v147, 31, v146
	v_ashrrev_i32_e32 v141, 31, v140
	v_lshlrev_b64 v[148:149], 14, v[146:147]
	v_lshl_add_u64 v[148:149], s[10:11], 0, v[148:149]
	v_lshlrev_b64 v[150:151], 1, v[140:141]
	v_max_f32_e32 v122, 0, v122
	v_max_f32_e32 v123, 0, v123
	v_lshl_add_u64 v[140:141], v[148:149], 0, v[150:151]
	v_pk_mul_f32 v[148:149], v[122:123], v[122:123]
	v_max_f32_e32 v124, 0, v124
	v_max_f32_e32 v126, 0, v126
	v_max_f32_e32 v127, 0, v127
	v_max_f32_e32 v122, 0, v128
	v_max_f32_e32 v123, 0, v129
	v_max_f32_e32 v125, 0, v125
	v_pk_mul_f32 v[126:127], v[126:127], v[126:127]
	v_pk_mul_f32 v[128:129], v[122:123], v[122:123]
	v_pk_mul_f32 v[152:153], v[124:125], v[124:125]
	v_cvt_pk_bf16_f32 v122, v126, v127
	v_cvt_pk_bf16_f32 v123, v128, v129
	v_cvt_pk_bf16_f32 v124, v148, v149
	v_cvt_pk_bf16_f32 v125, v152, v153
	v_max_f32_e32 v114, 0, v114
	v_max_f32_e32 v115, 0, v115
	global_store_dwordx4 v[140:141], v[122:125], off
	s_nop 1
	v_pk_mul_f32 v[122:123], v[114:115], v[114:115]
	v_max_f32_e32 v116, 0, v116
	v_max_f32_e32 v118, 0, v118
	v_max_f32_e32 v119, 0, v119
	v_max_f32_e32 v114, 0, v120
	v_max_f32_e32 v115, 0, v121
	v_max_f32_e32 v117, 0, v117
	v_pk_mul_f32 v[118:119], v[118:119], v[118:119]
	v_pk_mul_f32 v[120:121], v[114:115], v[114:115]
	v_pk_mul_f32 v[124:125], v[116:117], v[116:117]
	v_cvt_pk_bf16_f32 v114, v118, v119
	v_cvt_pk_bf16_f32 v115, v120, v121
	v_cvt_pk_bf16_f32 v116, v122, v123
	v_cvt_pk_bf16_f32 v117, v124, v125
	v_max_f32_e32 v106, 0, v106
	v_max_f32_e32 v107, 0, v107
	global_store_dwordx4 v[140:141], v[114:117], off offset:256
	s_nop 1
	v_or_b32_e32 v114, 16, v146
	v_pk_mul_f32 v[116:117], v[106:107], v[106:107]
	v_ashrrev_i32_e32 v115, 31, v114
	v_max_f32_e32 v108, 0, v108
	v_lshlrev_b64 v[114:115], 14, v[114:115]
	v_max_f32_e32 v110, 0, v110
	v_max_f32_e32 v111, 0, v111
	v_max_f32_e32 v106, 0, v112
	v_max_f32_e32 v107, 0, v113
	v_max_f32_e32 v109, 0, v109
	v_lshl_add_u64 v[114:115], s[10:11], 0, v[114:115]
; __device__ __forceinline__ unsigned cvt_pk_bf16(float lo, float hi) { f32x2 v = {lo, hi}; bf16x2_t r = __builtin_convertvector(v, bf16x2_t); return __builtin_bit_cast(unsigned, r); }
;     __device__ __forceinline__ void operator()(const f32x4 (&acc)[2][2][4][2], const pg8::Unit& u, int wr, int wc, int fr, int fq) const {
;     ...
;             for (int m = 0; m < 4; ++m) { bf16_t* rowp = O + (size_t)(row0 + ai * 128 + m * 16) * DFF + col0;
; #pragma unroll
;                 for (int bj = 0; bj < 2; ++bj) { f32x4 v0 = acc[ai][bj][m][0], v1 = acc[ai][bj][m][1];
; #pragma unroll
;                     for (int j = 0; j < 4; ++j) { const float a = fmaxf(v0[j], 0.f), b = fmaxf(v1[j], 0.f); v0[j] = a * a; v1[j] = b * b; }
;                     u32x4 w; w.x = cvt_pk_bf16(v0[0], v0[1]); w.y = cvt_pk_bf16(v0[2], v0[3]); w.z = cvt_pk_bf16(v1[0], v1[1]); w.w = cvt_pk_bf16(v1[2], v1[3]);
;                     *(u32x4*)(rowp + bj * 128) = w; } }
	v_pk_mul_f32 v[110:111], v[110:111], v[110:111]
	v_pk_mul_f32 v[112:113], v[106:107], v[106:107]
	v_pk_mul_f32 v[118:119], v[108:109], v[108:109]
	v_lshl_add_u64 v[114:115], v[114:115], 0, v[150:151]
	v_cvt_pk_bf16_f32 v106, v110, v111
	v_cvt_pk_bf16_f32 v107, v112, v113
	v_cvt_pk_bf16_f32 v108, v116, v117
	v_cvt_pk_bf16_f32 v109, v118, v119
	v_max_f32_e32 v98, 0, v98
	v_max_f32_e32 v99, 0, v99
	global_store_dwordx4 v[114:115], v[106:109], off
	s_nop 1
	v_pk_mul_f32 v[106:107], v[98:99], v[98:99]
	v_max_f32_e32 v100, 0, v100
	v_max_f32_e32 v102, 0, v102
	v_max_f32_e32 v103, 0, v103
	v_max_f32_e32 v98, 0, v104
	v_max_f32_e32 v99, 0, v105
	v_max_f32_e32 v101, 0, v101
	v_pk_mul_f32 v[102:103], v[102:103], v[102:103]
	v_pk_mul_f32 v[104:105], v[98:99], v[98:99]
	v_pk_mul_f32 v[108:109], v[100:101], v[100:101]
	v_cvt_pk_bf16_f32 v98, v102, v103
	v_cvt_pk_bf16_f32 v99, v104, v105
	v_cvt_pk_bf16_f32 v100, v106, v107
	v_cvt_pk_bf16_f32 v101, v108, v109
	v_max_f32_e32 v90, 0, v90
	v_max_f32_e32 v91, 0, v91
	global_store_dwordx4 v[114:115], v[98:101], off offset:256
	s_nop 1
	v_or_b32_e32 v98, 32, v146
	v_pk_mul_f32 v[100:101], v[90:91], v[90:91]
	v_ashrrev_i32_e32 v99, 31, v98
	v_max_f32_e32 v92, 0, v92
	v_lshlrev_b64 v[98:99], 14, v[98:99]
	v_max_f32_e32 v94, 0, v94
	v_max_f32_e32 v95, 0, v95
	v_max_f32_e32 v90, 0, v96
	v_max_f32_e32 v91, 0, v97
	v_max_f32_e32 v93, 0, v93
	v_lshl_add_u64 v[98:99], s[10:11], 0, v[98:99]
	v_pk_mul_f32 v[94:95], v[94:95], v[94:95]
	v_pk_mul_f32 v[96:97], v[90:91], v[90:91]
	v_pk_mul_f32 v[102:103], v[92:93], v[92:93]
	v_lshl_add_u64 v[98:99], v[98:99], 0, v[150:151]
	v_cvt_pk_bf16_f32 v90, v94, v95
	v_cvt_pk_bf16_f32 v91, v96, v97
	v_cvt_pk_bf16_f32 v92, v100, v101
	v_cvt_pk_bf16_f32 v93, v102, v103
	v_max_f32_e32 v82, 0, v82
	v_max_f32_e32 v83, 0, v83
	global_store_dwordx4 v[98:99], v[90:93], off
	s_nop 1
	v_pk_mul_f32 v[90:91], v[82:83], v[82:83]
	v_max_f32_e32 v84, 0, v84
	v_max_f32_e32 v86, 0, v86
	v_max_f32_e32 v87, 0, v87
	v_max_f32_e32 v82, 0, v88
	v_max_f32_e32 v83, 0, v89
	v_max_f32_e32 v85, 0, v85
	v_pk_mul_f32 v[86:87], v[86:87], v[86:87]
	v_pk_mul_f32 v[88:89], v[82:83], v[82:83]
	v_pk_mul_f32 v[92:93], v[84:85], v[84:85]
	v_cvt_pk_bf16_f32 v82, v86, v87
	v_cvt_pk_bf16_f32 v83, v88, v89
	v_cvt_pk_bf16_f32 v84, v90, v91
	v_cvt_pk_bf16_f32 v85, v92, v93
	v_max_f32_e32 v74, 0, v74
	v_max_f32_e32 v75, 0, v75
	global_store_dwordx4 v[98:99], v[82:85], off offset:256
	s_nop 1
	v_or_b32_e32 v82, 48, v146
	v_pk_mul_f32 v[84:85], v[74:75], v[74:75]
	v_ashrrev_i32_e32 v83, 31, v82
	v_max_f32_e32 v76, 0, v76
	v_lshlrev_b64 v[82:83], 14, v[82:83]
	v_max_f32_e32 v78, 0, v78
	v_max_f32_e32 v79, 0, v79
	v_max_f32_e32 v74, 0, v80
	v_max_f32_e32 v75, 0, v81
	v_max_f32_e32 v77, 0, v77
	v_lshl_add_u64 v[82:83], s[10:11], 0, v[82:83]
	v_pk_mul_f32 v[78:79], v[78:79], v[78:79]
	v_pk_mul_f32 v[80:81], v[74:75], v[74:75]
	v_pk_mul_f32 v[86:87], v[76:77], v[76:77]
	v_lshl_add_u64 v[82:83], v[82:83], 0, v[150:151]
	v_cvt_pk_bf16_f32 v74, v78, v79
	v_cvt_pk_bf16_f32 v75, v80, v81
	v_cvt_pk_bf16_f32 v76, v84, v85
	v_cvt_pk_bf16_f32 v77, v86, v87
	v_max_f32_e32 v66, 0, v66
	v_max_f32_e32 v67, 0, v67
	global_store_dwordx4 v[82:83], v[74:77], off
	s_nop 1
	v_pk_mul_f32 v[74:75], v[66:67], v[66:67]
	v_max_f32_e32 v68, 0, v68
	v_max_f32_e32 v70, 0, v70
	v_max_f32_e32 v71, 0, v71
	v_max_f32_e32 v66, 0, v72
	v_max_f32_e32 v67, 0, v73
	v_max_f32_e32 v69, 0, v69
	v_pk_mul_f32 v[70:71], v[70:71], v[70:71]
	v_pk_mul_f32 v[72:73], v[66:67], v[66:67]
	v_pk_mul_f32 v[76:77], v[68:69], v[68:69]
	v_cvt_pk_bf16_f32 v66, v70, v71
	v_cvt_pk_bf16_f32 v67, v72, v73
	v_cvt_pk_bf16_f32 v68, v74, v75
	v_cvt_pk_bf16_f32 v69, v76, v77
	v_max_f32_e32 v58, 0, v58
	v_max_f32_e32 v59, 0, v59
	global_store_dwordx4 v[82:83], v[66:69], off offset:256
	s_nop 1
	v_pk_mul_f32 v[68:69], v[58:59], v[58:59]
	v_max_f32_e32 v62, 0, v62
	v_max_f32_e32 v63, 0, v63
	v_max_f32_e32 v60, 0, v60
	v_pk_mul_f32 v[62:63], v[62:63], v[62:63]
	v_max_f32_e32 v58, 0, v64
	v_max_f32_e32 v59, 0, v65
	v_max_f32_e32 v61, 0, v61
	s_mov_b32 s15, 0x200000
	v_pk_mul_f32 v[64:65], v[58:59], v[58:59]
	v_pk_mul_f32 v[70:71], v[60:61], v[60:61]
	v_cvt_pk_bf16_f32 v58, v62, v63
	v_add_co_u32_e32 v62, vcc, s15, v140
	v_cvt_pk_bf16_f32 v59, v64, v65
	v_cvt_pk_bf16_f32 v60, v68, v69
	v_cvt_pk_bf16_f32 v61, v70, v71
	v_addc_co_u32_e32 v63, vcc, 0, v141, vcc
	v_max_f32_e32 v50, 0, v50
	v_max_f32_e32 v51, 0, v51
	global_store_dwordx4 v[62:63], v[58:61], off
	s_nop 1
	v_pk_mul_f32 v[58:59], v[50:51], v[50:51]
	v_max_f32_e32 v52, 0, v52
	v_max_f32_e32 v54, 0, v54
	v_max_f32_e32 v55, 0, v55
	v_max_f32_e32 v50, 0, v56
; __device__ __forceinline__ unsigned cvt_pk_bf16(float lo, float hi) { f32x2 v = {lo, hi}; bf16x2_t r = __builtin_convertvector(v, bf16x2_t); return __builtin_bit_cast(unsigned, r); }
; #define PG8_BAR __builtin_amdgcn_s_barrier()
; template <class Epi, class Sched, bool ALIGN_EPI = false, bool SP2 = false>
; __device__ __forceinline__ void gemm_phase(LAS unsigned char* lds, const Gemm g, const Sched& S, const Epi& E, const int tid_) {
;     ...
;         cur = nxt; cA = nA; cB = nB; ++ui;
;         if constexpr (ALIGN_EPI) { if (wr == 1) PG8_BAR; }
;     __device__ __forceinline__ void operator()(const f32x4 (&acc)[2][2][4][2], const pg8::Unit& u, int wr, int wc, int fr, int fq) const {
;     ...
;             for (int m = 0; m < 4; ++m) { bf16_t* rowp = O + (size_t)(row0 + ai * 128 + m * 16) * DFF + col0;
; #pragma unroll
;                 for (int bj = 0; bj < 2; ++bj) { f32x4 v0 = acc[ai][bj][m][0], v1 = acc[ai][bj][m][1];
; #pragma unroll
;                     for (int j = 0; j < 4; ++j) { const float a = fmaxf(v0[j], 0.f), b = fmaxf(v1[j], 0.f); v0[j] = a * a; v1[j] = b * b; }
;                     u32x4 w; w.x = cvt_pk_bf16(v0[0], v0[1]); w.y = cvt_pk_bf16(v0[2], v0[3]); w.z = cvt_pk_bf16(v1[0], v1[1]); w.w = cvt_pk_bf16(v1[2], v1[3]);
;                     *(u32x4*)(rowp + bj * 128) = w; } }
	v_max_f32_e32 v51, 0, v57
	v_max_f32_e32 v53, 0, v53
	s_mov_b64 s[20:21], 0x200000
	v_pk_mul_f32 v[54:55], v[54:55], v[54:55]
	v_pk_mul_f32 v[56:57], v[50:51], v[50:51]
	v_pk_mul_f32 v[60:61], v[52:53], v[52:53]
	v_lshl_add_u64 v[66:67], v[140:141], 0, s[20:21]
	v_cvt_pk_bf16_f32 v50, v54, v55
	v_cvt_pk_bf16_f32 v51, v56, v57
	v_cvt_pk_bf16_f32 v52, v58, v59
	v_cvt_pk_bf16_f32 v53, v60, v61
	v_max_f32_e32 v42, 0, v42
	v_max_f32_e32 v43, 0, v43
	global_store_dwordx4 v[66:67], v[50:53], off offset:256
	s_nop 1
	v_pk_mul_f32 v[52:53], v[42:43], v[42:43]
	v_max_f32_e32 v46, 0, v46
	v_max_f32_e32 v47, 0, v47
	v_max_f32_e32 v44, 0, v44
	v_pk_mul_f32 v[46:47], v[46:47], v[46:47]
	v_max_f32_e32 v42, 0, v48
	v_max_f32_e32 v43, 0, v49
	v_max_f32_e32 v45, 0, v45
	s_mov_b32 s15, 0x240000
	v_pk_mul_f32 v[48:49], v[42:43], v[42:43]
	v_pk_mul_f32 v[54:55], v[44:45], v[44:45]
	v_cvt_pk_bf16_f32 v42, v46, v47
	v_add_co_u32_e32 v46, vcc, s15, v140
	v_cvt_pk_bf16_f32 v43, v48, v49
	v_cvt_pk_bf16_f32 v44, v52, v53
	v_cvt_pk_bf16_f32 v45, v54, v55
	v_addc_co_u32_e32 v47, vcc, 0, v141, vcc
	v_max_f32_e32 v34, 0, v34
	v_max_f32_e32 v35, 0, v35
	global_store_dwordx4 v[46:47], v[42:45], off
	s_nop 1
	v_pk_mul_f32 v[42:43], v[34:35], v[34:35]
	v_max_f32_e32 v36, 0, v36
	v_max_f32_e32 v38, 0, v38
	v_max_f32_e32 v39, 0, v39
	v_max_f32_e32 v34, 0, v40
	v_max_f32_e32 v35, 0, v41
	v_max_f32_e32 v37, 0, v37
	s_mov_b64 s[20:21], 0x240000
	v_pk_mul_f32 v[38:39], v[38:39], v[38:39]
	v_pk_mul_f32 v[40:41], v[34:35], v[34:35]
	v_pk_mul_f32 v[44:45], v[36:37], v[36:37]
	v_lshl_add_u64 v[50:51], v[140:141], 0, s[20:21]
	v_cvt_pk_bf16_f32 v34, v38, v39
	v_cvt_pk_bf16_f32 v35, v40, v41
	v_cvt_pk_bf16_f32 v36, v42, v43
	v_cvt_pk_bf16_f32 v37, v44, v45
	v_max_f32_e32 v26, 0, v26
	v_max_f32_e32 v27, 0, v27
	global_store_dwordx4 v[50:51], v[34:37], off offset:256
	s_nop 1
	v_pk_mul_f32 v[36:37], v[26:27], v[26:27]
	v_max_f32_e32 v30, 0, v30
	v_max_f32_e32 v31, 0, v31
	v_max_f32_e32 v28, 0, v28
	v_pk_mul_f32 v[30:31], v[30:31], v[30:31]
	v_max_f32_e32 v26, 0, v32
	v_max_f32_e32 v27, 0, v33
	v_max_f32_e32 v29, 0, v29
	s_mov_b32 s15, 0x280000
	v_pk_mul_f32 v[32:33], v[26:27], v[26:27]
	v_pk_mul_f32 v[38:39], v[28:29], v[28:29]
	v_cvt_pk_bf16_f32 v26, v30, v31
	v_add_co_u32_e32 v30, vcc, s15, v140
	v_cvt_pk_bf16_f32 v27, v32, v33
	v_cvt_pk_bf16_f32 v28, v36, v37
	v_cvt_pk_bf16_f32 v29, v38, v39
	v_addc_co_u32_e32 v31, vcc, 0, v141, vcc
	v_max_f32_e32 v18, 0, v18
	v_max_f32_e32 v19, 0, v19
	global_store_dwordx4 v[30:31], v[26:29], off
	s_nop 1
	v_pk_mul_f32 v[26:27], v[18:19], v[18:19]
	v_max_f32_e32 v20, 0, v20
	v_max_f32_e32 v22, 0, v22
	v_max_f32_e32 v23, 0, v23
	v_max_f32_e32 v18, 0, v24
	v_max_f32_e32 v19, 0, v25
	v_max_f32_e32 v21, 0, v21
	s_mov_b64 s[20:21], 0x280000
	v_pk_mul_f32 v[22:23], v[22:23], v[22:23]
	v_pk_mul_f32 v[24:25], v[18:19], v[18:19]
	v_pk_mul_f32 v[28:29], v[20:21], v[20:21]
	v_lshl_add_u64 v[34:35], v[140:141], 0, s[20:21]
	v_cvt_pk_bf16_f32 v18, v22, v23
	v_cvt_pk_bf16_f32 v19, v24, v25
	v_cvt_pk_bf16_f32 v20, v26, v27
	v_cvt_pk_bf16_f32 v21, v28, v29
	v_max_f32_e32 v10, 0, v10
	v_max_f32_e32 v11, 0, v11
	global_store_dwordx4 v[34:35], v[18:21], off offset:256
	s_nop 1
	v_pk_mul_f32 v[20:21], v[10:11], v[10:11]
	v_max_f32_e32 v14, 0, v14
	v_max_f32_e32 v15, 0, v15
	v_max_f32_e32 v12, 0, v12
	v_pk_mul_f32 v[14:15], v[14:15], v[14:15]
	v_max_f32_e32 v10, 0, v16
	v_max_f32_e32 v11, 0, v17
	v_max_f32_e32 v13, 0, v13
	s_mov_b32 s15, 0x2c0000
	v_pk_mul_f32 v[16:17], v[10:11], v[10:11]
	v_pk_mul_f32 v[22:23], v[12:13], v[12:13]
	v_cvt_pk_bf16_f32 v10, v14, v15
	v_add_co_u32_e32 v14, vcc, s15, v140
	v_cvt_pk_bf16_f32 v11, v16, v17
	v_cvt_pk_bf16_f32 v12, v20, v21
	v_cvt_pk_bf16_f32 v13, v22, v23
	v_addc_co_u32_e32 v15, vcc, 0, v141, vcc
	v_max_f32_e32 v2, 0, v2
	v_max_f32_e32 v3, 0, v3
	global_store_dwordx4 v[14:15], v[10:13], off
	s_nop 1
	v_pk_mul_f32 v[10:11], v[2:3], v[2:3]
	v_max_f32_e32 v4, 0, v4
	v_max_f32_e32 v6, 0, v6
	v_max_f32_e32 v7, 0, v7
	v_max_f32_e32 v2, 0, v8
	v_max_f32_e32 v3, 0, v9
	v_max_f32_e32 v5, 0, v5
	s_mov_b64 s[20:21], 0x2c0000
	v_pk_mul_f32 v[6:7], v[6:7], v[6:7]
	v_pk_mul_f32 v[8:9], v[2:3], v[2:3]
	v_pk_mul_f32 v[12:13], v[4:5], v[4:5]
	v_lshl_add_u64 v[18:19], v[140:141], 0, s[20:21]
	v_cvt_pk_bf16_f32 v2, v6, v7
	v_cvt_pk_bf16_f32 v3, v8, v9
	v_cvt_pk_bf16_f32 v4, v10, v11
	v_cvt_pk_bf16_f32 v5, v12, v13
	s_andn2_b64 vcc, exec, s[40:41]
	s_mov_b64 s[20:21], -1
	global_store_dwordx4 v[18:19], v[2:5], off offset:256
	s_nop 1
	s_cbranch_vccnz .LBB0_26
	s_andn2_b64 vcc, exec, s[8:9]
	s_cbranch_vccnz .LBB0_25
	s_nop 0
	s_branch .LBB0_25

; #define PG8_STAGE(bufoff, gbase, voff) do { _Pragma("unroll") for (int _i = 0; _i < 2; ++_i) \
;         __builtin_amdgcn_global_load_lds((const unsigned*)((const char*)(gbase) + (voff)[_i]), (LAS unsigned*)(lds + (bufoff) + ldsw + _i * 8192), 16, 0, 0); } while (0)
; #define PG8_LDA(dst, b, h) do { _Pragma("unroll") for (int m = 0; m < 4; ++m) _Pragma("unroll") for (int k = 0; k < 2; ++k) dst[m][k] = *(const LAS bf16x8*)(lds + PG8_SA(b, h) + aoff + m * 2048 + k * 1024); } while (0)
; #define PG8_LDB(dst, b, h) do { _Pragma("unroll") for (int n = 0; n < 2; ++n) _Pragma("unroll") for (int k = 0; k < 2; ++k) dst[n][k] = *(const LAS bf16x8*)(lds + PG8_SB(b, h) + boff + n * 2048 + k * 1024); } while (0)
; #define PG8_MMA(ai, bj, At, Bt) do { __builtin_amdgcn_s_setprio(1); _Pragma("unroll") for (int m = 0; m < 4; ++m) _Pragma("unroll") for (int n = 0; n < 2; ++n) _Pragma("unroll") for (int k = 0; k < 2; ++k) \
;         acc[ai][bj][m][n] = __builtin_amdgcn_mfma_f32_16x16x32_bf16(Bt[n][k], At[m][k], acc[ai][bj][m][n], 0, 0, 0); __builtin_amdgcn_s_setprio(0); } while (0)
; #define PG8_WAIT_V(n) asm volatile("s_waitcnt vmcnt(" #n ")" ::: "memory")
; #define PG8_BAR __builtin_amdgcn_s_barrier()
; template <class Epi, class Sched, bool ALIGN_EPI = false, bool SP2 = false>
; __device__ __forceinline__ void gemm_phase(LAS unsigned char* lds, const Gemm g, const Sched& S, const Epi& E, const int tid_) {
;     ...
;         for (int t = 0; t < nt; t += 2) {
;             const bool last = (t == nt - 2);
;             const char* a1 = cA + (size_t)(t + 1) * kstep;
;             const char* a2 = last ? nA : cA + (size_t)(t + 2) * kstep; const char* b2 = last ? nB : cB + (size_t)(t + 2) * kstep;
;             const char* a3 = a2 + kstep; const char* b3 = b2 + kstep;
;             if (last && has_next) S.a_ready(nxt);
;             if constexpr (SP2) {
;             PG8_LDB(B0, 0, 0); PG8_LDB(B1, 0, 1); PG8_SCHED; PG8_LDA(At, 0, 0); PG8_STAGE(PG8_SA(1, 1), a1 + hstep, voffA);
;             PG8_WAIT_V(8); PG8_WAIT_L(0); PG8_BAR; PG8_MMA(0, 0, At, B0); PG8_MMA(0, 1, At, B1); PG8_BAR; PG8_SCHED;
;             PG8_LDA(At, 0, 1); PG8_STAGE(PG8_SB(0, 0), b2, voffB); PG8_STAGE(PG8_SB(0, 1), b2 + hstep, voffB); PG8_STAGE(PG8_SA(0, 0), a2, voffA);
;             PG8_WAIT_V(8); PG8_WAIT_L(0); PG8_BAR; PG8_MMA(1, 0, At, B0); PG8_MMA(1, 1, At, B1); PG8_BAR; PG8_SCHED;
.LBB0_70:
	s_add_u32 s48, s46, 0x100
	s_addc_u32 s49, s47, 0
	s_add_i32 s70, 0, 0x10000
	s_cmp_eq_u32 s69, 28
	s_cselect_b32 s55, s17, s49
	s_cselect_b32 s54, s21, s48
	s_cselect_b32 s51, s15, s68
	s_cselect_b32 s50, s66, s67
	s_add_i32 s71, 0, 0x14000
	v_add_u32_e32 v148, s70, v157
	v_add_u32_e32 v168, s71, v157
	ds_read_b128 v[130:133], v148
	ds_read_b128 v[134:137], v148 offset:1024
	ds_read_b128 v[138:141], v148 offset:2048
	ds_read_b128 v[148:151], v148 offset:3072
	ds_read_b128 v[152:155], v168
	ds_read_b128 v[160:163], v168 offset:1024
	ds_read_b128 v[164:167], v168 offset:2048
	ds_read_b128 v[168:171], v168 offset:3072
	s_add_i32 m0, s45, 0xc000
	ds_read_b128 v[172:175], v159
	ds_read_b128 v[176:179], v159 offset:1024
	ds_read_b128 v[180:183], v159 offset:2048
	ds_read_b128 v[200:203], v159 offset:3072
	ds_read_b128 v[204:207], v159 offset:4096
	ds_read_b128 v[208:211], v159 offset:5120
	ds_read_b128 v[212:215], v159 offset:6144
	ds_read_b128 v[216:219], v159 offset:7168
	global_load_lds_dwordx4 v144, s[46:47]
	s_add_i32 m0, s45, 0xe000
	s_nop 0
	global_load_lds_dwordx4 v146, s[46:47]
	s_waitcnt vmcnt(8)
	s_waitcnt lgkmcnt(0)
	s_barrier
	s_setprio 1
	s_waitcnt lgkmcnt(0)
	v_mfma_f32_16x16x32_bf16 v[126:129], v[130:133], v[172:175], v[126:129]
	v_mfma_f32_16x16x32_bf16 v[122:125], v[138:141], v[172:175], v[122:125]
	v_mfma_f32_16x16x32_bf16 v[118:121], v[130:133], v[180:183], v[118:121]
	v_mfma_f32_16x16x32_bf16 v[106:109], v[138:141], v[180:183], v[106:109]
	v_mfma_f32_16x16x32_bf16 v[102:105], v[130:133], v[204:207], v[102:105]
	v_mfma_f32_16x16x32_bf16 v[90:93], v[138:141], v[204:207], v[90:93]
	v_mfma_f32_16x16x32_bf16 v[86:89], v[130:133], v[212:215], v[86:89]
	v_mfma_f32_16x16x32_bf16 v[74:77], v[138:141], v[212:215], v[74:77]
	v_mfma_f32_16x16x32_bf16 v[126:129], v[134:137], v[176:179], v[126:129]
	v_mfma_f32_16x16x32_bf16 v[122:125], v[148:151], v[176:179], v[122:125]
	v_mfma_f32_16x16x32_bf16 v[118:121], v[134:137], v[200:203], v[118:121]
	v_mfma_f32_16x16x32_bf16 v[106:109], v[148:151], v[200:203], v[106:109]
	v_mfma_f32_16x16x32_bf16 v[102:105], v[134:137], v[208:211], v[102:105]
	v_mfma_f32_16x16x32_bf16 v[90:93], v[148:151], v[208:211], v[90:93]
	v_mfma_f32_16x16x32_bf16 v[86:89], v[134:137], v[216:219], v[86:89]
	v_mfma_f32_16x16x32_bf16 v[74:77], v[148:151], v[216:219], v[74:77]
	s_setprio 0
	s_setprio 1
	v_mfma_f32_16x16x32_bf16 v[114:117], v[152:155], v[172:175], v[114:117]
	v_mfma_f32_16x16x32_bf16 v[110:113], v[164:167], v[172:175], v[110:113]
	v_mfma_f32_16x16x32_bf16 v[98:101], v[152:155], v[180:183], v[98:101]
	v_mfma_f32_16x16x32_bf16 v[94:97], v[164:167], v[180:183], v[94:97]
	v_mfma_f32_16x16x32_bf16 v[82:85], v[152:155], v[204:207], v[82:85]
	v_mfma_f32_16x16x32_bf16 v[78:81], v[164:167], v[204:207], v[78:81]
	v_mfma_f32_16x16x32_bf16 v[70:73], v[152:155], v[212:215], v[70:73]
	v_mfma_f32_16x16x32_bf16 v[66:69], v[164:167], v[212:215], v[66:69]
	v_mfma_f32_16x16x32_bf16 v[114:117], v[160:163], v[176:179], v[114:117]
	v_mfma_f32_16x16x32_bf16 v[110:113], v[168:171], v[176:179], v[110:113]
	v_mfma_f32_16x16x32_bf16 v[98:101], v[160:163], v[200:203], v[98:101]
	v_mfma_f32_16x16x32_bf16 v[94:97], v[168:171], v[200:203], v[94:97]
	v_mfma_f32_16x16x32_bf16 v[82:85], v[160:163], v[208:211], v[82:85]
	v_mfma_f32_16x16x32_bf16 v[78:81], v[168:171], v[208:211], v[78:81]
	v_mfma_f32_16x16x32_bf16 v[70:73], v[160:163], v[216:219], v[70:73]
	v_mfma_f32_16x16x32_bf16 v[66:69], v[168:171], v[216:219], v[66:69]
	s_setprio 0
	s_barrier
	s_add_i32 s46, s70, s57
	s_mov_b32 m0, s46
	ds_read_b128 v[172:175], v159 offset:16384
	ds_read_b128 v[176:179], v159 offset:17408
	ds_read_b128 v[180:183], v159 offset:18432
	ds_read_b128 v[200:203], v159 offset:19456
	ds_read_b128 v[204:207], v159 offset:20480
	ds_read_b128 v[208:211], v159 offset:21504
	ds_read_b128 v[212:215], v159 offset:22528
	ds_read_b128 v[216:219], v159 offset:23552
	global_load_lds_dwordx4 v0, s[50:51]
	s_add_i32 m0, s46, 0x2000
	s_add_u32 s46, s50, 0x80000
	v_lshl_add_u64 v[192:193], s[50:51], 0, v[142:143]
	s_addc_u32 s47, s51, 0
	s_add_i32 s70, s71, s57
	global_load_lds_dwordx4 v142, s[50:51]
	s_mov_b32 m0, s70
	s_nop 0
	global_load_lds_dwordx4 v0, s[46:47]
	s_add_i32 m0, s70, 0x2000
	s_nop 0
	global_load_lds_dwordx4 v142, s[46:47]
	s_mov_b32 m0, s45
	s_nop 0
	global_load_lds_dwordx4 v0, s[54:55]
	s_mov_b32 m0, s58
	s_nop 0
	global_load_lds_dwordx4 v142, s[54:55]
	s_waitcnt vmcnt(8)
	s_waitcnt lgkmcnt(0)
	s_barrier
	s_setprio 1
	s_waitcnt lgkmcnt(0)
	v_mfma_f32_16x16x32_bf16 v[62:65], v[130:133], v[172:175], v[62:65]
	v_mfma_f32_16x16x32_bf16 v[58:61], v[138:141], v[172:175], v[58:61]
	v_mfma_f32_16x16x32_bf16 v[54:57], v[130:133], v[180:183], v[54:57]
	v_mfma_f32_16x16x32_bf16 v[42:45], v[138:141], v[180:183], v[42:45]
	v_mfma_f32_16x16x32_bf16 v[38:41], v[130:133], v[204:207], v[38:41]
	v_mfma_f32_16x16x32_bf16 v[26:29], v[138:141], v[204:207], v[26:29]
	v_mfma_f32_16x16x32_bf16 v[22:25], v[130:133], v[212:215], v[22:25]
	v_mfma_f32_16x16x32_bf16 v[10:13], v[138:141], v[212:215], v[10:13]
	v_mfma_f32_16x16x32_bf16 v[62:65], v[134:137], v[176:179], v[62:65]
	v_mfma_f32_16x16x32_bf16 v[58:61], v[148:151], v[176:179], v[58:61]
	v_mfma_f32_16x16x32_bf16 v[54:57], v[134:137], v[200:203], v[54:57]
	v_mfma_f32_16x16x32_bf16 v[42:45], v[148:151], v[200:203], v[42:45]
	v_mfma_f32_16x16x32_bf16 v[38:41], v[134:137], v[208:211], v[38:41]
	v_mfma_f32_16x16x32_bf16 v[26:29], v[148:151], v[208:211], v[26:29]
	v_mfma_f32_16x16x32_bf16 v[22:25], v[134:137], v[216:219], v[22:25]
	v_mfma_f32_16x16x32_bf16 v[10:13], v[148:151], v[216:219], v[10:13]
	s_setprio 0
	s_setprio 1
	v_mfma_f32_16x16x32_bf16 v[50:53], v[152:155], v[172:175], v[50:53]
	v_mfma_f32_16x16x32_bf16 v[46:49], v[164:167], v[172:175], v[46:49]
	v_mfma_f32_16x16x32_bf16 v[34:37], v[152:155], v[180:183], v[34:37]
	v_mfma_f32_16x16x32_bf16 v[30:33], v[164:167], v[180:183], v[30:33]
	v_mfma_f32_16x16x32_bf16 v[18:21], v[152:155], v[204:207], v[18:21]
	v_mfma_f32_16x16x32_bf16 v[14:17], v[164:167], v[204:207], v[14:17]
	v_mfma_f32_16x16x32_bf16 v[6:9], v[152:155], v[212:215], v[6:9]
	v_mfma_f32_16x16x32_bf16 v[2:5], v[164:167], v[212:215], v[2:5]
	v_mfma_f32_16x16x32_bf16 v[50:53], v[160:163], v[176:179], v[50:53]
	v_mfma_f32_16x16x32_bf16 v[46:49], v[168:171], v[176:179], v[46:49]
	v_mfma_f32_16x16x32_bf16 v[34:37], v[160:163], v[200:203], v[34:37]
	v_mfma_f32_16x16x32_bf16 v[30:33], v[168:171], v[200:203], v[30:33]
	v_mfma_f32_16x16x32_bf16 v[18:21], v[160:163], v[208:211], v[18:21]
	v_mfma_f32_16x16x32_bf16 v[14:17], v[168:171], v[208:211], v[14:17]
	v_mfma_f32_16x16x32_bf16 v[6:9], v[160:163], v[216:219], v[6:9]
	v_mfma_f32_16x16x32_bf16 v[2:5], v[168:171], v[216:219], v[2:5]
	s_setprio 0
	s_barrier
; #define PG8_STAGE(bufoff, gbase, voff) do { _Pragma("unroll") for (int _i = 0; _i < 2; ++_i) \
;         __builtin_amdgcn_global_load_lds((const unsigned*)((const char*)(gbase) + (voff)[_i]), (LAS unsigned*)(lds + (bufoff) + ldsw + _i * 8192), 16, 0, 0); } while (0)
; #define PG8_LDA(dst, b, h) do { _Pragma("unroll") for (int m = 0; m < 4; ++m) _Pragma("unroll") for (int k = 0; k < 2; ++k) dst[m][k] = *(const LAS bf16x8*)(lds + PG8_SA(b, h) + aoff + m * 2048 + k * 1024); } while (0)
; #define PG8_LDB(dst, b, h) do { _Pragma("unroll") for (int n = 0; n < 2; ++n) _Pragma("unroll") for (int k = 0; k < 2; ++k) dst[n][k] = *(const LAS bf16x8*)(lds + PG8_SB(b, h) + boff + n * 2048 + k * 1024); } while (0)
; #define PG8_MMA(ai, bj, At, Bt) do { __builtin_amdgcn_s_setprio(1); _Pragma("unroll") for (int m = 0; m < 4; ++m) _Pragma("unroll") for (int n = 0; n < 2; ++n) _Pragma("unroll") for (int k = 0; k < 2; ++k) \
;         acc[ai][bj][m][n] = __builtin_amdgcn_mfma_f32_16x16x32_bf16(Bt[n][k], At[m][k], acc[ai][bj][m][n], 0, 0, 0); __builtin_amdgcn_s_setprio(0); } while (0)
; #define PG8_WAIT_V(n) asm volatile("s_waitcnt vmcnt(" #n ")" ::: "memory")
; #define PG8_WAIT_L(n) asm volatile("s_waitcnt lgkmcnt(" #n ")" ::: "memory")
; #define PG8_BAR __builtin_amdgcn_s_barrier()
; #define PG8_SCHED __builtin_amdgcn_sched_barrier(0)
; template <class Epi, class Sched, bool ALIGN_EPI = false, bool SP2 = false>
; __device__ __forceinline__ void gemm_phase(LAS unsigned char* lds, const Gemm g, const Sched& S, const Epi& E, const int tid_) {
;     ...
;             PG8_LDB(B0, 1, 0); PG8_LDB(B1, 1, 1); PG8_SCHED; PG8_LDA(At, 1, 0); PG8_STAGE(PG8_SA(0, 1), a2 + hstep, voffA);
;             PG8_WAIT_V(8); PG8_WAIT_L(0); PG8_BAR; PG8_MMA(0, 0, At, B0); PG8_MMA(0, 1, At, B1); PG8_BAR; PG8_SCHED;
;             PG8_LDA(At, 1, 1); PG8_STAGE(PG8_SB(1, 0), b3, voffB); PG8_STAGE(PG8_SB(1, 1), b3 + hstep, voffB); PG8_STAGE(PG8_SA(1, 0), a3, voffA);
;             PG8_WAIT_V(8); PG8_WAIT_L(0); PG8_BAR; PG8_MMA(1, 0, At, B0); PG8_MMA(1, 1, At, B1); PG8_BAR; PG8_SCHED;
;     ...
;         if constexpr (ALIGN_EPI) { if (wr == 0) PG8_BAR; }
	s_add_i32 s70, 0, 0x18000
	s_add_i32 s71, 0, 0x1c000
	v_add_u32_e32 v148, s70, v157
	v_add_u32_e32 v168, s71, v157
	ds_read_b128 v[130:133], v148
	ds_read_b128 v[134:137], v148 offset:1024
	ds_read_b128 v[138:141], v148 offset:2048
	ds_read_b128 v[148:151], v148 offset:3072
	ds_read_b128 v[152:155], v168
	ds_read_b128 v[160:163], v168 offset:1024
	ds_read_b128 v[164:167], v168 offset:2048
	ds_read_b128 v[168:171], v168 offset:3072
	s_add_u32 s46, s54, 0x80000
	s_addc_u32 s47, s55, 0
	s_mov_b32 m0, s59
	ds_read_b128 v[172:175], v159 offset:32768
	ds_read_b128 v[176:179], v159 offset:33792
	ds_read_b128 v[180:183], v159 offset:34816
	ds_read_b128 v[200:203], v159 offset:35840
	ds_read_b128 v[204:207], v159 offset:36864
	ds_read_b128 v[208:211], v159 offset:37888
	ds_read_b128 v[212:215], v159 offset:38912
	ds_read_b128 v[216:219], v159 offset:39936
	global_load_lds_dwordx4 v0, s[46:47]
	s_mov_b32 m0, s60
	s_nop 0
	global_load_lds_dwordx4 v142, s[46:47]
	s_waitcnt vmcnt(8)
	s_waitcnt lgkmcnt(0)
	s_barrier
	s_setprio 1
	s_waitcnt lgkmcnt(0)
	v_mfma_f32_16x16x32_bf16 v[126:129], v[130:133], v[172:175], v[126:129]
	v_mfma_f32_16x16x32_bf16 v[122:125], v[138:141], v[172:175], v[122:125]
	v_mfma_f32_16x16x32_bf16 v[118:121], v[130:133], v[180:183], v[118:121]
	v_mfma_f32_16x16x32_bf16 v[106:109], v[138:141], v[180:183], v[106:109]
	v_mfma_f32_16x16x32_bf16 v[102:105], v[130:133], v[204:207], v[102:105]
	v_mfma_f32_16x16x32_bf16 v[90:93], v[138:141], v[204:207], v[90:93]
	v_mfma_f32_16x16x32_bf16 v[86:89], v[130:133], v[212:215], v[86:89]
	v_mfma_f32_16x16x32_bf16 v[74:77], v[138:141], v[212:215], v[74:77]
	v_mfma_f32_16x16x32_bf16 v[126:129], v[134:137], v[176:179], v[126:129]
	v_mfma_f32_16x16x32_bf16 v[122:125], v[148:151], v[176:179], v[122:125]
	v_mfma_f32_16x16x32_bf16 v[118:121], v[134:137], v[200:203], v[118:121]
	v_mfma_f32_16x16x32_bf16 v[106:109], v[148:151], v[200:203], v[106:109]
	v_mfma_f32_16x16x32_bf16 v[102:105], v[134:137], v[208:211], v[102:105]
	v_mfma_f32_16x16x32_bf16 v[90:93], v[148:151], v[208:211], v[90:93]
	v_mfma_f32_16x16x32_bf16 v[86:89], v[134:137], v[216:219], v[86:89]
	v_mfma_f32_16x16x32_bf16 v[74:77], v[148:151], v[216:219], v[74:77]
	s_setprio 0
	s_setprio 1
	v_mfma_f32_16x16x32_bf16 v[114:117], v[152:155], v[172:175], v[114:117]
	v_mfma_f32_16x16x32_bf16 v[110:113], v[164:167], v[172:175], v[110:113]
	v_mfma_f32_16x16x32_bf16 v[98:101], v[152:155], v[180:183], v[98:101]
	v_mfma_f32_16x16x32_bf16 v[94:97], v[164:167], v[180:183], v[94:97]
	v_mfma_f32_16x16x32_bf16 v[82:85], v[152:155], v[204:207], v[82:85]
	v_mfma_f32_16x16x32_bf16 v[78:81], v[164:167], v[204:207], v[78:81]
	v_mfma_f32_16x16x32_bf16 v[70:73], v[152:155], v[212:215], v[70:73]
	v_mfma_f32_16x16x32_bf16 v[66:69], v[164:167], v[212:215], v[66:69]
	v_mfma_f32_16x16x32_bf16 v[114:117], v[160:163], v[176:179], v[114:117]
	v_mfma_f32_16x16x32_bf16 v[110:113], v[168:171], v[176:179], v[110:113]
	v_mfma_f32_16x16x32_bf16 v[98:101], v[160:163], v[200:203], v[98:101]
	v_mfma_f32_16x16x32_bf16 v[94:97], v[168:171], v[200:203], v[94:97]
	v_mfma_f32_16x16x32_bf16 v[82:85], v[160:163], v[208:211], v[82:85]
	v_mfma_f32_16x16x32_bf16 v[78:81], v[168:171], v[208:211], v[78:81]
	v_mfma_f32_16x16x32_bf16 v[70:73], v[160:163], v[216:219], v[70:73]
	v_mfma_f32_16x16x32_bf16 v[66:69], v[168:171], v[216:219], v[66:69]
	s_setprio 0
	s_barrier
	s_add_i32 s46, s70, s57
	s_add_i32 m0, s46, 0xffffff80
	ds_read_b128 v[172:175], v159 offset:49152
	ds_read_b128 v[176:179], v159 offset:50176
	ds_read_b128 v[180:183], v159 offset:51200
	ds_read_b128 v[200:203], v159 offset:52224
	ds_read_b128 v[204:207], v159 offset:53248
	ds_read_b128 v[208:211], v159 offset:54272
	ds_read_b128 v[212:215], v159 offset:55296
	ds_read_b128 v[216:219], v159 offset:56320
	global_load_lds_dwordx4 v0, s[50:51] offset:128
	s_add_i32 m0, s46, 0x2000
	s_add_u32 s46, s50, 0x80080
	v_lshl_add_u64 v[184:185], v[192:193], 0, s[96:97]
	s_addc_u32 s47, s51, 0
	s_add_i32 s50, s71, s57
	global_load_lds_dwordx4 v[184:185], off
	s_mov_b32 m0, s50
	s_nop 0
	global_load_lds_dwordx4 v0, s[46:47]
	s_add_i32 m0, s50, 0x2000
	s_nop 0
	global_load_lds_dwordx4 v142, s[46:47]
	s_add_i32 m0, s62, 0xffffff80
	s_nop 0
	global_load_lds_dwordx4 v0, s[54:55] offset:128
	s_add_i32 m0, s63, 0xffffff80
	s_nop 0
	global_load_lds_dwordx4 v142, s[54:55] offset:128
	s_waitcnt vmcnt(8)
	s_waitcnt lgkmcnt(0)
	s_barrier
	s_setprio 1
	s_waitcnt lgkmcnt(0)
	v_mfma_f32_16x16x32_bf16 v[62:65], v[130:133], v[172:175], v[62:65]
	v_mfma_f32_16x16x32_bf16 v[58:61], v[138:141], v[172:175], v[58:61]
	v_mfma_f32_16x16x32_bf16 v[54:57], v[130:133], v[180:183], v[54:57]
	v_mfma_f32_16x16x32_bf16 v[42:45], v[138:141], v[180:183], v[42:45]
	v_mfma_f32_16x16x32_bf16 v[38:41], v[130:133], v[204:207], v[38:41]
	v_mfma_f32_16x16x32_bf16 v[26:29], v[138:141], v[204:207], v[26:29]
	v_mfma_f32_16x16x32_bf16 v[22:25], v[130:133], v[212:215], v[22:25]
	v_mfma_f32_16x16x32_bf16 v[10:13], v[138:141], v[212:215], v[10:13]
	v_mfma_f32_16x16x32_bf16 v[62:65], v[134:137], v[176:179], v[62:65]
	v_mfma_f32_16x16x32_bf16 v[58:61], v[148:151], v[176:179], v[58:61]
	v_mfma_f32_16x16x32_bf16 v[54:57], v[134:137], v[200:203], v[54:57]
	v_mfma_f32_16x16x32_bf16 v[42:45], v[148:151], v[200:203], v[42:45]
	v_mfma_f32_16x16x32_bf16 v[38:41], v[134:137], v[208:211], v[38:41]
	v_mfma_f32_16x16x32_bf16 v[26:29], v[148:151], v[208:211], v[26:29]
	v_mfma_f32_16x16x32_bf16 v[22:25], v[134:137], v[216:219], v[22:25]
	v_mfma_f32_16x16x32_bf16 v[10:13], v[148:151], v[216:219], v[10:13]
	s_setprio 0
	s_setprio 1
	v_mfma_f32_16x16x32_bf16 v[50:53], v[152:155], v[172:175], v[50:53]
	v_mfma_f32_16x16x32_bf16 v[46:49], v[164:167], v[172:175], v[46:49]
	v_mfma_f32_16x16x32_bf16 v[34:37], v[152:155], v[180:183], v[34:37]
	v_mfma_f32_16x16x32_bf16 v[30:33], v[164:167], v[180:183], v[30:33]
	v_mfma_f32_16x16x32_bf16 v[18:21], v[152:155], v[204:207], v[18:21]
	v_mfma_f32_16x16x32_bf16 v[14:17], v[164:167], v[204:207], v[14:17]
	v_mfma_f32_16x16x32_bf16 v[6:9], v[152:155], v[212:215], v[6:9]
	v_mfma_f32_16x16x32_bf16 v[2:5], v[164:167], v[212:215], v[2:5]
	v_mfma_f32_16x16x32_bf16 v[50:53], v[160:163], v[176:179], v[50:53]
	v_mfma_f32_16x16x32_bf16 v[46:49], v[168:171], v[176:179], v[46:49]
	v_mfma_f32_16x16x32_bf16 v[34:37], v[160:163], v[200:203], v[34:37]
	v_mfma_f32_16x16x32_bf16 v[30:33], v[168:171], v[200:203], v[30:33]
	v_mfma_f32_16x16x32_bf16 v[18:21], v[160:163], v[208:211], v[18:21]
	v_mfma_f32_16x16x32_bf16 v[14:17], v[168:171], v[208:211], v[14:17]
	v_mfma_f32_16x16x32_bf16 v[6:9], v[160:163], v[216:219], v[6:9]
	v_mfma_f32_16x16x32_bf16 v[2:5], v[168:171], v[216:219], v[2:5]
	s_setprio 0
	s_barrier
	s_add_i32 s69, s69, 2
	s_add_u32 s67, s67, 0x100
	s_addc_u32 s68, s68, 0
	s_cmp_gt_u32 s69, 29
	s_mov_b64 s[46:47], s[48:49]
	s_cbranch_scc0 .LBB0_70
	s_andn2_b64 vcc, s[12:13], s[40:41]
	s_cbranch_vccz .LBB0_73
	s_barrier
;     __device__ __forceinline__ void operator()(const f32x4 (&acc)[2][2][4][2], const pg8::Unit& u, int wr, int wc, int fr, int fq) const {
;         const int row0 = u.pm * 256 + wr * 64 + fr, col0 = u.pn * 256 + wc * 32 + 4 * fq;
; #pragma unroll
;         for (int ai = 0; ai < 2; ++ai) {
;             f32x4 r[4][2][2];
; #pragma unroll
;             for (int m = 0; m < 4; ++m) { const size_t off = (size_t)(row0 + ai * 128 + m * 16) * 2048 + col0;
; #pragma unroll
;                 for (int bj = 0; bj < 2; ++bj)
; #pragma unroll
;                     for (int n = 0; n < 2; ++n) r[m][bj][n] = *(const f32x4*)(res + off + bj * 128 + n * 16); }
;             asm volatile("" ::: "memory");
; #pragma unroll
;             for (int m = 0; m < 4; ++m) { const size_t off = (size_t)(row0 + ai * 128 + m * 16) * 2048 + col0;
; #pragma unroll
;                 for (int bj = 0; bj < 2; ++bj)
; #pragma unroll
;                     for (int n = 0; n < 2; ++n) *(f32x4*)(out + off + bj * 128 + n * 16) = r[m][bj][n] + acc[ai][bj][m][n]; }
;             asm volatile("" ::: "memory");
;         }
.LBB0_73:
	v_lshl_or_b32 v132, s20, 8, v158
	v_lshl_add_u32 v130, s44, 8, v156
	v_ashrrev_i32_e32 v133, 31, v132
	v_readlane_b32 s20, v255, 29
	v_lshlrev_b64 v[148:149], 2, v[132:133]
	v_readlane_b32 s21, v255, 30
	v_ashrrev_i32_e32 v131, 31, v130
	v_lshlrev_b64 v[152:153], 13, v[130:131]
	v_lshl_add_u64 v[150:151], s[20:21], 0, v[148:149]
	v_lshl_add_u64 v[132:133], v[150:151], 0, v[152:153]
	global_load_dwordx4 v[160:163], v[132:133], off
	global_load_dwordx4 v[164:167], v[132:133], off offset:64
	global_load_dwordx4 v[168:171], v[132:133], off offset:512
	global_load_dwordx4 v[172:175], v[132:133], off offset:576
	v_or_b32_e32 v132, 16, v130
	v_ashrrev_i32_e32 v133, 31, v132
	v_lshlrev_b64 v[184:185], 13, v[132:133]
	v_lshl_add_u64 v[132:133], v[150:151], 0, v[184:185]
	global_load_dwordx4 v[176:179], v[132:133], off
	global_load_dwordx4 v[180:183], v[132:133], off offset:64
	global_load_dwordx4 v[200:203], v[132:133], off offset:512
	global_load_dwordx4 v[204:207], v[132:133], off offset:576
	v_or_b32_e32 v132, 32, v130
	v_ashrrev_i32_e32 v133, 31, v132
	v_or_b32_e32 v130, 48, v130
	v_lshlrev_b64 v[192:193], 13, v[132:133]
	v_ashrrev_i32_e32 v131, 31, v130
	v_lshl_add_u64 v[132:133], v[150:151], 0, v[192:193]
	v_lshlrev_b64 v[154:155], 13, v[130:131]
	global_load_dwordx4 v[208:211], v[132:133], off
	global_load_dwordx4 v[212:215], v[132:133], off offset:64
	global_load_dwordx4 v[216:219], v[132:133], off offset:512
	global_load_dwordx4 v[220:223], v[132:133], off offset:576
	v_lshl_add_u64 v[130:131], v[150:151], 0, v[154:155]
	global_load_dwordx4 v[242:245], v[130:131], off
	global_load_dwordx4 v[138:141], v[130:131], off offset:64
	global_load_dwordx4 v[134:137], v[130:131], off offset:512
	s_nop 0
	global_load_dwordx4 v[130:133], v[130:131], off offset:576
	s_mov_b64 s[20:21], 0x100000
	s_andn2_b64 vcc, exec, s[40:41]
	s_waitcnt vmcnt(0)
	v_pk_add_f32 v[126:127], v[126:127], v[160:161]
	v_lshl_add_u64 v[160:161], s[8:9], 0, v[152:153]
	v_lshl_add_u64 v[160:161], v[160:161], 0, v[148:149]
	v_pk_add_f32 v[116:117], v[116:117], v[170:171]
	v_pk_add_f32 v[114:115], v[114:115], v[168:169]
	global_store_dwordx4 v[160:161], v[114:117], off offset:512
	v_pk_add_f32 v[112:113], v[112:113], v[174:175]
	v_pk_add_f32 v[100:101], v[100:101], v[202:203]
	v_lshl_add_u64 v[114:115], s[8:9], 0, v[184:185]
	v_lshl_add_u64 v[114:115], v[114:115], 0, v[148:149]
	v_pk_add_f32 v[98:99], v[98:99], v[200:201]
	global_store_dwordx4 v[114:115], v[98:101], off offset:512
	v_pk_add_f32 v[110:111], v[110:111], v[172:173]
	v_pk_add_f32 v[96:97], v[96:97], v[206:207]
	v_lshl_add_u64 v[98:99], s[8:9], 0, v[192:193]
	v_lshl_add_u64 v[98:99], v[98:99], 0, v[148:149]
	v_pk_add_f32 v[84:85], v[84:85], v[218:219]
	v_pk_add_f32 v[82:83], v[82:83], v[216:217]
	v_pk_add_f32 v[94:95], v[94:95], v[204:205]
	global_store_dwordx4 v[98:99], v[82:85], off offset:512
	v_pk_add_f32 v[80:81], v[80:81], v[222:223]
	v_pk_add_f32 v[78:79], v[78:79], v[220:221]
	v_lshl_add_u64 v[82:83], s[8:9], 0, v[154:155]
	v_pk_add_f32 v[128:129], v[128:129], v[162:163]
	v_pk_add_f32 v[124:125], v[124:125], v[166:167]
	v_pk_add_f32 v[122:123], v[122:123], v[164:165]
	global_store_dwordx4 v[160:161], v[110:113], off offset:576
	v_pk_add_f32 v[108:109], v[108:109], v[182:183]
	v_pk_add_f32 v[106:107], v[106:107], v[180:181]
	v_pk_add_f32 v[112:113], v[120:121], v[178:179]
	v_pk_add_f32 v[110:111], v[118:119], v[176:177]
	global_store_dwordx4 v[114:115], v[94:97], off offset:576
	v_pk_add_f32 v[92:93], v[92:93], v[214:215]
	v_pk_add_f32 v[90:91], v[90:91], v[212:213]
	v_pk_add_f32 v[96:97], v[104:105], v[210:211]
	v_pk_add_f32 v[94:95], v[102:103], v[208:209]
	global_store_dwordx4 v[98:99], v[78:81], off offset:576
	v_lshl_add_u64 v[82:83], v[82:83], 0, v[148:149]
	v_pk_add_f32 v[76:77], v[76:77], v[140:141]
	v_pk_add_f32 v[80:81], v[88:89], v[244:245]
	v_pk_add_f32 v[78:79], v[86:87], v[242:243]
	v_pk_add_f32 v[74:75], v[74:75], v[138:139]
	v_pk_add_f32 v[72:73], v[72:73], v[136:137]
	v_pk_add_f32 v[70:71], v[70:71], v[134:135]
	v_pk_add_f32 v[68:69], v[68:69], v[132:133]
	v_pk_add_f32 v[66:67], v[66:67], v[130:131]
	global_store_dwordx4 v[160:161], v[126:129], off
	global_store_dwordx4 v[160:161], v[122:125], off offset:64
	global_store_dwordx4 v[114:115], v[110:113], off
	global_store_dwordx4 v[114:115], v[106:109], off offset:64
	global_store_dwordx4 v[98:99], v[94:97], off
	global_store_dwordx4 v[98:99], v[90:93], off offset:64
	global_store_dwordx4 v[82:83], v[78:81], off
	global_store_dwordx4 v[82:83], v[74:77], off offset:64
	global_store_dwordx4 v[82:83], v[70:73], off offset:512
	global_store_dwordx4 v[82:83], v[66:69], off offset:576
	v_lshl_add_u64 v[132:133], v[152:153], 0, s[20:21]
	s_mov_b64 s[20:21], 0x120000
	v_lshl_add_u64 v[66:67], v[150:151], 0, v[132:133]
	global_load_dwordx4 v[80:83], v[66:67], off
	global_load_dwordx4 v[84:87], v[66:67], off offset:64
	global_load_dwordx4 v[88:91], v[66:67], off offset:512
	global_load_dwordx4 v[92:95], v[66:67], off offset:576
	v_lshl_add_u64 v[134:135], v[152:153], 0, s[20:21]
	v_lshl_add_u64 v[66:67], v[150:151], 0, v[134:135]
	s_mov_b64 s[20:21], 0x140000
	global_load_dwordx4 v[96:99], v[66:67], off
	global_load_dwordx4 v[100:103], v[66:67], off offset:64
	global_load_dwordx4 v[104:107], v[66:67], off offset:512
	global_load_dwordx4 v[108:111], v[66:67], off offset:576
	v_lshl_add_u64 v[136:137], v[152:153], 0, s[20:21]
	s_mov_b64 s[20:21], 0x160000
	v_lshl_add_u64 v[66:67], v[150:151], 0, v[136:137]
	v_lshl_add_u64 v[78:79], v[152:153], 0, s[20:21]
	global_load_dwordx4 v[112:115], v[66:67], off
	global_load_dwordx4 v[116:119], v[66:67], off offset:64
	global_load_dwordx4 v[120:123], v[66:67], off offset:512
	global_load_dwordx4 v[124:127], v[66:67], off offset:576
	v_lshl_add_u64 v[66:67], v[150:151], 0, v[78:79]
	global_load_dwordx4 v[128:131], v[66:67], off
	global_load_dwordx4 v[74:77], v[66:67], off offset:64
	global_load_dwordx4 v[70:73], v[66:67], off offset:512
	s_nop 0
	global_load_dwordx4 v[66:69], v[66:67], off offset:576
	s_mov_b64 s[20:21], -1
	s_waitcnt vmcnt(15)
; #define PG8_BAR __builtin_amdgcn_s_barrier()
; template <class Epi, class Sched, bool ALIGN_EPI = false, bool SP2 = false>
; __device__ __forceinline__ void gemm_phase(LAS unsigned char* lds, const Gemm g, const Sched& S, const Epi& E, const int tid_) {
;     ...
;         if (!has_next) break;
; #pragma unroll
;         for (int a = 0; a < 2; ++a)
; #pragma unroll
;             for (int b = 0; b < 2; ++b)
; #pragma unroll
;                 for (int m = 0; m < 4; ++m)
; #pragma unroll
;                     for (int n = 0; n < 2; ++n) acc[a][b][m][n] = (f32x4){0.f, 0.f, 0.f, 0.f};
;         cur = nxt; cA = nA; cB = nB; ++ui;
;         if constexpr (ALIGN_EPI) { if (wr == 1) PG8_BAR; }
;     __device__ __forceinline__ void operator()(const f32x4 (&acc)[2][2][4][2], const pg8::Unit& u, int wr, int wc, int fr, int fq) const {
;     ...
;         for (int ai = 0; ai < 2; ++ai) {
;             f32x4 r[4][2][2];
; #pragma unroll
;             for (int m = 0; m < 4; ++m) { const size_t off = (size_t)(row0 + ai * 128 + m * 16) * 2048 + col0;
; #pragma unroll
;                 for (int bj = 0; bj < 2; ++bj)
; #pragma unroll
;                     for (int n = 0; n < 2; ++n) r[m][bj][n] = *(const f32x4*)(res + off + bj * 128 + n * 16); }
;             asm volatile("" ::: "memory");
; #pragma unroll
;             for (int m = 0; m < 4; ++m) { const size_t off = (size_t)(row0 + ai * 128 + m * 16) * 2048 + col0;
; #pragma unroll
;                 for (int bj = 0; bj < 2; ++bj)
; #pragma unroll
;                     for (int n = 0; n < 2; ++n) *(f32x4*)(out + off + bj * 128 + n * 16) = r[m][bj][n] + acc[ai][bj][m][n]; }
;             asm volatile("" ::: "memory");
;         }
	v_pk_add_f32 v[62:63], v[62:63], v[80:81]
	v_lshl_add_u64 v[80:81], s[8:9], 0, v[132:133]
	v_lshl_add_u64 v[80:81], v[80:81], 0, v[148:149]
	s_waitcnt vmcnt(13)
	v_pk_add_f32 v[52:53], v[52:53], v[90:91]
	v_pk_add_f32 v[50:51], v[50:51], v[88:89]
	global_store_dwordx4 v[80:81], v[50:53], off offset:512
	s_waitcnt vmcnt(10)
	v_pk_add_f32 v[36:37], v[36:37], v[106:107]
	v_pk_add_f32 v[34:35], v[34:35], v[104:105]
	v_lshl_add_u64 v[50:51], s[8:9], 0, v[134:135]
	v_lshl_add_u64 v[50:51], v[50:51], 0, v[148:149]
	global_store_dwordx4 v[50:51], v[34:37], off offset:512
	s_waitcnt vmcnt(7)
	v_pk_add_f32 v[20:21], v[20:21], v[122:123]
	v_pk_add_f32 v[18:19], v[18:19], v[120:121]
	v_lshl_add_u64 v[34:35], s[8:9], 0, v[136:137]
	v_lshl_add_u64 v[34:35], v[34:35], 0, v[148:149]
	v_pk_add_f32 v[48:49], v[48:49], v[94:95]
	v_pk_add_f32 v[46:47], v[46:47], v[92:93]
	v_pk_add_f32 v[32:33], v[32:33], v[110:111]
	v_pk_add_f32 v[30:31], v[30:31], v[108:109]
	global_store_dwordx4 v[34:35], v[18:21], off offset:512
	s_waitcnt vmcnt(7)
	v_pk_add_f32 v[16:17], v[16:17], v[126:127]
	v_pk_add_f32 v[14:15], v[14:15], v[124:125]
	v_lshl_add_u64 v[18:19], s[8:9], 0, v[78:79]
	v_pk_add_f32 v[64:65], v[64:65], v[82:83]
	v_pk_add_f32 v[60:61], v[60:61], v[86:87]
	v_pk_add_f32 v[58:59], v[58:59], v[84:85]
	global_store_dwordx4 v[80:81], v[46:49], off offset:576
	v_pk_add_f32 v[44:45], v[44:45], v[102:103]
	v_pk_add_f32 v[42:43], v[42:43], v[100:101]
	v_pk_add_f32 v[48:49], v[56:57], v[98:99]
	v_pk_add_f32 v[46:47], v[54:55], v[96:97]
	global_store_dwordx4 v[50:51], v[30:33], off offset:576
	v_pk_add_f32 v[28:29], v[28:29], v[118:119]
	v_pk_add_f32 v[26:27], v[26:27], v[116:117]
	v_pk_add_f32 v[32:33], v[40:41], v[114:115]
	v_pk_add_f32 v[30:31], v[38:39], v[112:113]
	global_store_dwordx4 v[34:35], v[14:17], off offset:576
	v_lshl_add_u64 v[18:19], v[18:19], 0, v[148:149]
	s_waitcnt vmcnt(8)
	v_pk_add_f32 v[12:13], v[12:13], v[76:77]
	v_pk_add_f32 v[16:17], v[24:25], v[130:131]
	v_pk_add_f32 v[14:15], v[22:23], v[128:129]
	v_pk_add_f32 v[10:11], v[10:11], v[74:75]
	s_waitcnt vmcnt(7)
	v_pk_add_f32 v[8:9], v[8:9], v[72:73]
	v_pk_add_f32 v[6:7], v[6:7], v[70:71]
	s_waitcnt vmcnt(6)
	v_pk_add_f32 v[4:5], v[4:5], v[68:69]
	v_pk_add_f32 v[2:3], v[2:3], v[66:67]
	global_store_dwordx4 v[80:81], v[62:65], off
	global_store_dwordx4 v[80:81], v[58:61], off offset:64
	global_store_dwordx4 v[50:51], v[46:49], off
	global_store_dwordx4 v[50:51], v[42:45], off offset:64
	global_store_dwordx4 v[34:35], v[30:33], off
	global_store_dwordx4 v[34:35], v[26:29], off offset:64
	global_store_dwordx4 v[18:19], v[14:17], off
	global_store_dwordx4 v[18:19], v[10:13], off offset:64
	global_store_dwordx4 v[18:19], v[6:9], off offset:512
	global_store_dwordx4 v[18:19], v[2:5], off offset:576
	s_cbranch_vccnz .LBB0_62
	s_andn2_b64 vcc, exec, s[10:11]
	s_cbranch_vccnz .LBB0_61
	s_nop 0
	s_branch .LBB0_61

; #define PG8_STAGE(bufoff, gbase, voff) do { _Pragma("unroll") for (int _i = 0; _i < 2; ++_i) \
;         __builtin_amdgcn_global_load_lds((const unsigned*)((const char*)(gbase) + (voff)[_i]), (LAS unsigned*)(lds + (bufoff) + ldsw + _i * 8192), 16, 0, 0); } while (0)
; #define PG8_LDA(dst, b, h) do { _Pragma("unroll") for (int m = 0; m < 4; ++m) _Pragma("unroll") for (int k = 0; k < 2; ++k) dst[m][k] = *(const LAS bf16x8*)(lds + PG8_SA(b, h) + aoff + m * 2048 + k * 1024); } while (0)
; #define PG8_LDB(dst, b, h) do { _Pragma("unroll") for (int n = 0; n < 2; ++n) _Pragma("unroll") for (int k = 0; k < 2; ++k) dst[n][k] = *(const LAS bf16x8*)(lds + PG8_SB(b, h) + boff + n * 2048 + k * 1024); } while (0)
; #define PG8_MMA(ai, bj, At, Bt) do { __builtin_amdgcn_s_setprio(1); _Pragma("unroll") for (int m = 0; m < 4; ++m) _Pragma("unroll") for (int n = 0; n < 2; ++n) _Pragma("unroll") for (int k = 0; k < 2; ++k) \
;         acc[ai][bj][m][n] = __builtin_amdgcn_mfma_f32_16x16x32_bf16(Bt[n][k], At[m][k], acc[ai][bj][m][n], 0, 0, 0); __builtin_amdgcn_s_setprio(0); } while (0)
; #define PG8_WAIT_V(n) asm volatile("s_waitcnt vmcnt(" #n ")" ::: "memory")
; #define PG8_BAR __builtin_amdgcn_s_barrier()
; template <class Epi, class Sched, bool ALIGN_EPI = false, bool SP2 = false>
; __device__ __forceinline__ void gemm_phase(LAS unsigned char* lds, const Gemm g, const Sched& S, const Epi& E, const int tid_) {
;     ...
;         for (int t = 0; t < nt; t += 2) {
;             const bool last = (t == nt - 2);
;             const char* a1 = cA + (size_t)(t + 1) * kstep;
;             const char* a2 = last ? nA : cA + (size_t)(t + 2) * kstep; const char* b2 = last ? nB : cB + (size_t)(t + 2) * kstep;
;             const char* a3 = a2 + kstep; const char* b3 = b2 + kstep;
;             if (last && has_next) S.a_ready(nxt);
;             if constexpr (SP2) {
;             PG8_LDB(B0, 0, 0); PG8_LDB(B1, 0, 1); PG8_SCHED; PG8_LDA(At, 0, 0); PG8_STAGE(PG8_SA(1, 1), a1 + hstep, voffA);
;             PG8_WAIT_V(8); PG8_WAIT_L(0); PG8_BAR; PG8_MMA(0, 0, At, B0); PG8_MMA(0, 1, At, B1); PG8_BAR; PG8_SCHED;
;             PG8_LDA(At, 0, 1); PG8_STAGE(PG8_SB(0, 0), b2, voffB); PG8_STAGE(PG8_SB(0, 1), b2 + hstep, voffB); PG8_STAGE(PG8_SA(0, 0), a2, voffA);
;             PG8_WAIT_V(8); PG8_WAIT_L(0); PG8_BAR; PG8_MMA(1, 0, At, B0); PG8_MMA(1, 1, At, B1); PG8_BAR; PG8_SCHED;
.LBB0_96:
	s_add_u32 s54, s50, 0xfffc0080
	s_addc_u32 s55, s51, -1
	s_add_i32 s72, 0, 0x10000
	s_cmp_eq_u32 s71, 12
	s_cselect_b32 s57, s19, s55
	s_cselect_b32 s56, s20, s54
	s_cselect_b32 s55, s17, s70
	s_cselect_b32 s54, s21, s69
	s_add_i32 s74, 0, 0x14000
	v_add_u32_e32 v142, s72, v177
	v_add_u32_e32 v162, s74, v177
	ds_read_b128 v[130:133], v142
	ds_read_b128 v[134:137], v142 offset:1024
	ds_read_b128 v[138:141], v142 offset:2048
	ds_read_b128 v[142:145], v142 offset:3072
	s_nop 0
	ds_read_b128 v[146:149], v162
	ds_read_b128 v[154:157], v162 offset:1024
	ds_read_b128 v[158:161], v162 offset:2048
	ds_read_b128 v[162:165], v162 offset:3072
	s_add_i32 m0, s49, 0xc000
	ds_read_b128 v[180:183], v179
	ds_read_b128 v[206:209], v179 offset:1024
	ds_read_b128 v[210:213], v179 offset:2048
	ds_read_b128 v[214:217], v179 offset:3072
	ds_read_b128 v[218:221], v179 offset:4096
	ds_read_b128 v[222:225], v179 offset:5120
	ds_read_b128 v[242:245], v179 offset:6144
	ds_read_b128 v[246:249], v179 offset:7168
	global_load_lds_dwordx4 v150, s[50:51]
	s_add_i32 m0, s49, 0xe000
	s_nop 0
	global_load_lds_dwordx4 v152, s[50:51]
	s_waitcnt vmcnt(8)
	s_waitcnt lgkmcnt(0)
	s_barrier
	s_setprio 1
	s_waitcnt lgkmcnt(0)
	v_mfma_f32_16x16x32_bf16 v[126:129], v[130:133], v[180:183], v[126:129]
	v_mfma_f32_16x16x32_bf16 v[122:125], v[138:141], v[180:183], v[122:125]
	v_mfma_f32_16x16x32_bf16 v[118:121], v[130:133], v[210:213], v[118:121]
	v_mfma_f32_16x16x32_bf16 v[114:117], v[138:141], v[210:213], v[114:117]
	v_mfma_f32_16x16x32_bf16 v[98:101], v[130:133], v[218:221], v[98:101]
	v_mfma_f32_16x16x32_bf16 v[90:93], v[138:141], v[218:221], v[90:93]
	v_mfma_f32_16x16x32_bf16 v[82:85], v[130:133], v[242:245], v[82:85]
	v_mfma_f32_16x16x32_bf16 v[74:77], v[138:141], v[242:245], v[74:77]
	v_mfma_f32_16x16x32_bf16 v[126:129], v[134:137], v[206:209], v[126:129]
	v_mfma_f32_16x16x32_bf16 v[122:125], v[142:145], v[206:209], v[122:125]
	v_mfma_f32_16x16x32_bf16 v[118:121], v[134:137], v[214:217], v[118:121]
	v_mfma_f32_16x16x32_bf16 v[114:117], v[142:145], v[214:217], v[114:117]
	v_mfma_f32_16x16x32_bf16 v[98:101], v[134:137], v[222:225], v[98:101]
	v_mfma_f32_16x16x32_bf16 v[90:93], v[142:145], v[222:225], v[90:93]
	v_mfma_f32_16x16x32_bf16 v[82:85], v[134:137], v[246:249], v[82:85]
	v_mfma_f32_16x16x32_bf16 v[74:77], v[142:145], v[246:249], v[74:77]
	s_setprio 0
	s_setprio 1
	v_mfma_f32_16x16x32_bf16 v[110:113], v[146:149], v[180:183], v[110:113]
	v_mfma_f32_16x16x32_bf16 v[106:109], v[158:161], v[180:183], v[106:109]
	v_mfma_f32_16x16x32_bf16 v[102:105], v[146:149], v[210:213], v[102:105]
	v_mfma_f32_16x16x32_bf16 v[94:97], v[158:161], v[210:213], v[94:97]
	v_mfma_f32_16x16x32_bf16 v[86:89], v[146:149], v[218:221], v[86:89]
	v_mfma_f32_16x16x32_bf16 v[78:81], v[158:161], v[218:221], v[78:81]
	v_mfma_f32_16x16x32_bf16 v[70:73], v[146:149], v[242:245], v[70:73]
	v_mfma_f32_16x16x32_bf16 v[66:69], v[158:161], v[242:245], v[66:69]
	v_mfma_f32_16x16x32_bf16 v[110:113], v[154:157], v[206:209], v[110:113]
	v_mfma_f32_16x16x32_bf16 v[106:109], v[162:165], v[206:209], v[106:109]
	v_mfma_f32_16x16x32_bf16 v[102:105], v[154:157], v[214:217], v[102:105]
	v_mfma_f32_16x16x32_bf16 v[94:97], v[162:165], v[214:217], v[94:97]
	v_mfma_f32_16x16x32_bf16 v[86:89], v[154:157], v[222:225], v[86:89]
	v_mfma_f32_16x16x32_bf16 v[78:81], v[162:165], v[222:225], v[78:81]
	v_mfma_f32_16x16x32_bf16 v[70:73], v[154:157], v[246:249], v[70:73]
	v_mfma_f32_16x16x32_bf16 v[66:69], v[162:165], v[246:249], v[66:69]
	s_setprio 0
	s_barrier
	s_add_i32 s72, s72, s60
	s_mov_b32 m0, s72
	ds_read_b128 v[180:183], v179 offset:16384
	ds_read_b128 v[206:209], v179 offset:17408
	ds_read_b128 v[210:213], v179 offset:18432
	ds_read_b128 v[214:217], v179 offset:19456
	ds_read_b128 v[218:221], v179 offset:20480
	ds_read_b128 v[222:225], v179 offset:21504
	ds_read_b128 v[242:245], v179 offset:22528
	ds_read_b128 v[246:249], v179 offset:23552
	global_load_lds_dwordx4 v0, s[54:55]
	s_add_i32 m0, s72, 0x2000
	s_add_u32 s72, s54, 0x40000
	v_lshl_add_u64 v[236:237], s[54:55], 0, v[204:205]
	s_addc_u32 s73, s55, 0
	s_add_i32 s74, s74, s60
	global_load_lds_dwordx4 v204, s[54:55]
	s_mov_b32 m0, s74
	v_lshl_add_u64 v[252:253], s[56:57], 0, v[202:203]
	global_load_lds_dwordx4 v0, s[72:73]
	s_add_i32 m0, s74, 0x2000
	s_nop 0
	global_load_lds_dwordx4 v204, s[72:73]
	v_lshl_add_u64 v[250:251], s[56:57], 0, v[200:201]
	s_mov_b32 m0, s49
	s_nop 0
	global_load_lds_dwordx4 v200, s[56:57]
	s_mov_b32 m0, s61
	s_nop 0
	global_load_lds_dwordx4 v202, s[56:57]
	s_waitcnt vmcnt(8)
	s_waitcnt lgkmcnt(0)
	s_barrier
; #define PG8_STAGE(bufoff, gbase, voff) do { _Pragma("unroll") for (int _i = 0; _i < 2; ++_i) \
;         __builtin_amdgcn_global_load_lds((const unsigned*)((const char*)(gbase) + (voff)[_i]), (LAS unsigned*)(lds + (bufoff) + ldsw + _i * 8192), 16, 0, 0); } while (0)
; #define PG8_LDA(dst, b, h) do { _Pragma("unroll") for (int m = 0; m < 4; ++m) _Pragma("unroll") for (int k = 0; k < 2; ++k) dst[m][k] = *(const LAS bf16x8*)(lds + PG8_SA(b, h) + aoff + m * 2048 + k * 1024); } while (0)
; #define PG8_LDB(dst, b, h) do { _Pragma("unroll") for (int n = 0; n < 2; ++n) _Pragma("unroll") for (int k = 0; k < 2; ++k) dst[n][k] = *(const LAS bf16x8*)(lds + PG8_SB(b, h) + boff + n * 2048 + k * 1024); } while (0)
; #define PG8_MMA(ai, bj, At, Bt) do { __builtin_amdgcn_s_setprio(1); _Pragma("unroll") for (int m = 0; m < 4; ++m) _Pragma("unroll") for (int n = 0; n < 2; ++n) _Pragma("unroll") for (int k = 0; k < 2; ++k) \
;         acc[ai][bj][m][n] = __builtin_amdgcn_mfma_f32_16x16x32_bf16(Bt[n][k], At[m][k], acc[ai][bj][m][n], 0, 0, 0); __builtin_amdgcn_s_setprio(0); } while (0)
; #define PG8_WAIT_V(n) asm volatile("s_waitcnt vmcnt(" #n ")" ::: "memory")
; #define PG8_WAIT_L(n) asm volatile("s_waitcnt lgkmcnt(" #n ")" ::: "memory")
; #define PG8_BAR __builtin_amdgcn_s_barrier()
; #define PG8_SCHED __builtin_amdgcn_sched_barrier(0)
; template <class Epi, class Sched, bool ALIGN_EPI = false, bool SP2 = false>
; __device__ __forceinline__ void gemm_phase(LAS unsigned char* lds, const Gemm g, const Sched& S, const Epi& E, const int tid_) {
;     ...
;             PG8_WAIT_V(8); PG8_WAIT_L(0); PG8_BAR; PG8_MMA(1, 0, At, B0); PG8_MMA(1, 1, At, B1); PG8_BAR; PG8_SCHED;
;             PG8_LDB(B0, 1, 0); PG8_LDB(B1, 1, 1); PG8_SCHED; PG8_LDA(At, 1, 0); PG8_STAGE(PG8_SA(0, 1), a2 + hstep, voffA);
;             PG8_WAIT_V(8); PG8_WAIT_L(0); PG8_BAR; PG8_MMA(0, 0, At, B0); PG8_MMA(0, 1, At, B1); PG8_BAR; PG8_SCHED;
;             PG8_LDA(At, 1, 1); PG8_STAGE(PG8_SB(1, 0), b3, voffB); PG8_STAGE(PG8_SB(1, 1), b3 + hstep, voffB); PG8_STAGE(PG8_SA(1, 0), a3, voffA);
;             PG8_WAIT_V(8); PG8_WAIT_L(0); PG8_BAR; PG8_MMA(1, 0, At, B0); PG8_MMA(1, 1, At, B1); PG8_BAR; PG8_SCHED;
	s_setprio 1
	s_waitcnt lgkmcnt(0)
	v_mfma_f32_16x16x32_bf16 v[62:65], v[130:133], v[180:183], v[62:65]
	v_mfma_f32_16x16x32_bf16 v[58:61], v[138:141], v[180:183], v[58:61]
	v_mfma_f32_16x16x32_bf16 v[50:53], v[130:133], v[210:213], v[50:53]
	v_mfma_f32_16x16x32_bf16 v[42:45], v[138:141], v[210:213], v[42:45]
	v_mfma_f32_16x16x32_bf16 v[34:37], v[130:133], v[218:221], v[34:37]
	v_mfma_f32_16x16x32_bf16 v[26:29], v[138:141], v[218:221], v[26:29]
	v_mfma_f32_16x16x32_bf16 v[18:21], v[130:133], v[242:245], v[18:21]
	v_mfma_f32_16x16x32_bf16 v[10:13], v[138:141], v[242:245], v[10:13]
	v_mfma_f32_16x16x32_bf16 v[62:65], v[134:137], v[206:209], v[62:65]
	v_mfma_f32_16x16x32_bf16 v[58:61], v[142:145], v[206:209], v[58:61]
	v_mfma_f32_16x16x32_bf16 v[50:53], v[134:137], v[214:217], v[50:53]
	v_mfma_f32_16x16x32_bf16 v[42:45], v[142:145], v[214:217], v[42:45]
	v_mfma_f32_16x16x32_bf16 v[34:37], v[134:137], v[222:225], v[34:37]
	v_mfma_f32_16x16x32_bf16 v[26:29], v[142:145], v[222:225], v[26:29]
	v_mfma_f32_16x16x32_bf16 v[18:21], v[134:137], v[246:249], v[18:21]
	v_mfma_f32_16x16x32_bf16 v[10:13], v[142:145], v[246:249], v[10:13]
	s_setprio 0
	s_setprio 1
	v_mfma_f32_16x16x32_bf16 v[54:57], v[146:149], v[180:183], v[54:57]
	v_mfma_f32_16x16x32_bf16 v[46:49], v[158:161], v[180:183], v[46:49]
	v_mfma_f32_16x16x32_bf16 v[38:41], v[146:149], v[210:213], v[38:41]
	v_mfma_f32_16x16x32_bf16 v[30:33], v[158:161], v[210:213], v[30:33]
	v_mfma_f32_16x16x32_bf16 v[22:25], v[146:149], v[218:221], v[22:25]
	v_mfma_f32_16x16x32_bf16 v[14:17], v[158:161], v[218:221], v[14:17]
	v_mfma_f32_16x16x32_bf16 v[6:9], v[146:149], v[242:245], v[6:9]
	v_mfma_f32_16x16x32_bf16 v[2:5], v[158:161], v[242:245], v[2:5]
	v_mfma_f32_16x16x32_bf16 v[54:57], v[154:157], v[206:209], v[54:57]
	v_mfma_f32_16x16x32_bf16 v[46:49], v[162:165], v[206:209], v[46:49]
	v_mfma_f32_16x16x32_bf16 v[38:41], v[154:157], v[214:217], v[38:41]
	v_mfma_f32_16x16x32_bf16 v[30:33], v[162:165], v[214:217], v[30:33]
	v_mfma_f32_16x16x32_bf16 v[22:25], v[154:157], v[222:225], v[22:25]
	v_mfma_f32_16x16x32_bf16 v[14:17], v[162:165], v[222:225], v[14:17]
	v_mfma_f32_16x16x32_bf16 v[6:9], v[154:157], v[246:249], v[6:9]
	v_mfma_f32_16x16x32_bf16 v[2:5], v[162:165], v[246:249], v[2:5]
	s_setprio 0
	s_barrier
	s_add_i32 s72, 0, 0x18000
	s_add_i32 s73, 0, 0x1c000
	v_add_u32_e32 v142, s72, v177
	v_add_u32_e32 v162, s73, v177
	ds_read_b128 v[130:133], v142
	ds_read_b128 v[134:137], v142 offset:1024
	ds_read_b128 v[138:141], v142 offset:2048
	ds_read_b128 v[142:145], v142 offset:3072
	ds_read_b128 v[146:149], v162
	ds_read_b128 v[154:157], v162 offset:1024
	ds_read_b128 v[158:161], v162 offset:2048
	ds_read_b128 v[162:165], v162 offset:3072
	s_add_u32 s56, s56, 0x40000
	s_addc_u32 s57, s57, 0
	s_mov_b32 m0, s62
	ds_read_b128 v[180:183], v179 offset:32768
	ds_read_b128 v[206:209], v179 offset:33792
	ds_read_b128 v[210:213], v179 offset:34816
	ds_read_b128 v[214:217], v179 offset:35840
	ds_read_b128 v[218:221], v179 offset:36864
	ds_read_b128 v[222:225], v179 offset:37888
	ds_read_b128 v[242:245], v179 offset:38912
	ds_read_b128 v[246:249], v179 offset:39936
	global_load_lds_dwordx4 v200, s[56:57]
	s_mov_b32 m0, s63
	s_nop 0
	global_load_lds_dwordx4 v202, s[56:57]
	s_waitcnt vmcnt(8)
	s_waitcnt lgkmcnt(0)
	s_barrier
	s_setprio 1
	s_waitcnt lgkmcnt(0)
	v_mfma_f32_16x16x32_bf16 v[126:129], v[130:133], v[180:183], v[126:129]
	v_mfma_f32_16x16x32_bf16 v[122:125], v[138:141], v[180:183], v[122:125]
	v_mfma_f32_16x16x32_bf16 v[118:121], v[130:133], v[210:213], v[118:121]
	v_mfma_f32_16x16x32_bf16 v[114:117], v[138:141], v[210:213], v[114:117]
	v_mfma_f32_16x16x32_bf16 v[98:101], v[130:133], v[218:221], v[98:101]
	v_mfma_f32_16x16x32_bf16 v[90:93], v[138:141], v[218:221], v[90:93]
	v_mfma_f32_16x16x32_bf16 v[82:85], v[130:133], v[242:245], v[82:85]
	v_mfma_f32_16x16x32_bf16 v[74:77], v[138:141], v[242:245], v[74:77]
	v_mfma_f32_16x16x32_bf16 v[126:129], v[134:137], v[206:209], v[126:129]
	v_mfma_f32_16x16x32_bf16 v[122:125], v[142:145], v[206:209], v[122:125]
	v_mfma_f32_16x16x32_bf16 v[118:121], v[134:137], v[214:217], v[118:121]
	v_mfma_f32_16x16x32_bf16 v[114:117], v[142:145], v[214:217], v[114:117]
	v_mfma_f32_16x16x32_bf16 v[98:101], v[134:137], v[222:225], v[98:101]
	v_mfma_f32_16x16x32_bf16 v[90:93], v[142:145], v[222:225], v[90:93]
	v_mfma_f32_16x16x32_bf16 v[82:85], v[134:137], v[246:249], v[82:85]
	v_mfma_f32_16x16x32_bf16 v[74:77], v[142:145], v[246:249], v[74:77]
	s_setprio 0
	s_setprio 1
	v_mfma_f32_16x16x32_bf16 v[110:113], v[146:149], v[180:183], v[110:113]
	v_mfma_f32_16x16x32_bf16 v[106:109], v[158:161], v[180:183], v[106:109]
	v_mfma_f32_16x16x32_bf16 v[102:105], v[146:149], v[210:213], v[102:105]
	v_mfma_f32_16x16x32_bf16 v[94:97], v[158:161], v[210:213], v[94:97]
	v_mfma_f32_16x16x32_bf16 v[86:89], v[146:149], v[218:221], v[86:89]
	v_mfma_f32_16x16x32_bf16 v[78:81], v[158:161], v[218:221], v[78:81]
	v_mfma_f32_16x16x32_bf16 v[70:73], v[146:149], v[242:245], v[70:73]
	v_mfma_f32_16x16x32_bf16 v[66:69], v[158:161], v[242:245], v[66:69]
	v_mfma_f32_16x16x32_bf16 v[110:113], v[154:157], v[206:209], v[110:113]
	v_mfma_f32_16x16x32_bf16 v[106:109], v[162:165], v[206:209], v[106:109]
	v_mfma_f32_16x16x32_bf16 v[102:105], v[154:157], v[214:217], v[102:105]
	v_mfma_f32_16x16x32_bf16 v[94:97], v[162:165], v[214:217], v[94:97]
	v_mfma_f32_16x16x32_bf16 v[86:89], v[154:157], v[222:225], v[86:89]
	v_mfma_f32_16x16x32_bf16 v[78:81], v[162:165], v[222:225], v[78:81]
	v_mfma_f32_16x16x32_bf16 v[70:73], v[154:157], v[246:249], v[70:73]
	v_mfma_f32_16x16x32_bf16 v[66:69], v[162:165], v[246:249], v[66:69]
	s_setprio 0
	s_barrier
; #define PG8_STAGE(bufoff, gbase, voff) do { _Pragma("unroll") for (int _i = 0; _i < 2; ++_i) \
;         __builtin_amdgcn_global_load_lds((const unsigned*)((const char*)(gbase) + (voff)[_i]), (LAS unsigned*)(lds + (bufoff) + ldsw + _i * 8192), 16, 0, 0); } while (0)
; #define PG8_LDA(dst, b, h) do { _Pragma("unroll") for (int m = 0; m < 4; ++m) _Pragma("unroll") for (int k = 0; k < 2; ++k) dst[m][k] = *(const LAS bf16x8*)(lds + PG8_SA(b, h) + aoff + m * 2048 + k * 1024); } while (0)
; #define PG8_MMA(ai, bj, At, Bt) do { __builtin_amdgcn_s_setprio(1); _Pragma("unroll") for (int m = 0; m < 4; ++m) _Pragma("unroll") for (int n = 0; n < 2; ++n) _Pragma("unroll") for (int k = 0; k < 2; ++k) \
;         acc[ai][bj][m][n] = __builtin_amdgcn_mfma_f32_16x16x32_bf16(Bt[n][k], At[m][k], acc[ai][bj][m][n], 0, 0, 0); __builtin_amdgcn_s_setprio(0); } while (0)
; #define PG8_WAIT_V(n) asm volatile("s_waitcnt vmcnt(" #n ")" ::: "memory")
; #define PG8_WAIT_L(n) asm volatile("s_waitcnt lgkmcnt(" #n ")" ::: "memory")
; #define PG8_BAR __builtin_amdgcn_s_barrier()
; template <class Epi, class Sched, bool ALIGN_EPI = false, bool SP2 = false>
; __device__ __forceinline__ void gemm_phase(LAS unsigned char* lds, const Gemm g, const Sched& S, const Epi& E, const int tid_) {
;     ...
;             PG8_LDA(At, 1, 1); PG8_STAGE(PG8_SB(1, 0), b3, voffB); PG8_STAGE(PG8_SB(1, 1), b3 + hstep, voffB); PG8_STAGE(PG8_SA(1, 0), a3, voffA);
;             PG8_WAIT_V(8); PG8_WAIT_L(0); PG8_BAR; PG8_MMA(1, 0, At, B0); PG8_MMA(1, 1, At, B1); PG8_BAR; PG8_SCHED;
;     ...
;         if constexpr (ALIGN_EPI) { if (wr == 0) PG8_BAR; }
;     __device__ __forceinline__ void operator()(const f32x4 (&acc)[2][2][4][2], const pg8::Unit& u, int wr, int wc, int fr, int fq) const {
;         const int row0 = u.pm * 256 + wr * 64 + fr, col0 = u.pn * 256 + wc * 32 + 8 * fq;
; #pragma unroll
;         for (int ai = 0; ai < 2; ++ai) {
;             u32x4 gwv[4][2], pwv[4][2];
; #pragma unroll
;             for (int m = 0; m < 4; ++m) { const size_t r = (size_t)(row0 + ai * 128 + m * 16);
; #pragma unroll
;                 for (int bj = 0; bj < 2; ++bj) { gwv[m][bj] = *(const u32x4*)(sg + r * 4096 + col0 + bj * 128);
;                     pwv[m][bj] = add ? *(const u32x4*)(mg + r * 2048 + col0 + bj * 128) : (u32x4){0u, 0u, 0u, 0u}; } }
;             asm volatile("" ::: "memory");
	s_add_i32 s56, s72, s60
	s_add_i32 m0, s56, 0xffffff80
	ds_read_b128 v[180:183], v179 offset:49152
	ds_read_b128 v[206:209], v179 offset:50176
	ds_read_b128 v[210:213], v179 offset:51200
	ds_read_b128 v[214:217], v179 offset:52224
	ds_read_b128 v[218:221], v179 offset:53248
	ds_read_b128 v[222:225], v179 offset:54272
	ds_read_b128 v[242:245], v179 offset:55296
	ds_read_b128 v[246:249], v179 offset:56320
	global_load_lds_dwordx4 v0, s[54:55] offset:128
	s_add_i32 m0, s56, 0x2000
	s_add_u32 s54, s54, 0x40080
	v_lshl_add_u64 v[184:185], v[236:237], 0, s[96:97]
	s_addc_u32 s55, s55, 0
	s_add_i32 s56, s73, s60
	global_load_lds_dwordx4 v[184:185], off
	s_mov_b32 m0, s56
	s_nop 0
	global_load_lds_dwordx4 v0, s[54:55]
	s_add_i32 m0, s56, 0x2000
	s_nop 0
	global_load_lds_dwordx4 v204, s[54:55]
	v_lshl_add_u64 v[184:185], v[250:251], 0, s[96:97]
	s_mov_b32 m0, s64
	s_nop 0
	global_load_lds_dwordx4 v[184:185], off
	v_lshl_add_u64 v[184:185], v[252:253], 0, s[96:97]
	s_mov_b32 m0, s65
	s_nop 0
	global_load_lds_dwordx4 v[184:185], off
	s_waitcnt vmcnt(8)
	s_waitcnt lgkmcnt(0)
	s_barrier
	s_setprio 1
	s_waitcnt lgkmcnt(0)
	v_mfma_f32_16x16x32_bf16 v[62:65], v[130:133], v[180:183], v[62:65]
	v_mfma_f32_16x16x32_bf16 v[58:61], v[138:141], v[180:183], v[58:61]
	v_mfma_f32_16x16x32_bf16 v[50:53], v[130:133], v[210:213], v[50:53]
	v_mfma_f32_16x16x32_bf16 v[42:45], v[138:141], v[210:213], v[42:45]
	v_mfma_f32_16x16x32_bf16 v[34:37], v[130:133], v[218:221], v[34:37]
	v_mfma_f32_16x16x32_bf16 v[26:29], v[138:141], v[218:221], v[26:29]
	v_mfma_f32_16x16x32_bf16 v[18:21], v[130:133], v[242:245], v[18:21]
	v_mfma_f32_16x16x32_bf16 v[10:13], v[138:141], v[242:245], v[10:13]
	v_mfma_f32_16x16x32_bf16 v[62:65], v[134:137], v[206:209], v[62:65]
	v_mfma_f32_16x16x32_bf16 v[58:61], v[142:145], v[206:209], v[58:61]
	v_mfma_f32_16x16x32_bf16 v[50:53], v[134:137], v[214:217], v[50:53]
	v_mfma_f32_16x16x32_bf16 v[42:45], v[142:145], v[214:217], v[42:45]
	v_mfma_f32_16x16x32_bf16 v[34:37], v[134:137], v[222:225], v[34:37]
	v_mfma_f32_16x16x32_bf16 v[26:29], v[142:145], v[222:225], v[26:29]
	v_mfma_f32_16x16x32_bf16 v[18:21], v[134:137], v[246:249], v[18:21]
	v_mfma_f32_16x16x32_bf16 v[10:13], v[142:145], v[246:249], v[10:13]
	s_setprio 0
	s_setprio 1
	v_mfma_f32_16x16x32_bf16 v[54:57], v[146:149], v[180:183], v[54:57]
	v_mfma_f32_16x16x32_bf16 v[46:49], v[158:161], v[180:183], v[46:49]
	v_mfma_f32_16x16x32_bf16 v[38:41], v[146:149], v[210:213], v[38:41]
	v_mfma_f32_16x16x32_bf16 v[30:33], v[158:161], v[210:213], v[30:33]
	v_mfma_f32_16x16x32_bf16 v[22:25], v[146:149], v[218:221], v[22:25]
	v_mfma_f32_16x16x32_bf16 v[14:17], v[158:161], v[218:221], v[14:17]
	v_mfma_f32_16x16x32_bf16 v[6:9], v[146:149], v[242:245], v[6:9]
	v_mfma_f32_16x16x32_bf16 v[2:5], v[158:161], v[242:245], v[2:5]
	v_mfma_f32_16x16x32_bf16 v[54:57], v[154:157], v[206:209], v[54:57]
	v_mfma_f32_16x16x32_bf16 v[46:49], v[162:165], v[206:209], v[46:49]
	v_mfma_f32_16x16x32_bf16 v[38:41], v[154:157], v[214:217], v[38:41]
	v_mfma_f32_16x16x32_bf16 v[30:33], v[162:165], v[214:217], v[30:33]
	v_mfma_f32_16x16x32_bf16 v[22:25], v[154:157], v[222:225], v[22:25]
	v_mfma_f32_16x16x32_bf16 v[14:17], v[162:165], v[222:225], v[14:17]
	v_mfma_f32_16x16x32_bf16 v[6:9], v[154:157], v[246:249], v[6:9]
	v_mfma_f32_16x16x32_bf16 v[2:5], v[162:165], v[246:249], v[2:5]
	s_setprio 0
	s_barrier
	s_add_i32 s71, s71, 2
	s_add_u32 s50, s50, 0x100
	s_addc_u32 s51, s51, 0
	s_add_u32 s69, s69, 0x100
	s_addc_u32 s70, s70, 0
	s_cmp_gt_u32 s71, 13
	s_cbranch_scc0 .LBB0_96
	s_andn2_b64 vcc, s[14:15], s[40:41]
	s_cbranch_vccz .LBB0_99
	s_barrier
.LBB0_99:
	v_lshl_or_b32 v130, s68, 8, v178
	v_lshl_add_u32 v156, s48, 8, v176
	v_ashrrev_i32_e32 v131, 31, v130
	v_lshlrev_b64 v[154:155], 1, v[130:131]
	v_ashrrev_i32_e32 v157, 31, v156
	v_lshl_add_u64 v[158:159], s[12:13], 0, v[154:155]
	v_lshlrev_b64 v[130:131], 13, v[156:157]
	v_lshl_add_u64 v[130:131], v[158:159], 0, v[130:131]
	global_load_dwordx4 v[180:183], v[130:131], off
	global_load_dwordx4 v[206:209], v[130:131], off offset:256
	v_or_b32_e32 v130, 16, v156
	v_ashrrev_i32_e32 v131, 31, v130
	v_lshlrev_b64 v[132:133], 13, v[130:131]
	v_lshl_add_u64 v[132:133], v[158:159], 0, v[132:133]
	global_load_dwordx4 v[210:213], v[132:133], off
	global_load_dwordx4 v[146:149], v[132:133], off offset:256
	v_lshlrev_b64 v[164:165], 12, v[130:131]
	v_or_b32_e32 v130, 32, v156
	v_ashrrev_i32_e32 v131, 31, v130
	v_lshlrev_b64 v[132:133], 13, v[130:131]
	v_lshl_add_u64 v[132:133], v[158:159], 0, v[132:133]
	global_load_dwordx4 v[142:145], v[132:133], off
	global_load_dwordx4 v[134:137], v[132:133], off offset:256
	v_lshlrev_b64 v[162:163], 12, v[130:131]
	v_or_b32_e32 v130, 48, v156
	v_ashrrev_i32_e32 v131, 31, v130
	v_lshlrev_b64 v[132:133], 13, v[130:131]
	v_lshl_add_u64 v[132:133], v[158:159], 0, v[132:133]
	v_lshlrev_b64 v[160:161], 12, v[130:131]
	global_load_dwordx4 v[138:141], v[132:133], off
	s_nop 0
	global_load_dwordx4 v[130:133], v[132:133], off offset:256
	v_lshlrev_b64 v[184:185], 12, v[156:157]
	s_mov_b64 s[20:21], -1
	s_andn2_b64 vcc, exec, s[40:41]
	s_waitcnt vmcnt(0)
; __device__ __forceinline__ void unpack8(const u32x4 w, float* f) { f[0] = bflo(w.x); f[1] = bfhi(w.x); f[2] = bflo(w.y); f[3] = bfhi(w.y); f[4] = bflo(w.z); f[5] = bfhi(w.z); f[6] = bflo(w.w); f[7] = bfhi(w.w); }
; __device__ __forceinline__ u32x4 pack8(const float* f) { u32x4 w; w.x = cvt_pk_bf16(f[0], f[1]); w.y = cvt_pk_bf16(f[2], f[3]); w.z = cvt_pk_bf16(f[4], f[5]); w.w = cvt_pk_bf16(f[6], f[7]); return w; }
;     __device__ __forceinline__ void operator()(const f32x4 (&acc)[2][2][4][2], const pg8::Unit& u, int wr, int wc, int fr, int fq) const {
;         const int row0 = u.pm * 256 + wr * 64 + fr, col0 = u.pn * 256 + wc * 32 + 8 * fq;
; #pragma unroll
;         for (int ai = 0; ai < 2; ++ai) {
;             u32x4 gwv[4][2], pwv[4][2];
; #pragma unroll
;             for (int m = 0; m < 4; ++m) { const size_t r = (size_t)(row0 + ai * 128 + m * 16);
; #pragma unroll
;                 for (int bj = 0; bj < 2; ++bj) { gwv[m][bj] = *(const u32x4*)(sg + r * 4096 + col0 + bj * 128);
;                     pwv[m][bj] = add ? *(const u32x4*)(mg + r * 2048 + col0 + bj * 128) : (u32x4){0u, 0u, 0u, 0u}; } }
;             asm volatile("" ::: "memory");
; #pragma unroll
;             for (int m = 0; m < 4; ++m) { const size_t r = (size_t)(row0 + ai * 128 + m * 16);
; #pragma unroll
;                 for (int bj = 0; bj < 2; ++bj) {
;                     float gf[8], pf[8], of[8]; unpack8(gwv[m][bj], gf); unpack8(pwv[m][bj], pf);
;                     const f32x4 v0 = acc[ai][bj][m][0], v1 = acc[ai][bj][m][1];
; #pragma unroll
;                     for (int j = 0; j < 4; ++j) { of[j] = gf[j] * v0[j] + pf[j]; of[4 + j] = gf[4 + j] * v1[j] + pf[4 + j]; }
;                     *(u32x4*)(mg + r * 2048 + col0 + bj * 128) = pack8(of); } }
	v_lshlrev_b32_e32 v192, 16, v180
	v_and_b32_e32 v193, 0xffff0000, v180
	v_pk_fma_f32 v[126:127], v[126:127], v[192:193], 0 op_sel_hi:[1,1,0]
	v_lshlrev_b32_e32 v192, 16, v182
	v_and_b32_e32 v193, 0xffff0000, v182
	v_pk_fma_f32 v[192:193], v[122:123], v[192:193], 0 op_sel_hi:[1,1,0]
	v_lshlrev_b32_e32 v122, 16, v181
	v_and_b32_e32 v123, 0xffff0000, v181
	v_pk_fma_f32 v[128:129], v[128:129], v[122:123], 0 op_sel_hi:[1,1,0]
	v_lshlrev_b32_e32 v122, 16, v183
	v_and_b32_e32 v123, 0xffff0000, v183
	v_pk_fma_f32 v[180:181], v[124:125], v[122:123], 0 op_sel_hi:[1,1,0]
	v_cvt_pk_bf16_f32 v122, v126, v127
	v_lshl_add_u64 v[126:127], s[42:43], 0, v[184:185]
	v_cvt_pk_bf16_f32 v123, v128, v129
	v_cvt_pk_bf16_f32 v124, v192, v193
	v_cvt_pk_bf16_f32 v125, v180, v181
	v_lshl_add_u64 v[126:127], v[126:127], 0, v[154:155]
	global_store_dwordx4 v[126:127], v[122:125], off
	s_nop 1
	v_lshlrev_b32_e32 v122, 16, v206
	v_and_b32_e32 v123, 0xffff0000, v206
	v_pk_fma_f32 v[110:111], v[110:111], v[122:123], 0 op_sel_hi:[1,1,0]
	v_lshlrev_b32_e32 v122, 16, v208
	v_and_b32_e32 v123, 0xffff0000, v208
	v_pk_fma_f32 v[122:123], v[106:107], v[122:123], 0 op_sel_hi:[1,1,0]
	v_lshlrev_b32_e32 v106, 16, v207
	v_and_b32_e32 v107, 0xffff0000, v207
	v_pk_fma_f32 v[112:113], v[112:113], v[106:107], 0 op_sel_hi:[1,1,0]
	v_lshlrev_b32_e32 v106, 16, v209
	v_and_b32_e32 v107, 0xffff0000, v209
	v_pk_fma_f32 v[124:125], v[108:109], v[106:107], 0 op_sel_hi:[1,1,0]
	v_cvt_pk_bf16_f32 v106, v110, v111
	v_cvt_pk_bf16_f32 v107, v112, v113
	v_cvt_pk_bf16_f32 v108, v122, v123
	v_cvt_pk_bf16_f32 v109, v124, v125
	global_store_dwordx4 v[126:127], v[106:109], off offset:256
	v_lshlrev_b32_e32 v110, 16, v211
	v_and_b32_e32 v111, 0xffff0000, v211
	v_lshlrev_b32_e32 v106, 16, v210
	v_and_b32_e32 v107, 0xffff0000, v210
	v_pk_fma_f32 v[106:107], v[118:119], v[106:107], 0 op_sel_hi:[1,1,0]
	v_lshlrev_b32_e32 v108, 16, v212
	v_and_b32_e32 v109, 0xffff0000, v212
	v_pk_fma_f32 v[110:111], v[120:121], v[110:111], 0 op_sel_hi:[1,1,0]
	v_lshlrev_b32_e32 v112, 16, v213
	v_and_b32_e32 v113, 0xffff0000, v213
	v_pk_fma_f32 v[108:109], v[114:115], v[108:109], 0 op_sel_hi:[1,1,0]
	v_pk_fma_f32 v[112:113], v[116:117], v[112:113], 0 op_sel_hi:[1,1,0]
	v_cvt_pk_bf16_f32 v106, v106, v107
	v_cvt_pk_bf16_f32 v107, v110, v111
	v_lshl_add_u64 v[110:111], s[42:43], 0, v[164:165]
	v_cvt_pk_bf16_f32 v108, v108, v109
	v_cvt_pk_bf16_f32 v109, v112, v113
	v_lshl_add_u64 v[110:111], v[110:111], 0, v[154:155]
	global_store_dwordx4 v[110:111], v[106:109], off
	s_nop 1
	v_lshlrev_b32_e32 v106, 16, v146
	v_and_b32_e32 v107, 0xffff0000, v146
	v_pk_fma_f32 v[102:103], v[102:103], v[106:107], 0 op_sel_hi:[1,1,0]
	v_lshlrev_b32_e32 v106, 16, v148
	v_and_b32_e32 v107, 0xffff0000, v148
	v_pk_fma_f32 v[106:107], v[94:95], v[106:107], 0 op_sel_hi:[1,1,0]
	v_lshlrev_b32_e32 v94, 16, v147
	v_and_b32_e32 v95, 0xffff0000, v147
	v_pk_fma_f32 v[104:105], v[104:105], v[94:95], 0 op_sel_hi:[1,1,0]
	v_lshlrev_b32_e32 v94, 16, v149
	v_and_b32_e32 v95, 0xffff0000, v149
	v_pk_fma_f32 v[108:109], v[96:97], v[94:95], 0 op_sel_hi:[1,1,0]
	v_cvt_pk_bf16_f32 v94, v102, v103
	v_cvt_pk_bf16_f32 v95, v104, v105
	v_cvt_pk_bf16_f32 v96, v106, v107
	v_cvt_pk_bf16_f32 v97, v108, v109
	global_store_dwordx4 v[110:111], v[94:97], off offset:256
	s_nop 1
	v_lshlrev_b32_e32 v96, 16, v144
	v_and_b32_e32 v97, 0xffff0000, v144
	v_lshlrev_b32_e32 v94, 16, v142
	v_and_b32_e32 v95, 0xffff0000, v142
	v_pk_fma_f32 v[96:97], v[90:91], v[96:97], 0 op_sel_hi:[1,1,0]
	v_lshlrev_b32_e32 v90, 16, v143
	v_and_b32_e32 v91, 0xffff0000, v143
	v_pk_fma_f32 v[94:95], v[98:99], v[94:95], 0 op_sel_hi:[1,1,0]
	v_pk_fma_f32 v[98:99], v[100:101], v[90:91], 0 op_sel_hi:[1,1,0]
	v_lshlrev_b32_e32 v90, 16, v145
	v_and_b32_e32 v91, 0xffff0000, v145
	v_pk_fma_f32 v[100:101], v[92:93], v[90:91], 0 op_sel_hi:[1,1,0]
	v_cvt_pk_bf16_f32 v90, v94, v95
	v_lshl_add_u64 v[94:95], s[42:43], 0, v[162:163]
	v_cvt_pk_bf16_f32 v91, v98, v99
	v_cvt_pk_bf16_f32 v92, v96, v97
	v_cvt_pk_bf16_f32 v93, v100, v101
	v_lshl_add_u64 v[94:95], v[94:95], 0, v[154:155]
	global_store_dwordx4 v[94:95], v[90:93], off
	s_nop 1
	v_lshlrev_b32_e32 v90, 16, v134
	v_and_b32_e32 v91, 0xffff0000, v134
	v_pk_fma_f32 v[86:87], v[86:87], v[90:91], 0 op_sel_hi:[1,1,0]
	v_lshlrev_b32_e32 v90, 16, v136
	v_and_b32_e32 v91, 0xffff0000, v136
	v_pk_fma_f32 v[90:91], v[78:79], v[90:91], 0 op_sel_hi:[1,1,0]
	v_lshlrev_b32_e32 v78, 16, v135
	v_and_b32_e32 v79, 0xffff0000, v135
	v_pk_fma_f32 v[88:89], v[88:89], v[78:79], 0 op_sel_hi:[1,1,0]
	v_lshlrev_b32_e32 v78, 16, v137
	v_and_b32_e32 v79, 0xffff0000, v137
	v_pk_fma_f32 v[92:93], v[80:81], v[78:79], 0 op_sel_hi:[1,1,0]
	v_cvt_pk_bf16_f32 v78, v86, v87
	v_cvt_pk_bf16_f32 v79, v88, v89
	v_cvt_pk_bf16_f32 v80, v90, v91
	v_cvt_pk_bf16_f32 v81, v92, v93
	global_store_dwordx4 v[94:95], v[78:81], off offset:256
	s_nop 1
	v_lshlrev_b32_e32 v80, 16, v140
	v_and_b32_e32 v81, 0xffff0000, v140
	v_lshlrev_b32_e32 v78, 16, v138
	v_and_b32_e32 v79, 0xffff0000, v138
	v_pk_fma_f32 v[80:81], v[74:75], v[80:81], 0 op_sel_hi:[1,1,0]
	v_lshlrev_b32_e32 v74, 16, v139
	v_and_b32_e32 v75, 0xffff0000, v139
	v_pk_fma_f32 v[78:79], v[82:83], v[78:79], 0 op_sel_hi:[1,1,0]
	v_pk_fma_f32 v[82:83], v[84:85], v[74:75], 0 op_sel_hi:[1,1,0]
	v_lshlrev_b32_e32 v74, 16, v141
	v_and_b32_e32 v75, 0xffff0000, v141
	v_pk_fma_f32 v[84:85], v[76:77], v[74:75], 0 op_sel_hi:[1,1,0]
	v_cvt_pk_bf16_f32 v74, v78, v79
	v_lshl_add_u64 v[78:79], s[42:43], 0, v[160:161]
	v_cvt_pk_bf16_f32 v75, v82, v83
	v_cvt_pk_bf16_f32 v76, v80, v81
	v_cvt_pk_bf16_f32 v77, v84, v85
	v_lshl_add_u64 v[78:79], v[78:79], 0, v[154:155]
; __device__ __forceinline__ void unpack8(const u32x4 w, float* f) { f[0] = bflo(w.x); f[1] = bfhi(w.x); f[2] = bflo(w.y); f[3] = bfhi(w.y); f[4] = bflo(w.z); f[5] = bfhi(w.z); f[6] = bflo(w.w); f[7] = bfhi(w.w); }
; __device__ __forceinline__ u32x4 pack8(const float* f) { u32x4 w; w.x = cvt_pk_bf16(f[0], f[1]); w.y = cvt_pk_bf16(f[2], f[3]); w.z = cvt_pk_bf16(f[4], f[5]); w.w = cvt_pk_bf16(f[6], f[7]); return w; }
;     __device__ __forceinline__ void operator()(const f32x4 (&acc)[2][2][4][2], const pg8::Unit& u, int wr, int wc, int fr, int fq) const {
;     ...
;         for (int ai = 0; ai < 2; ++ai) {
;             u32x4 gwv[4][2], pwv[4][2];
; #pragma unroll
;             for (int m = 0; m < 4; ++m) { const size_t r = (size_t)(row0 + ai * 128 + m * 16);
; #pragma unroll
;                 for (int bj = 0; bj < 2; ++bj) { gwv[m][bj] = *(const u32x4*)(sg + r * 4096 + col0 + bj * 128);
;                     pwv[m][bj] = add ? *(const u32x4*)(mg + r * 2048 + col0 + bj * 128) : (u32x4){0u, 0u, 0u, 0u}; } }
;             asm volatile("" ::: "memory");
; #pragma unroll
;             for (int m = 0; m < 4; ++m) { const size_t r = (size_t)(row0 + ai * 128 + m * 16);
; #pragma unroll
;                 for (int bj = 0; bj < 2; ++bj) {
;                     float gf[8], pf[8], of[8]; unpack8(gwv[m][bj], gf); unpack8(pwv[m][bj], pf);
;                     const f32x4 v0 = acc[ai][bj][m][0], v1 = acc[ai][bj][m][1];
; #pragma unroll
;                     for (int j = 0; j < 4; ++j) { of[j] = gf[j] * v0[j] + pf[j]; of[4 + j] = gf[4 + j] * v1[j] + pf[4 + j]; }
;                     *(u32x4*)(mg + r * 2048 + col0 + bj * 128) = pack8(of); } }
	global_store_dwordx4 v[78:79], v[74:77], off
	s_nop 1
	v_lshlrev_b32_e32 v74, 16, v130
	v_and_b32_e32 v75, 0xffff0000, v130
	v_pk_fma_f32 v[70:71], v[70:71], v[74:75], 0 op_sel_hi:[1,1,0]
	v_lshlrev_b32_e32 v74, 16, v132
	v_and_b32_e32 v75, 0xffff0000, v132
	v_pk_fma_f32 v[74:75], v[66:67], v[74:75], 0 op_sel_hi:[1,1,0]
	v_lshlrev_b32_e32 v66, 16, v131
	v_and_b32_e32 v67, 0xffff0000, v131
	v_pk_fma_f32 v[72:73], v[72:73], v[66:67], 0 op_sel_hi:[1,1,0]
	v_lshlrev_b32_e32 v66, 16, v133
	v_and_b32_e32 v67, 0xffff0000, v133
	v_pk_fma_f32 v[76:77], v[68:69], v[66:67], 0 op_sel_hi:[1,1,0]
	v_cvt_pk_bf16_f32 v66, v70, v71
	v_cvt_pk_bf16_f32 v67, v72, v73
	v_cvt_pk_bf16_f32 v68, v74, v75
	v_cvt_pk_bf16_f32 v69, v76, v77
	global_store_dwordx4 v[78:79], v[66:69], off offset:256
	s_nop 1
	v_add_u32_e32 v66, 0x80, v156
	v_ashrrev_i32_e32 v67, 31, v66
	v_lshlrev_b64 v[68:69], 13, v[66:67]
	v_lshl_add_u64 v[68:69], v[158:159], 0, v[68:69]
	global_load_dwordx4 v[70:73], v[68:69], off
	global_load_dwordx4 v[74:77], v[68:69], off offset:256
	v_lshlrev_b64 v[98:99], 12, v[66:67]
	v_add_u32_e32 v66, 0x90, v156
	v_ashrrev_i32_e32 v67, 31, v66
	v_lshlrev_b64 v[68:69], 13, v[66:67]
	v_lshl_add_u64 v[68:69], v[158:159], 0, v[68:69]
	global_load_dwordx4 v[78:81], v[68:69], off
	global_load_dwordx4 v[82:85], v[68:69], off offset:256
	v_lshlrev_b64 v[100:101], 12, v[66:67]
	v_add_u32_e32 v66, 0xa0, v156
	v_ashrrev_i32_e32 v67, 31, v66
	v_lshlrev_b64 v[68:69], 13, v[66:67]
	v_lshl_add_u64 v[68:69], v[158:159], 0, v[68:69]
	global_load_dwordx4 v[86:89], v[68:69], off
	global_load_dwordx4 v[90:93], v[68:69], off offset:256
	v_lshlrev_b64 v[102:103], 12, v[66:67]
	v_add_u32_e32 v66, 0xb0, v156
	v_ashrrev_i32_e32 v67, 31, v66
	v_lshlrev_b64 v[68:69], 13, v[66:67]
	v_lshl_add_u64 v[68:69], v[158:159], 0, v[68:69]
	v_lshlrev_b64 v[104:105], 12, v[66:67]
	global_load_dwordx4 v[94:97], v[68:69], off
	s_nop 0
	global_load_dwordx4 v[66:69], v[68:69], off offset:256
	s_waitcnt vmcnt(7)
	v_lshlrev_b32_e32 v106, 16, v70
	v_and_b32_e32 v107, 0xffff0000, v70
	v_pk_fma_f32 v[62:63], v[62:63], v[106:107], 0 op_sel_hi:[1,1,0]
	v_lshlrev_b32_e32 v106, 16, v72
	v_and_b32_e32 v107, 0xffff0000, v72
	v_pk_fma_f32 v[106:107], v[58:59], v[106:107], 0 op_sel_hi:[1,1,0]
	v_lshlrev_b32_e32 v58, 16, v71
	v_and_b32_e32 v59, 0xffff0000, v71
	v_pk_fma_f32 v[64:65], v[64:65], v[58:59], 0 op_sel_hi:[1,1,0]
	v_lshlrev_b32_e32 v58, 16, v73
	v_and_b32_e32 v59, 0xffff0000, v73
	v_pk_fma_f32 v[70:71], v[60:61], v[58:59], 0 op_sel_hi:[1,1,0]
	v_cvt_pk_bf16_f32 v58, v62, v63
	v_lshl_add_u64 v[62:63], s[42:43], 0, v[98:99]
	v_cvt_pk_bf16_f32 v59, v64, v65
	v_cvt_pk_bf16_f32 v60, v106, v107
	v_cvt_pk_bf16_f32 v61, v70, v71
	v_lshl_add_u64 v[62:63], v[62:63], 0, v[154:155]
	global_store_dwordx4 v[62:63], v[58:61], off
	s_waitcnt vmcnt(7)
	s_nop 0
	v_lshlrev_b32_e32 v58, 16, v74
	v_and_b32_e32 v59, 0xffff0000, v74
	v_pk_fma_f32 v[54:55], v[54:55], v[58:59], 0 op_sel_hi:[1,1,0]
	v_lshlrev_b32_e32 v58, 16, v76
	v_and_b32_e32 v59, 0xffff0000, v76
	v_pk_fma_f32 v[58:59], v[46:47], v[58:59], 0 op_sel_hi:[1,1,0]
	v_lshlrev_b32_e32 v46, 16, v75
	v_and_b32_e32 v47, 0xffff0000, v75
	v_pk_fma_f32 v[56:57], v[56:57], v[46:47], 0 op_sel_hi:[1,1,0]
	v_lshlrev_b32_e32 v46, 16, v77
	v_and_b32_e32 v47, 0xffff0000, v77
	v_pk_fma_f32 v[60:61], v[48:49], v[46:47], 0 op_sel_hi:[1,1,0]
	v_cvt_pk_bf16_f32 v46, v54, v55
	v_cvt_pk_bf16_f32 v47, v56, v57
	v_cvt_pk_bf16_f32 v48, v58, v59
	v_cvt_pk_bf16_f32 v49, v60, v61
	global_store_dwordx4 v[62:63], v[46:49], off offset:256
	s_waitcnt vmcnt(7)
	s_nop 0
	v_lshlrev_b32_e32 v48, 16, v80
	v_and_b32_e32 v49, 0xffff0000, v80
	v_lshlrev_b32_e32 v46, 16, v78
	v_and_b32_e32 v47, 0xffff0000, v78
	v_pk_fma_f32 v[48:49], v[42:43], v[48:49], 0 op_sel_hi:[1,1,0]
	v_lshlrev_b32_e32 v42, 16, v79
	v_and_b32_e32 v43, 0xffff0000, v79
	v_pk_fma_f32 v[46:47], v[50:51], v[46:47], 0 op_sel_hi:[1,1,0]
	v_pk_fma_f32 v[50:51], v[52:53], v[42:43], 0 op_sel_hi:[1,1,0]
	v_lshlrev_b32_e32 v42, 16, v81
	v_and_b32_e32 v43, 0xffff0000, v81
	v_pk_fma_f32 v[52:53], v[44:45], v[42:43], 0 op_sel_hi:[1,1,0]
	v_cvt_pk_bf16_f32 v42, v46, v47
	v_lshl_add_u64 v[46:47], s[42:43], 0, v[100:101]
	v_cvt_pk_bf16_f32 v43, v50, v51
	v_cvt_pk_bf16_f32 v44, v48, v49
	v_cvt_pk_bf16_f32 v45, v52, v53
	v_lshl_add_u64 v[46:47], v[46:47], 0, v[154:155]
	global_store_dwordx4 v[46:47], v[42:45], off
	s_waitcnt vmcnt(7)
; __device__ __forceinline__ void unpack8(const u32x4 w, float* f) { f[0] = bflo(w.x); f[1] = bfhi(w.x); f[2] = bflo(w.y); f[3] = bfhi(w.y); f[4] = bflo(w.z); f[5] = bfhi(w.z); f[6] = bflo(w.w); f[7] = bfhi(w.w); }
; __device__ __forceinline__ u32x4 pack8(const float* f) { u32x4 w; w.x = cvt_pk_bf16(f[0], f[1]); w.y = cvt_pk_bf16(f[2], f[3]); w.z = cvt_pk_bf16(f[4], f[5]); w.w = cvt_pk_bf16(f[6], f[7]); return w; }
; #define PG8_BAR __builtin_amdgcn_s_barrier()
; template <class Epi, class Sched, bool ALIGN_EPI = false, bool SP2 = false>
; __device__ __forceinline__ void gemm_phase(LAS unsigned char* lds, const Gemm g, const Sched& S, const Epi& E, const int tid_) {
;     ...
;         if (!has_next) break;
; #pragma unroll
;         for (int a = 0; a < 2; ++a)
; #pragma unroll
;             for (int b = 0; b < 2; ++b)
; #pragma unroll
;                 for (int m = 0; m < 4; ++m)
; #pragma unroll
;                     for (int n = 0; n < 2; ++n) acc[a][b][m][n] = (f32x4){0.f, 0.f, 0.f, 0.f};
;         cur = nxt; cA = nA; cB = nB; ++ui;
;         if constexpr (ALIGN_EPI) { if (wr == 1) PG8_BAR; }
;     __device__ __forceinline__ void operator()(const f32x4 (&acc)[2][2][4][2], const pg8::Unit& u, int wr, int wc, int fr, int fq) const {
;     ...
;             for (int m = 0; m < 4; ++m) { const size_t r = (size_t)(row0 + ai * 128 + m * 16);
; #pragma unroll
;                 for (int bj = 0; bj < 2; ++bj) {
;                     float gf[8], pf[8], of[8]; unpack8(gwv[m][bj], gf); unpack8(pwv[m][bj], pf);
;                     const f32x4 v0 = acc[ai][bj][m][0], v1 = acc[ai][bj][m][1];
; #pragma unroll
;                     for (int j = 0; j < 4; ++j) { of[j] = gf[j] * v0[j] + pf[j]; of[4 + j] = gf[4 + j] * v1[j] + pf[4 + j]; }
;                     *(u32x4*)(mg + r * 2048 + col0 + bj * 128) = pack8(of); } }
	s_nop 0
	v_lshlrev_b32_e32 v42, 16, v82
	v_and_b32_e32 v43, 0xffff0000, v82
	v_pk_fma_f32 v[38:39], v[38:39], v[42:43], 0 op_sel_hi:[1,1,0]
	v_lshlrev_b32_e32 v42, 16, v84
	v_and_b32_e32 v43, 0xffff0000, v84
	v_pk_fma_f32 v[42:43], v[30:31], v[42:43], 0 op_sel_hi:[1,1,0]
	v_lshlrev_b32_e32 v30, 16, v83
	v_and_b32_e32 v31, 0xffff0000, v83
	v_pk_fma_f32 v[40:41], v[40:41], v[30:31], 0 op_sel_hi:[1,1,0]
	v_lshlrev_b32_e32 v30, 16, v85
	v_and_b32_e32 v31, 0xffff0000, v85
	v_pk_fma_f32 v[44:45], v[32:33], v[30:31], 0 op_sel_hi:[1,1,0]
	v_cvt_pk_bf16_f32 v30, v38, v39
	v_cvt_pk_bf16_f32 v31, v40, v41
	v_cvt_pk_bf16_f32 v32, v42, v43
	v_cvt_pk_bf16_f32 v33, v44, v45
	global_store_dwordx4 v[46:47], v[30:33], off offset:256
	s_waitcnt vmcnt(7)
	s_nop 0
	v_lshlrev_b32_e32 v32, 16, v88
	v_and_b32_e32 v33, 0xffff0000, v88
	v_lshlrev_b32_e32 v30, 16, v86
	v_and_b32_e32 v31, 0xffff0000, v86
	v_pk_fma_f32 v[32:33], v[26:27], v[32:33], 0 op_sel_hi:[1,1,0]
	v_lshlrev_b32_e32 v26, 16, v87
	v_and_b32_e32 v27, 0xffff0000, v87
	v_pk_fma_f32 v[30:31], v[34:35], v[30:31], 0 op_sel_hi:[1,1,0]
	v_pk_fma_f32 v[34:35], v[36:37], v[26:27], 0 op_sel_hi:[1,1,0]
	v_lshlrev_b32_e32 v26, 16, v89
	v_and_b32_e32 v27, 0xffff0000, v89
	v_pk_fma_f32 v[36:37], v[28:29], v[26:27], 0 op_sel_hi:[1,1,0]
	v_cvt_pk_bf16_f32 v26, v30, v31
	v_lshl_add_u64 v[30:31], s[42:43], 0, v[102:103]
	v_cvt_pk_bf16_f32 v27, v34, v35
	v_cvt_pk_bf16_f32 v28, v32, v33
	v_cvt_pk_bf16_f32 v29, v36, v37
	v_lshl_add_u64 v[30:31], v[30:31], 0, v[154:155]
	global_store_dwordx4 v[30:31], v[26:29], off
	s_waitcnt vmcnt(7)
	s_nop 0
	v_lshlrev_b32_e32 v26, 16, v90
	v_and_b32_e32 v27, 0xffff0000, v90
	v_pk_fma_f32 v[22:23], v[22:23], v[26:27], 0 op_sel_hi:[1,1,0]
	v_lshlrev_b32_e32 v26, 16, v92
	v_and_b32_e32 v27, 0xffff0000, v92
	v_pk_fma_f32 v[26:27], v[14:15], v[26:27], 0 op_sel_hi:[1,1,0]
	v_lshlrev_b32_e32 v14, 16, v91
	v_and_b32_e32 v15, 0xffff0000, v91
	v_pk_fma_f32 v[24:25], v[24:25], v[14:15], 0 op_sel_hi:[1,1,0]
	v_lshlrev_b32_e32 v14, 16, v93
	v_and_b32_e32 v15, 0xffff0000, v93
	v_pk_fma_f32 v[28:29], v[16:17], v[14:15], 0 op_sel_hi:[1,1,0]
	v_cvt_pk_bf16_f32 v14, v22, v23
	v_cvt_pk_bf16_f32 v15, v24, v25
	v_cvt_pk_bf16_f32 v16, v26, v27
	v_cvt_pk_bf16_f32 v17, v28, v29
	global_store_dwordx4 v[30:31], v[14:17], off offset:256
	s_waitcnt vmcnt(7)
	s_nop 0
	v_lshlrev_b32_e32 v16, 16, v96
	v_and_b32_e32 v17, 0xffff0000, v96
	v_lshlrev_b32_e32 v14, 16, v94
	v_and_b32_e32 v15, 0xffff0000, v94
	v_pk_fma_f32 v[16:17], v[10:11], v[16:17], 0 op_sel_hi:[1,1,0]
	v_lshlrev_b32_e32 v10, 16, v95
	v_and_b32_e32 v11, 0xffff0000, v95
	v_pk_fma_f32 v[14:15], v[18:19], v[14:15], 0 op_sel_hi:[1,1,0]
	v_pk_fma_f32 v[18:19], v[20:21], v[10:11], 0 op_sel_hi:[1,1,0]
	v_lshlrev_b32_e32 v10, 16, v97
	v_and_b32_e32 v11, 0xffff0000, v97
	v_pk_fma_f32 v[20:21], v[12:13], v[10:11], 0 op_sel_hi:[1,1,0]
	v_cvt_pk_bf16_f32 v10, v14, v15
	v_lshl_add_u64 v[14:15], s[42:43], 0, v[104:105]
	v_cvt_pk_bf16_f32 v11, v18, v19
	v_cvt_pk_bf16_f32 v12, v16, v17
	v_cvt_pk_bf16_f32 v13, v20, v21
	v_lshl_add_u64 v[14:15], v[14:15], 0, v[154:155]
	global_store_dwordx4 v[14:15], v[10:13], off
	s_waitcnt vmcnt(7)
	s_nop 0
	v_lshlrev_b32_e32 v10, 16, v66
	v_and_b32_e32 v11, 0xffff0000, v66
	v_pk_fma_f32 v[6:7], v[6:7], v[10:11], 0 op_sel_hi:[1,1,0]
	v_lshlrev_b32_e32 v10, 16, v68
	v_and_b32_e32 v11, 0xffff0000, v68
	v_pk_fma_f32 v[10:11], v[2:3], v[10:11], 0 op_sel_hi:[1,1,0]
	v_lshlrev_b32_e32 v2, 16, v67
	v_and_b32_e32 v3, 0xffff0000, v67
	v_pk_fma_f32 v[8:9], v[8:9], v[2:3], 0 op_sel_hi:[1,1,0]
	v_lshlrev_b32_e32 v2, 16, v69
	v_and_b32_e32 v3, 0xffff0000, v69
	v_pk_fma_f32 v[12:13], v[4:5], v[2:3], 0 op_sel_hi:[1,1,0]
	v_cvt_pk_bf16_f32 v2, v6, v7
	v_cvt_pk_bf16_f32 v3, v8, v9
	v_cvt_pk_bf16_f32 v4, v10, v11
	v_cvt_pk_bf16_f32 v5, v12, v13
	global_store_dwordx4 v[14:15], v[2:5], off offset:256
	s_cbranch_vccnz .LBB0_88
	s_andn2_b64 vcc, exec, s[10:11]
	s_cbranch_vccnz .LBB0_87
	s_nop 0
	s_branch .LBB0_87

; #define PG8_STAGE(bufoff, gbase, voff) do { _Pragma("unroll") for (int _i = 0; _i < 2; ++_i) \
;         __builtin_amdgcn_global_load_lds((const unsigned*)((const char*)(gbase) + (voff)[_i]), (LAS unsigned*)(lds + (bufoff) + ldsw + _i * 8192), 16, 0, 0); } while (0)
; #define PG8_LDA(dst, b, h) do { _Pragma("unroll") for (int m = 0; m < 4; ++m) _Pragma("unroll") for (int k = 0; k < 2; ++k) dst[m][k] = *(const LAS bf16x8*)(lds + PG8_SA(b, h) + aoff + m * 2048 + k * 1024); } while (0)
; #define PG8_LDB(dst, b, h) do { _Pragma("unroll") for (int n = 0; n < 2; ++n) _Pragma("unroll") for (int k = 0; k < 2; ++k) dst[n][k] = *(const LAS bf16x8*)(lds + PG8_SB(b, h) + boff + n * 2048 + k * 1024); } while (0)
; #define PG8_MMA(ai, bj, At, Bt) do { __builtin_amdgcn_s_setprio(1); _Pragma("unroll") for (int m = 0; m < 4; ++m) _Pragma("unroll") for (int n = 0; n < 2; ++n) _Pragma("unroll") for (int k = 0; k < 2; ++k) \
;         acc[ai][bj][m][n] = __builtin_amdgcn_mfma_f32_16x16x32_bf16(Bt[n][k], At[m][k], acc[ai][bj][m][n], 0, 0, 0); __builtin_amdgcn_s_setprio(0); } while (0)
; #define PG8_WAIT_V(n) asm volatile("s_waitcnt vmcnt(" #n ")" ::: "memory")
; #define PG8_BAR __builtin_amdgcn_s_barrier()
; template <class Epi, class Sched, bool ALIGN_EPI = false, bool SP2 = false>
; __device__ __forceinline__ void gemm_phase(LAS unsigned char* lds, const Gemm g, const Sched& S, const Epi& E, const int tid_) {
;     ...
;         for (int t = 0; t < nt; t += 2) {
;             const bool last = (t == nt - 2);
;             const char* a1 = cA + (size_t)(t + 1) * kstep;
;             const char* a2 = last ? nA : cA + (size_t)(t + 2) * kstep; const char* b2 = last ? nB : cB + (size_t)(t + 2) * kstep;
;             const char* a3 = a2 + kstep; const char* b3 = b2 + kstep;
;             if (last && has_next) S.a_ready(nxt);
;             if constexpr (SP2) {
;             PG8_LDB(B0, 0, 0); PG8_LDB(B1, 0, 1); PG8_SCHED; PG8_LDA(At, 0, 0); PG8_STAGE(PG8_SA(1, 1), a1 + hstep, voffA);
;             PG8_WAIT_V(8); PG8_WAIT_L(0); PG8_BAR; PG8_MMA(0, 0, At, B0); PG8_MMA(0, 1, At, B1); PG8_BAR; PG8_SCHED;
;             PG8_LDA(At, 0, 1); PG8_STAGE(PG8_SB(0, 0), b2, voffB); PG8_STAGE(PG8_SB(0, 1), b2 + hstep, voffB); PG8_STAGE(PG8_SA(0, 0), a2, voffA);
;             PG8_WAIT_V(8); PG8_WAIT_L(0); PG8_BAR; PG8_MMA(1, 0, At, B0); PG8_MMA(1, 1, At, B1); PG8_BAR; PG8_SCHED;
.LBB0_120:
	s_add_u32 s50, s48, 0xfffc0080
	s_addc_u32 s51, s49, -1
	s_add_i32 s70, 0, 0x10000
	s_cmp_eq_u32 s69, 12
	s_cselect_b32 s55, s17, s51
	s_cselect_b32 s54, s21, s50
	s_cselect_b32 s51, s15, s68
	s_cselect_b32 s50, s66, s67
	s_add_i32 s72, 0, 0x14000
	v_add_u32_e32 v142, s70, v199
	v_add_u32_e32 v158, s72, v199
	ds_read_b128 v[130:133], v142
	ds_read_b128 v[134:137], v142 offset:1024
	ds_read_b128 v[138:141], v142 offset:2048
	ds_read_b128 v[142:145], v142 offset:3072
	ds_read_b128 v[146:149], v158
	ds_read_b128 v[150:153], v158 offset:1024
	ds_read_b128 v[154:157], v158 offset:2048
	ds_read_b128 v[158:161], v158 offset:3072
	s_add_i32 m0, s47, 0xc000
	ds_read_b128 v[162:165], v237
	ds_read_b128 v[166:169], v237 offset:1024
	ds_read_b128 v[170:173], v237 offset:2048
	ds_read_b128 v[174:177], v237 offset:3072
	ds_read_b128 v[178:181], v237 offset:4096
	ds_read_b128 v[182:185], v237 offset:5120
	ds_read_b128 v[210:213], v237 offset:6144
	ds_read_b128 v[214:217], v237 offset:7168
	global_load_lds_dwordx4 v206, s[48:49]
	s_add_i32 m0, s47, 0xe000
	s_nop 0
	global_load_lds_dwordx4 v208, s[48:49]
	s_waitcnt vmcnt(8)
	s_waitcnt lgkmcnt(0)
	s_barrier
	s_setprio 1
	s_waitcnt lgkmcnt(0)
	v_mfma_f32_16x16x32_bf16 v[126:129], v[130:133], v[162:165], v[126:129]
	v_mfma_f32_16x16x32_bf16 v[122:125], v[138:141], v[162:165], v[122:125]
	v_mfma_f32_16x16x32_bf16 v[110:113], v[130:133], v[170:173], v[110:113]
	v_mfma_f32_16x16x32_bf16 v[106:109], v[138:141], v[170:173], v[106:109]
	v_mfma_f32_16x16x32_bf16 v[94:97], v[130:133], v[178:181], v[94:97]
	v_mfma_f32_16x16x32_bf16 v[90:93], v[138:141], v[178:181], v[90:93]
	v_mfma_f32_16x16x32_bf16 v[78:81], v[130:133], v[210:213], v[78:81]
	v_mfma_f32_16x16x32_bf16 v[74:77], v[138:141], v[210:213], v[74:77]
	v_mfma_f32_16x16x32_bf16 v[126:129], v[134:137], v[166:169], v[126:129]
	v_mfma_f32_16x16x32_bf16 v[122:125], v[142:145], v[166:169], v[122:125]
	v_mfma_f32_16x16x32_bf16 v[110:113], v[134:137], v[174:177], v[110:113]
	v_mfma_f32_16x16x32_bf16 v[106:109], v[142:145], v[174:177], v[106:109]
	v_mfma_f32_16x16x32_bf16 v[94:97], v[134:137], v[182:185], v[94:97]
	v_mfma_f32_16x16x32_bf16 v[90:93], v[142:145], v[182:185], v[90:93]
	v_mfma_f32_16x16x32_bf16 v[78:81], v[134:137], v[214:217], v[78:81]
	v_mfma_f32_16x16x32_bf16 v[74:77], v[142:145], v[214:217], v[74:77]
	s_setprio 0
	s_setprio 1
	v_mfma_f32_16x16x32_bf16 v[118:121], v[146:149], v[162:165], v[118:121]
	v_mfma_f32_16x16x32_bf16 v[114:117], v[154:157], v[162:165], v[114:117]
	v_mfma_f32_16x16x32_bf16 v[102:105], v[146:149], v[170:173], v[102:105]
	v_mfma_f32_16x16x32_bf16 v[98:101], v[154:157], v[170:173], v[98:101]
	v_mfma_f32_16x16x32_bf16 v[86:89], v[146:149], v[178:181], v[86:89]
	v_mfma_f32_16x16x32_bf16 v[82:85], v[154:157], v[178:181], v[82:85]
	v_mfma_f32_16x16x32_bf16 v[70:73], v[146:149], v[210:213], v[70:73]
	v_mfma_f32_16x16x32_bf16 v[66:69], v[154:157], v[210:213], v[66:69]
	v_mfma_f32_16x16x32_bf16 v[118:121], v[150:153], v[166:169], v[118:121]
	v_mfma_f32_16x16x32_bf16 v[114:117], v[158:161], v[166:169], v[114:117]
	v_mfma_f32_16x16x32_bf16 v[102:105], v[150:153], v[174:177], v[102:105]
	v_mfma_f32_16x16x32_bf16 v[98:101], v[158:161], v[174:177], v[98:101]
	v_mfma_f32_16x16x32_bf16 v[86:89], v[150:153], v[182:185], v[86:89]
	v_mfma_f32_16x16x32_bf16 v[82:85], v[158:161], v[182:185], v[82:85]
	v_mfma_f32_16x16x32_bf16 v[70:73], v[150:153], v[214:217], v[70:73]
	v_mfma_f32_16x16x32_bf16 v[66:69], v[158:161], v[214:217], v[66:69]
	s_setprio 0
	s_barrier
	s_add_i32 s70, s70, s58
	s_mov_b32 m0, s70
	ds_read_b128 v[162:165], v237 offset:16384
	ds_read_b128 v[166:169], v237 offset:17408
	ds_read_b128 v[170:173], v237 offset:18432
	ds_read_b128 v[174:177], v237 offset:19456
	ds_read_b128 v[178:181], v237 offset:20480
	ds_read_b128 v[182:185], v237 offset:21504
	ds_read_b128 v[210:213], v237 offset:22528
	ds_read_b128 v[214:217], v237 offset:23552
	global_load_lds_dwordx4 v0, s[50:51]
	s_add_i32 m0, s70, 0x2000
	s_add_u32 s70, s50, 0x40000
	v_lshl_add_u64 v[218:219], s[50:51], 0, v[204:205]
	s_addc_u32 s71, s51, 0
	s_add_i32 s72, s72, s58
	global_load_lds_dwordx4 v204, s[50:51]
	s_mov_b32 m0, s72
	v_lshl_add_u64 v[222:223], s[54:55], 0, v[202:203]
	global_load_lds_dwordx4 v0, s[70:71]
	s_add_i32 m0, s72, 0x2000
	s_nop 0
	global_load_lds_dwordx4 v204, s[70:71]
	v_lshl_add_u64 v[220:221], s[54:55], 0, v[200:201]
	s_mov_b32 m0, s47
	s_nop 0
	global_load_lds_dwordx4 v200, s[54:55]
	s_mov_b32 m0, s59
	s_nop 0
	global_load_lds_dwordx4 v202, s[54:55]
	s_waitcnt vmcnt(8)
	s_waitcnt lgkmcnt(0)
	s_barrier
; #define PG8_STAGE(bufoff, gbase, voff) do { _Pragma("unroll") for (int _i = 0; _i < 2; ++_i) \
;         __builtin_amdgcn_global_load_lds((const unsigned*)((const char*)(gbase) + (voff)[_i]), (LAS unsigned*)(lds + (bufoff) + ldsw + _i * 8192), 16, 0, 0); } while (0)
; #define PG8_LDA(dst, b, h) do { _Pragma("unroll") for (int m = 0; m < 4; ++m) _Pragma("unroll") for (int k = 0; k < 2; ++k) dst[m][k] = *(const LAS bf16x8*)(lds + PG8_SA(b, h) + aoff + m * 2048 + k * 1024); } while (0)
; #define PG8_LDB(dst, b, h) do { _Pragma("unroll") for (int n = 0; n < 2; ++n) _Pragma("unroll") for (int k = 0; k < 2; ++k) dst[n][k] = *(const LAS bf16x8*)(lds + PG8_SB(b, h) + boff + n * 2048 + k * 1024); } while (0)
; #define PG8_MMA(ai, bj, At, Bt) do { __builtin_amdgcn_s_setprio(1); _Pragma("unroll") for (int m = 0; m < 4; ++m) _Pragma("unroll") for (int n = 0; n < 2; ++n) _Pragma("unroll") for (int k = 0; k < 2; ++k) \
;         acc[ai][bj][m][n] = __builtin_amdgcn_mfma_f32_16x16x32_bf16(Bt[n][k], At[m][k], acc[ai][bj][m][n], 0, 0, 0); __builtin_amdgcn_s_setprio(0); } while (0)
; #define PG8_WAIT_V(n) asm volatile("s_waitcnt vmcnt(" #n ")" ::: "memory")
; #define PG8_WAIT_L(n) asm volatile("s_waitcnt lgkmcnt(" #n ")" ::: "memory")
; #define PG8_BAR __builtin_amdgcn_s_barrier()
; #define PG8_SCHED __builtin_amdgcn_sched_barrier(0)
; template <class Epi, class Sched, bool ALIGN_EPI = false, bool SP2 = false>
; __device__ __forceinline__ void gemm_phase(LAS unsigned char* lds, const Gemm g, const Sched& S, const Epi& E, const int tid_) {
;     ...
;             PG8_WAIT_V(8); PG8_WAIT_L(0); PG8_BAR; PG8_MMA(1, 0, At, B0); PG8_MMA(1, 1, At, B1); PG8_BAR; PG8_SCHED;
;             PG8_LDB(B0, 1, 0); PG8_LDB(B1, 1, 1); PG8_SCHED; PG8_LDA(At, 1, 0); PG8_STAGE(PG8_SA(0, 1), a2 + hstep, voffA);
;             PG8_WAIT_V(8); PG8_WAIT_L(0); PG8_BAR; PG8_MMA(0, 0, At, B0); PG8_MMA(0, 1, At, B1); PG8_BAR; PG8_SCHED;
;             PG8_LDA(At, 1, 1); PG8_STAGE(PG8_SB(1, 0), b3, voffB); PG8_STAGE(PG8_SB(1, 1), b3 + hstep, voffB); PG8_STAGE(PG8_SA(1, 0), a3, voffA);
;             PG8_WAIT_V(8); PG8_WAIT_L(0); PG8_BAR; PG8_MMA(1, 0, At, B0); PG8_MMA(1, 1, At, B1); PG8_BAR; PG8_SCHED;
	s_setprio 1
	s_waitcnt lgkmcnt(0)
	v_mfma_f32_16x16x32_bf16 v[62:65], v[130:133], v[162:165], v[62:65]
	v_mfma_f32_16x16x32_bf16 v[58:61], v[138:141], v[162:165], v[58:61]
	v_mfma_f32_16x16x32_bf16 v[46:49], v[130:133], v[170:173], v[46:49]
	v_mfma_f32_16x16x32_bf16 v[42:45], v[138:141], v[170:173], v[42:45]
	v_mfma_f32_16x16x32_bf16 v[30:33], v[130:133], v[178:181], v[30:33]
	v_mfma_f32_16x16x32_bf16 v[26:29], v[138:141], v[178:181], v[26:29]
	v_mfma_f32_16x16x32_bf16 v[14:17], v[130:133], v[210:213], v[14:17]
	v_mfma_f32_16x16x32_bf16 v[10:13], v[138:141], v[210:213], v[10:13]
	v_mfma_f32_16x16x32_bf16 v[62:65], v[134:137], v[166:169], v[62:65]
	v_mfma_f32_16x16x32_bf16 v[58:61], v[142:145], v[166:169], v[58:61]
	v_mfma_f32_16x16x32_bf16 v[46:49], v[134:137], v[174:177], v[46:49]
	v_mfma_f32_16x16x32_bf16 v[42:45], v[142:145], v[174:177], v[42:45]
	v_mfma_f32_16x16x32_bf16 v[30:33], v[134:137], v[182:185], v[30:33]
	v_mfma_f32_16x16x32_bf16 v[26:29], v[142:145], v[182:185], v[26:29]
	v_mfma_f32_16x16x32_bf16 v[14:17], v[134:137], v[214:217], v[14:17]
	v_mfma_f32_16x16x32_bf16 v[10:13], v[142:145], v[214:217], v[10:13]
	s_setprio 0
	s_setprio 1
	v_mfma_f32_16x16x32_bf16 v[54:57], v[146:149], v[162:165], v[54:57]
	v_mfma_f32_16x16x32_bf16 v[50:53], v[154:157], v[162:165], v[50:53]
	v_mfma_f32_16x16x32_bf16 v[38:41], v[146:149], v[170:173], v[38:41]
	v_mfma_f32_16x16x32_bf16 v[34:37], v[154:157], v[170:173], v[34:37]
	v_mfma_f32_16x16x32_bf16 v[22:25], v[146:149], v[178:181], v[22:25]
	v_mfma_f32_16x16x32_bf16 v[18:21], v[154:157], v[178:181], v[18:21]
	v_mfma_f32_16x16x32_bf16 v[6:9], v[146:149], v[210:213], v[6:9]
	v_mfma_f32_16x16x32_bf16 v[2:5], v[154:157], v[210:213], v[2:5]
	v_mfma_f32_16x16x32_bf16 v[54:57], v[150:153], v[166:169], v[54:57]
	v_mfma_f32_16x16x32_bf16 v[50:53], v[158:161], v[166:169], v[50:53]
	v_mfma_f32_16x16x32_bf16 v[38:41], v[150:153], v[174:177], v[38:41]
	v_mfma_f32_16x16x32_bf16 v[34:37], v[158:161], v[174:177], v[34:37]
	v_mfma_f32_16x16x32_bf16 v[22:25], v[150:153], v[182:185], v[22:25]
	v_mfma_f32_16x16x32_bf16 v[18:21], v[158:161], v[182:185], v[18:21]
	v_mfma_f32_16x16x32_bf16 v[6:9], v[150:153], v[214:217], v[6:9]
	v_mfma_f32_16x16x32_bf16 v[2:5], v[158:161], v[214:217], v[2:5]
	s_setprio 0
	s_barrier
	s_add_i32 s70, 0, 0x18000
	s_add_i32 s71, 0, 0x1c000
	v_add_u32_e32 v142, s70, v199
	v_add_u32_e32 v158, s71, v199
	ds_read_b128 v[130:133], v142
	ds_read_b128 v[134:137], v142 offset:1024
	ds_read_b128 v[138:141], v142 offset:2048
	ds_read_b128 v[142:145], v142 offset:3072
	ds_read_b128 v[146:149], v158
	ds_read_b128 v[150:153], v158 offset:1024
	ds_read_b128 v[154:157], v158 offset:2048
	ds_read_b128 v[158:161], v158 offset:3072
	s_add_u32 s54, s54, 0x40000
	s_addc_u32 s55, s55, 0
	s_mov_b32 m0, s60
	ds_read_b128 v[162:165], v237 offset:32768
	ds_read_b128 v[166:169], v237 offset:33792
	ds_read_b128 v[170:173], v237 offset:34816
	ds_read_b128 v[174:177], v237 offset:35840
	ds_read_b128 v[178:181], v237 offset:36864
	ds_read_b128 v[182:185], v237 offset:37888
	ds_read_b128 v[210:213], v237 offset:38912
	ds_read_b128 v[214:217], v237 offset:39936
	global_load_lds_dwordx4 v200, s[54:55]
	s_mov_b32 m0, s61
	s_nop 0
	global_load_lds_dwordx4 v202, s[54:55]
	s_waitcnt vmcnt(8)
	s_waitcnt lgkmcnt(0)
	s_barrier
	s_setprio 1
	s_waitcnt lgkmcnt(0)
	v_mfma_f32_16x16x32_bf16 v[126:129], v[130:133], v[162:165], v[126:129]
	v_mfma_f32_16x16x32_bf16 v[122:125], v[138:141], v[162:165], v[122:125]
	v_mfma_f32_16x16x32_bf16 v[110:113], v[130:133], v[170:173], v[110:113]
	v_mfma_f32_16x16x32_bf16 v[106:109], v[138:141], v[170:173], v[106:109]
	v_mfma_f32_16x16x32_bf16 v[94:97], v[130:133], v[178:181], v[94:97]
	v_mfma_f32_16x16x32_bf16 v[90:93], v[138:141], v[178:181], v[90:93]
	v_mfma_f32_16x16x32_bf16 v[78:81], v[130:133], v[210:213], v[78:81]
	v_mfma_f32_16x16x32_bf16 v[74:77], v[138:141], v[210:213], v[74:77]
	v_mfma_f32_16x16x32_bf16 v[126:129], v[134:137], v[166:169], v[126:129]
	v_mfma_f32_16x16x32_bf16 v[122:125], v[142:145], v[166:169], v[122:125]
	v_mfma_f32_16x16x32_bf16 v[110:113], v[134:137], v[174:177], v[110:113]
	v_mfma_f32_16x16x32_bf16 v[106:109], v[142:145], v[174:177], v[106:109]
	v_mfma_f32_16x16x32_bf16 v[94:97], v[134:137], v[182:185], v[94:97]
	v_mfma_f32_16x16x32_bf16 v[90:93], v[142:145], v[182:185], v[90:93]
	v_mfma_f32_16x16x32_bf16 v[78:81], v[134:137], v[214:217], v[78:81]
	v_mfma_f32_16x16x32_bf16 v[74:77], v[142:145], v[214:217], v[74:77]
	s_setprio 0
	s_setprio 1
	v_mfma_f32_16x16x32_bf16 v[118:121], v[146:149], v[162:165], v[118:121]
	v_mfma_f32_16x16x32_bf16 v[114:117], v[154:157], v[162:165], v[114:117]
	v_mfma_f32_16x16x32_bf16 v[102:105], v[146:149], v[170:173], v[102:105]
	v_mfma_f32_16x16x32_bf16 v[98:101], v[154:157], v[170:173], v[98:101]
	v_mfma_f32_16x16x32_bf16 v[86:89], v[146:149], v[178:181], v[86:89]
	v_mfma_f32_16x16x32_bf16 v[82:85], v[154:157], v[178:181], v[82:85]
	v_mfma_f32_16x16x32_bf16 v[70:73], v[146:149], v[210:213], v[70:73]
	v_mfma_f32_16x16x32_bf16 v[66:69], v[154:157], v[210:213], v[66:69]
	v_mfma_f32_16x16x32_bf16 v[118:121], v[150:153], v[166:169], v[118:121]
	v_mfma_f32_16x16x32_bf16 v[114:117], v[158:161], v[166:169], v[114:117]
	v_mfma_f32_16x16x32_bf16 v[102:105], v[150:153], v[174:177], v[102:105]
	v_mfma_f32_16x16x32_bf16 v[98:101], v[158:161], v[174:177], v[98:101]
	v_mfma_f32_16x16x32_bf16 v[86:89], v[150:153], v[182:185], v[86:89]
	v_mfma_f32_16x16x32_bf16 v[82:85], v[158:161], v[182:185], v[82:85]
	v_mfma_f32_16x16x32_bf16 v[70:73], v[150:153], v[214:217], v[70:73]
	v_mfma_f32_16x16x32_bf16 v[66:69], v[158:161], v[214:217], v[66:69]
	s_setprio 0
	s_barrier
; #define PG8_STAGE(bufoff, gbase, voff) do { _Pragma("unroll") for (int _i = 0; _i < 2; ++_i) \
;         __builtin_amdgcn_global_load_lds((const unsigned*)((const char*)(gbase) + (voff)[_i]), (LAS unsigned*)(lds + (bufoff) + ldsw + _i * 8192), 16, 0, 0); } while (0)
; #define PG8_LDA(dst, b, h) do { _Pragma("unroll") for (int m = 0; m < 4; ++m) _Pragma("unroll") for (int k = 0; k < 2; ++k) dst[m][k] = *(const LAS bf16x8*)(lds + PG8_SA(b, h) + aoff + m * 2048 + k * 1024); } while (0)
; #define PG8_MMA(ai, bj, At, Bt) do { __builtin_amdgcn_s_setprio(1); _Pragma("unroll") for (int m = 0; m < 4; ++m) _Pragma("unroll") for (int n = 0; n < 2; ++n) _Pragma("unroll") for (int k = 0; k < 2; ++k) \
;         acc[ai][bj][m][n] = __builtin_amdgcn_mfma_f32_16x16x32_bf16(Bt[n][k], At[m][k], acc[ai][bj][m][n], 0, 0, 0); __builtin_amdgcn_s_setprio(0); } while (0)
; #define PG8_WAIT_V(n) asm volatile("s_waitcnt vmcnt(" #n ")" ::: "memory")
; #define PG8_WAIT_L(n) asm volatile("s_waitcnt lgkmcnt(" #n ")" ::: "memory")
; #define PG8_BAR __builtin_amdgcn_s_barrier()
; template <class Epi, class Sched, bool ALIGN_EPI = false, bool SP2 = false>
; __device__ __forceinline__ void gemm_phase(LAS unsigned char* lds, const Gemm g, const Sched& S, const Epi& E, const int tid_) {
;     ...
;             PG8_LDA(At, 1, 1); PG8_STAGE(PG8_SB(1, 0), b3, voffB); PG8_STAGE(PG8_SB(1, 1), b3 + hstep, voffB); PG8_STAGE(PG8_SA(1, 0), a3, voffA);
;             PG8_WAIT_V(8); PG8_WAIT_L(0); PG8_BAR; PG8_MMA(1, 0, At, B0); PG8_MMA(1, 1, At, B1); PG8_BAR; PG8_SCHED;
;     ...
;         if constexpr (ALIGN_EPI) { if (wr == 0) PG8_BAR; }
;     __device__ __forceinline__ void operator()(const f32x4 (&acc)[2][2][4][2], const pg8::Unit& u, int wr, int wc, int fr, int fq) const {
;         const int row0 = u.pm * 256 + wr * 64 + fr, col0 = u.pn * 256 + wc * 32 + 8 * fq;
; #pragma unroll
;         for (int ai = 0; ai < 2; ++ai) {
;             u32x4 gwv[4][2], pwv[4][2];
; #pragma unroll
;             for (int m = 0; m < 4; ++m) { const size_t r = (size_t)(row0 + ai * 128 + m * 16);
; #pragma unroll
;                 for (int bj = 0; bj < 2; ++bj) { gwv[m][bj] = *(const u32x4*)(sg + r * 4096 + col0 + bj * 128);
;                     pwv[m][bj] = add ? *(const u32x4*)(mg + r * 2048 + col0 + bj * 128) : (u32x4){0u, 0u, 0u, 0u}; } }
;             asm volatile("" ::: "memory");
	s_add_i32 s54, s70, s58
	s_add_i32 m0, s54, 0xffffff80
	ds_read_b128 v[162:165], v237 offset:49152
	ds_read_b128 v[166:169], v237 offset:50176
	ds_read_b128 v[170:173], v237 offset:51200
	ds_read_b128 v[174:177], v237 offset:52224
	ds_read_b128 v[178:181], v237 offset:53248
	ds_read_b128 v[182:185], v237 offset:54272
	ds_read_b128 v[210:213], v237 offset:55296
	ds_read_b128 v[214:217], v237 offset:56320
	global_load_lds_dwordx4 v0, s[50:51] offset:128
	s_add_i32 m0, s54, 0x2000
	s_add_u32 s50, s50, 0x40080
	v_lshl_add_u64 v[192:193], v[218:219], 0, s[96:97]
	s_addc_u32 s51, s51, 0
	s_add_i32 s54, s71, s58
	global_load_lds_dwordx4 v[192:193], off
	s_mov_b32 m0, s54
	s_nop 0
	global_load_lds_dwordx4 v0, s[50:51]
	s_add_i32 m0, s54, 0x2000
	s_nop 0
	global_load_lds_dwordx4 v204, s[50:51]
	v_lshl_add_u64 v[192:193], v[220:221], 0, s[96:97]
	s_mov_b32 m0, s62
	s_nop 0
	global_load_lds_dwordx4 v[192:193], off
	v_lshl_add_u64 v[192:193], v[222:223], 0, s[96:97]
	s_mov_b32 m0, s63
	s_nop 0
	global_load_lds_dwordx4 v[192:193], off
	s_waitcnt vmcnt(8)
	s_waitcnt lgkmcnt(0)
	s_barrier
	s_setprio 1
	s_waitcnt lgkmcnt(0)
	v_mfma_f32_16x16x32_bf16 v[62:65], v[130:133], v[162:165], v[62:65]
	v_mfma_f32_16x16x32_bf16 v[58:61], v[138:141], v[162:165], v[58:61]
	v_mfma_f32_16x16x32_bf16 v[46:49], v[130:133], v[170:173], v[46:49]
	v_mfma_f32_16x16x32_bf16 v[42:45], v[138:141], v[170:173], v[42:45]
	v_mfma_f32_16x16x32_bf16 v[30:33], v[130:133], v[178:181], v[30:33]
	v_mfma_f32_16x16x32_bf16 v[26:29], v[138:141], v[178:181], v[26:29]
	v_mfma_f32_16x16x32_bf16 v[14:17], v[130:133], v[210:213], v[14:17]
	v_mfma_f32_16x16x32_bf16 v[10:13], v[138:141], v[210:213], v[10:13]
	v_mfma_f32_16x16x32_bf16 v[62:65], v[134:137], v[166:169], v[62:65]
	v_mfma_f32_16x16x32_bf16 v[58:61], v[142:145], v[166:169], v[58:61]
	v_mfma_f32_16x16x32_bf16 v[46:49], v[134:137], v[174:177], v[46:49]
	v_mfma_f32_16x16x32_bf16 v[42:45], v[142:145], v[174:177], v[42:45]
	v_mfma_f32_16x16x32_bf16 v[30:33], v[134:137], v[182:185], v[30:33]
	v_mfma_f32_16x16x32_bf16 v[26:29], v[142:145], v[182:185], v[26:29]
	v_mfma_f32_16x16x32_bf16 v[14:17], v[134:137], v[214:217], v[14:17]
	v_mfma_f32_16x16x32_bf16 v[10:13], v[142:145], v[214:217], v[10:13]
	s_setprio 0
	s_setprio 1
	v_mfma_f32_16x16x32_bf16 v[54:57], v[146:149], v[162:165], v[54:57]
	v_mfma_f32_16x16x32_bf16 v[50:53], v[154:157], v[162:165], v[50:53]
	v_mfma_f32_16x16x32_bf16 v[38:41], v[146:149], v[170:173], v[38:41]
	v_mfma_f32_16x16x32_bf16 v[34:37], v[154:157], v[170:173], v[34:37]
	v_mfma_f32_16x16x32_bf16 v[22:25], v[146:149], v[178:181], v[22:25]
	v_mfma_f32_16x16x32_bf16 v[18:21], v[154:157], v[178:181], v[18:21]
	v_mfma_f32_16x16x32_bf16 v[6:9], v[146:149], v[210:213], v[6:9]
	v_mfma_f32_16x16x32_bf16 v[2:5], v[154:157], v[210:213], v[2:5]
	v_mfma_f32_16x16x32_bf16 v[54:57], v[150:153], v[166:169], v[54:57]
	v_mfma_f32_16x16x32_bf16 v[50:53], v[158:161], v[166:169], v[50:53]
	v_mfma_f32_16x16x32_bf16 v[38:41], v[150:153], v[174:177], v[38:41]
	v_mfma_f32_16x16x32_bf16 v[34:37], v[158:161], v[174:177], v[34:37]
	v_mfma_f32_16x16x32_bf16 v[22:25], v[150:153], v[182:185], v[22:25]
	v_mfma_f32_16x16x32_bf16 v[18:21], v[158:161], v[182:185], v[18:21]
	v_mfma_f32_16x16x32_bf16 v[6:9], v[150:153], v[214:217], v[6:9]
	v_mfma_f32_16x16x32_bf16 v[2:5], v[158:161], v[214:217], v[2:5]
	s_setprio 0
	s_barrier
	s_add_i32 s69, s69, 2
	s_add_u32 s48, s48, 0x100
	s_addc_u32 s49, s49, 0
	s_add_u32 s67, s67, 0x100
	s_addc_u32 s68, s68, 0
	s_cmp_gt_u32 s69, 13
	s_cbranch_scc0 .LBB0_120
	s_andn2_b64 vcc, s[12:13], s[40:41]
	s_cbranch_vccz .LBB0_123
	s_barrier
.LBB0_123:
	v_lshl_or_b32 v130, s20, 8, v236
	v_lshl_add_u32 v214, s46, 8, v191
	v_ashrrev_i32_e32 v131, 31, v130
	v_lshlrev_b64 v[210:211], 1, v[130:131]
	v_ashrrev_i32_e32 v215, 31, v214
	v_lshl_add_u64 v[216:217], s[10:11], 0, v[210:211]
	v_lshlrev_b64 v[130:131], 13, v[214:215]
	v_lshl_add_u64 v[212:213], s[42:43], 0, v[210:211]
	v_lshl_add_u64 v[130:131], v[216:217], 0, v[130:131]
	v_lshlrev_b64 v[224:225], 12, v[214:215]
	v_lshl_add_u64 v[132:133], v[212:213], 0, v[224:225]
	global_load_dwordx4 v[242:245], v[130:131], off
	global_load_dwordx4 v[246:249], v[132:133], off
	global_load_dwordx4 v[182:185], v[130:131], off offset:256
	global_load_dwordx4 v[178:181], v[132:133], off offset:256
	v_or_b32_e32 v130, 16, v214
	v_ashrrev_i32_e32 v131, 31, v130
	v_lshlrev_b64 v[132:133], 13, v[130:131]
	v_lshl_add_u64 v[132:133], v[216:217], 0, v[132:133]
	v_lshlrev_b64 v[222:223], 12, v[130:131]
	v_lshl_add_u64 v[130:131], v[212:213], 0, v[222:223]
	global_load_dwordx4 v[170:173], v[132:133], off
	global_load_dwordx4 v[174:177], v[130:131], off
	global_load_dwordx4 v[166:169], v[132:133], off offset:256
	global_load_dwordx4 v[162:165], v[130:131], off offset:256
	v_or_b32_e32 v130, 32, v214
	v_ashrrev_i32_e32 v131, 31, v130
	v_lshlrev_b64 v[132:133], 13, v[130:131]
	v_lshl_add_u64 v[132:133], v[216:217], 0, v[132:133]
	v_lshlrev_b64 v[220:221], 12, v[130:131]
	v_lshl_add_u64 v[130:131], v[212:213], 0, v[220:221]
	global_load_dwordx4 v[158:161], v[132:133], off
	global_load_dwordx4 v[154:157], v[130:131], off
	global_load_dwordx4 v[142:145], v[132:133], off offset:256
	global_load_dwordx4 v[138:141], v[130:131], off offset:256
	v_or_b32_e32 v130, 48, v214
	v_ashrrev_i32_e32 v131, 31, v130
	v_lshlrev_b64 v[132:133], 13, v[130:131]
	v_lshlrev_b64 v[218:219], 12, v[130:131]
	v_lshl_add_u64 v[132:133], v[216:217], 0, v[132:133]
	v_lshl_add_u64 v[130:131], v[212:213], 0, v[218:219]
	global_load_dwordx4 v[150:153], v[132:133], off
	global_load_dwordx4 v[146:149], v[130:131], off
	global_load_dwordx4 v[134:137], v[132:133], off offset:256
	s_nop 0
	global_load_dwordx4 v[130:133], v[130:131], off offset:256
	s_mov_b64 s[20:21], -1
	s_andn2_b64 vcc, exec, s[40:41]
	s_waitcnt vmcnt(0)
; __device__ __forceinline__ void unpack8(const u32x4 w, float* f) { f[0] = bflo(w.x); f[1] = bfhi(w.x); f[2] = bflo(w.y); f[3] = bfhi(w.y); f[4] = bflo(w.z); f[5] = bfhi(w.z); f[6] = bflo(w.w); f[7] = bfhi(w.w); }
; __device__ __forceinline__ u32x4 pack8(const float* f) { u32x4 w; w.x = cvt_pk_bf16(f[0], f[1]); w.y = cvt_pk_bf16(f[2], f[3]); w.z = cvt_pk_bf16(f[4], f[5]); w.w = cvt_pk_bf16(f[6], f[7]); return w; }
;     __device__ __forceinline__ void operator()(const f32x4 (&acc)[2][2][4][2], const pg8::Unit& u, int wr, int wc, int fr, int fq) const {
;     ...
;             for (int m = 0; m < 4; ++m) { const size_t r = (size_t)(row0 + ai * 128 + m * 16);
; #pragma unroll
;                 for (int bj = 0; bj < 2; ++bj) {
;                     float gf[8], pf[8], of[8]; unpack8(gwv[m][bj], gf); unpack8(pwv[m][bj], pf);
;                     const f32x4 v0 = acc[ai][bj][m][0], v1 = acc[ai][bj][m][1];
; #pragma unroll
;                     for (int j = 0; j < 4; ++j) { of[j] = gf[j] * v0[j] + pf[j]; of[4 + j] = gf[4 + j] * v1[j] + pf[4 + j]; }
;                     *(u32x4*)(mg + r * 2048 + col0 + bj * 128) = pack8(of); } }
	v_lshlrev_b32_e32 v192, 16, v242
	v_and_b32_e32 v193, 0xffff0000, v242
	v_lshlrev_b32_e32 v250, 16, v246
	v_and_b32_e32 v251, 0xffff0000, v246
	v_pk_fma_f32 v[126:127], v[126:127], v[192:193], v[250:251]
	v_lshlrev_b32_e32 v192, 16, v244
	v_and_b32_e32 v193, 0xffff0000, v244
	v_lshlrev_b32_e32 v250, 16, v248
	v_and_b32_e32 v251, 0xffff0000, v248
	v_pk_fma_f32 v[192:193], v[122:123], v[192:193], v[250:251]
	v_lshlrev_b32_e32 v122, 16, v243
	v_and_b32_e32 v123, 0xffff0000, v243
	v_lshlrev_b32_e32 v242, 16, v247
	v_and_b32_e32 v243, 0xffff0000, v247
	v_pk_fma_f32 v[128:129], v[128:129], v[122:123], v[242:243]
	v_lshlrev_b32_e32 v122, 16, v245
	v_and_b32_e32 v123, 0xffff0000, v245
	v_lshlrev_b32_e32 v242, 16, v249
	v_and_b32_e32 v243, 0xffff0000, v249
	v_pk_fma_f32 v[242:243], v[124:125], v[122:123], v[242:243]
	v_cvt_pk_bf16_f32 v122, v126, v127
	v_lshl_add_u64 v[126:127], s[42:43], 0, v[224:225]
	v_cvt_pk_bf16_f32 v123, v128, v129
	v_cvt_pk_bf16_f32 v124, v192, v193
	v_cvt_pk_bf16_f32 v125, v242, v243
	v_lshl_add_u64 v[126:127], v[126:127], 0, v[210:211]
	global_store_dwordx4 v[126:127], v[122:125], off
	s_nop 1
	v_lshlrev_b32_e32 v122, 16, v182
	v_and_b32_e32 v123, 0xffff0000, v182
	v_lshlrev_b32_e32 v124, 16, v178
	v_and_b32_e32 v125, 0xffff0000, v178
	v_pk_fma_f32 v[118:119], v[118:119], v[122:123], v[124:125]
	v_lshlrev_b32_e32 v122, 16, v184
	v_and_b32_e32 v123, 0xffff0000, v184
	v_lshlrev_b32_e32 v124, 16, v180
	v_and_b32_e32 v125, 0xffff0000, v180
	v_pk_fma_f32 v[122:123], v[114:115], v[122:123], v[124:125]
	v_lshlrev_b32_e32 v114, 16, v183
	v_and_b32_e32 v115, 0xffff0000, v183
	v_lshlrev_b32_e32 v124, 16, v179
	v_and_b32_e32 v125, 0xffff0000, v179
	v_pk_fma_f32 v[120:121], v[120:121], v[114:115], v[124:125]
	v_lshlrev_b32_e32 v114, 16, v185
	v_and_b32_e32 v115, 0xffff0000, v185
	v_lshlrev_b32_e32 v124, 16, v181
	v_and_b32_e32 v125, 0xffff0000, v181
	v_pk_fma_f32 v[124:125], v[116:117], v[114:115], v[124:125]
	v_cvt_pk_bf16_f32 v114, v118, v119
	v_cvt_pk_bf16_f32 v115, v120, v121
	v_cvt_pk_bf16_f32 v116, v122, v123
	v_cvt_pk_bf16_f32 v117, v124, v125
	global_store_dwordx4 v[126:127], v[114:117], off offset:256
	s_nop 1
	v_lshlrev_b32_e32 v114, 16, v170
	v_and_b32_e32 v115, 0xffff0000, v170
	v_lshlrev_b32_e32 v116, 16, v174
	v_and_b32_e32 v117, 0xffff0000, v174
	v_pk_fma_f32 v[110:111], v[110:111], v[114:115], v[116:117]
	v_lshlrev_b32_e32 v114, 16, v172
	v_and_b32_e32 v115, 0xffff0000, v172
	v_lshlrev_b32_e32 v116, 16, v176
	v_and_b32_e32 v117, 0xffff0000, v176
	v_pk_fma_f32 v[114:115], v[106:107], v[114:115], v[116:117]
	v_lshlrev_b32_e32 v106, 16, v171
	v_and_b32_e32 v107, 0xffff0000, v171
	v_lshlrev_b32_e32 v116, 16, v175
	v_and_b32_e32 v117, 0xffff0000, v175
	v_pk_fma_f32 v[112:113], v[112:113], v[106:107], v[116:117]
	v_lshlrev_b32_e32 v106, 16, v173
	v_and_b32_e32 v107, 0xffff0000, v173
	v_lshlrev_b32_e32 v116, 16, v177
	v_and_b32_e32 v117, 0xffff0000, v177
	v_pk_fma_f32 v[116:117], v[108:109], v[106:107], v[116:117]
	v_cvt_pk_bf16_f32 v106, v110, v111
	v_lshl_add_u64 v[110:111], s[42:43], 0, v[222:223]
	v_cvt_pk_bf16_f32 v107, v112, v113
	v_cvt_pk_bf16_f32 v108, v114, v115
	v_cvt_pk_bf16_f32 v109, v116, v117
	v_lshl_add_u64 v[110:111], v[110:111], 0, v[210:211]
	global_store_dwordx4 v[110:111], v[106:109], off
	s_nop 1
	v_lshlrev_b32_e32 v106, 16, v166
	v_and_b32_e32 v107, 0xffff0000, v166
	v_lshlrev_b32_e32 v108, 16, v162
	v_and_b32_e32 v109, 0xffff0000, v162
	v_pk_fma_f32 v[102:103], v[102:103], v[106:107], v[108:109]
	v_lshlrev_b32_e32 v106, 16, v168
	v_and_b32_e32 v107, 0xffff0000, v168
	v_lshlrev_b32_e32 v108, 16, v164
	v_and_b32_e32 v109, 0xffff0000, v164
	v_pk_fma_f32 v[106:107], v[98:99], v[106:107], v[108:109]
	v_lshlrev_b32_e32 v98, 16, v167
	v_and_b32_e32 v99, 0xffff0000, v167
	v_lshlrev_b32_e32 v108, 16, v163
	v_and_b32_e32 v109, 0xffff0000, v163
	v_pk_fma_f32 v[104:105], v[104:105], v[98:99], v[108:109]
	v_lshlrev_b32_e32 v98, 16, v169
	v_and_b32_e32 v99, 0xffff0000, v169
	v_lshlrev_b32_e32 v108, 16, v165
	v_and_b32_e32 v109, 0xffff0000, v165
	v_pk_fma_f32 v[108:109], v[100:101], v[98:99], v[108:109]
	v_cvt_pk_bf16_f32 v98, v102, v103
	v_cvt_pk_bf16_f32 v99, v104, v105
	v_cvt_pk_bf16_f32 v100, v106, v107
	v_cvt_pk_bf16_f32 v101, v108, v109
	global_store_dwordx4 v[110:111], v[98:101], off offset:256
	s_nop 1
	v_lshlrev_b32_e32 v98, 16, v158
	v_and_b32_e32 v99, 0xffff0000, v158
	v_lshlrev_b32_e32 v100, 16, v154
	v_and_b32_e32 v101, 0xffff0000, v154
	v_pk_fma_f32 v[94:95], v[94:95], v[98:99], v[100:101]
	v_lshlrev_b32_e32 v98, 16, v160
	v_and_b32_e32 v99, 0xffff0000, v160
	v_lshlrev_b32_e32 v100, 16, v156
	v_and_b32_e32 v101, 0xffff0000, v156
	v_pk_fma_f32 v[98:99], v[90:91], v[98:99], v[100:101]
	v_lshlrev_b32_e32 v90, 16, v159
	v_and_b32_e32 v91, 0xffff0000, v159
	v_lshlrev_b32_e32 v100, 16, v155
	v_and_b32_e32 v101, 0xffff0000, v155
	v_pk_fma_f32 v[96:97], v[96:97], v[90:91], v[100:101]
	v_lshlrev_b32_e32 v90, 16, v161
	v_and_b32_e32 v91, 0xffff0000, v161
	v_lshlrev_b32_e32 v100, 16, v157
	v_and_b32_e32 v101, 0xffff0000, v157
	v_pk_fma_f32 v[100:101], v[92:93], v[90:91], v[100:101]
	v_cvt_pk_bf16_f32 v90, v94, v95
	v_lshl_add_u64 v[94:95], s[42:43], 0, v[220:221]
	v_cvt_pk_bf16_f32 v91, v96, v97
	v_cvt_pk_bf16_f32 v92, v98, v99
	v_cvt_pk_bf16_f32 v93, v100, v101
	v_lshl_add_u64 v[94:95], v[94:95], 0, v[210:211]
	global_store_dwordx4 v[94:95], v[90:93], off
	s_nop 1
	v_lshlrev_b32_e32 v90, 16, v142
	v_and_b32_e32 v91, 0xffff0000, v142
	v_lshlrev_b32_e32 v92, 16, v138
	v_and_b32_e32 v93, 0xffff0000, v138
	v_pk_fma_f32 v[86:87], v[86:87], v[90:91], v[92:93]
	v_lshlrev_b32_e32 v90, 16, v144
	v_and_b32_e32 v91, 0xffff0000, v144
; __device__ __forceinline__ void unpack8(const u32x4 w, float* f) { f[0] = bflo(w.x); f[1] = bfhi(w.x); f[2] = bflo(w.y); f[3] = bfhi(w.y); f[4] = bflo(w.z); f[5] = bfhi(w.z); f[6] = bflo(w.w); f[7] = bfhi(w.w); }
; __device__ __forceinline__ u32x4 pack8(const float* f) { u32x4 w; w.x = cvt_pk_bf16(f[0], f[1]); w.y = cvt_pk_bf16(f[2], f[3]); w.z = cvt_pk_bf16(f[4], f[5]); w.w = cvt_pk_bf16(f[6], f[7]); return w; }
;     __device__ __forceinline__ void operator()(const f32x4 (&acc)[2][2][4][2], const pg8::Unit& u, int wr, int wc, int fr, int fq) const {
;     ...
;         for (int ai = 0; ai < 2; ++ai) {
;             u32x4 gwv[4][2], pwv[4][2];
; #pragma unroll
;             for (int m = 0; m < 4; ++m) { const size_t r = (size_t)(row0 + ai * 128 + m * 16);
; #pragma unroll
;                 for (int bj = 0; bj < 2; ++bj) { gwv[m][bj] = *(const u32x4*)(sg + r * 4096 + col0 + bj * 128);
;                     pwv[m][bj] = add ? *(const u32x4*)(mg + r * 2048 + col0 + bj * 128) : (u32x4){0u, 0u, 0u, 0u}; } }
;             asm volatile("" ::: "memory");
; #pragma unroll
;             for (int m = 0; m < 4; ++m) { const size_t r = (size_t)(row0 + ai * 128 + m * 16);
; #pragma unroll
;                 for (int bj = 0; bj < 2; ++bj) {
;                     float gf[8], pf[8], of[8]; unpack8(gwv[m][bj], gf); unpack8(pwv[m][bj], pf);
;                     const f32x4 v0 = acc[ai][bj][m][0], v1 = acc[ai][bj][m][1];
; #pragma unroll
;                     for (int j = 0; j < 4; ++j) { of[j] = gf[j] * v0[j] + pf[j]; of[4 + j] = gf[4 + j] * v1[j] + pf[4 + j]; }
;                     *(u32x4*)(mg + r * 2048 + col0 + bj * 128) = pack8(of); } }
	v_lshlrev_b32_e32 v92, 16, v140
	v_and_b32_e32 v93, 0xffff0000, v140
	v_pk_fma_f32 v[90:91], v[82:83], v[90:91], v[92:93]
	v_lshlrev_b32_e32 v82, 16, v143
	v_and_b32_e32 v83, 0xffff0000, v143
	v_lshlrev_b32_e32 v92, 16, v139
	v_and_b32_e32 v93, 0xffff0000, v139
	v_pk_fma_f32 v[88:89], v[88:89], v[82:83], v[92:93]
	v_lshlrev_b32_e32 v82, 16, v145
	v_and_b32_e32 v83, 0xffff0000, v145
	v_lshlrev_b32_e32 v92, 16, v141
	v_and_b32_e32 v93, 0xffff0000, v141
	v_pk_fma_f32 v[92:93], v[84:85], v[82:83], v[92:93]
	v_cvt_pk_bf16_f32 v82, v86, v87
	v_cvt_pk_bf16_f32 v83, v88, v89
	v_cvt_pk_bf16_f32 v84, v90, v91
	v_cvt_pk_bf16_f32 v85, v92, v93
	global_store_dwordx4 v[94:95], v[82:85], off offset:256
	s_nop 1
	v_lshlrev_b32_e32 v82, 16, v150
	v_and_b32_e32 v83, 0xffff0000, v150
	v_lshlrev_b32_e32 v84, 16, v146
	v_and_b32_e32 v85, 0xffff0000, v146
	v_pk_fma_f32 v[78:79], v[78:79], v[82:83], v[84:85]
	v_lshlrev_b32_e32 v82, 16, v152
	v_and_b32_e32 v83, 0xffff0000, v152
	v_lshlrev_b32_e32 v84, 16, v148
	v_and_b32_e32 v85, 0xffff0000, v148
	v_pk_fma_f32 v[82:83], v[74:75], v[82:83], v[84:85]
	v_lshlrev_b32_e32 v74, 16, v151
	v_and_b32_e32 v75, 0xffff0000, v151
	v_lshlrev_b32_e32 v84, 16, v147
	v_and_b32_e32 v85, 0xffff0000, v147
	v_pk_fma_f32 v[80:81], v[80:81], v[74:75], v[84:85]
	v_lshlrev_b32_e32 v74, 16, v153
	v_and_b32_e32 v75, 0xffff0000, v153
	v_lshlrev_b32_e32 v84, 16, v149
	v_and_b32_e32 v85, 0xffff0000, v149
	v_pk_fma_f32 v[84:85], v[76:77], v[74:75], v[84:85]
	v_cvt_pk_bf16_f32 v74, v78, v79
	v_lshl_add_u64 v[78:79], s[42:43], 0, v[218:219]
	v_cvt_pk_bf16_f32 v75, v80, v81
	v_cvt_pk_bf16_f32 v76, v82, v83
	v_cvt_pk_bf16_f32 v77, v84, v85
	v_lshl_add_u64 v[78:79], v[78:79], 0, v[210:211]
	global_store_dwordx4 v[78:79], v[74:77], off
	s_nop 1
	v_lshlrev_b32_e32 v74, 16, v134
	v_and_b32_e32 v75, 0xffff0000, v134
	v_lshlrev_b32_e32 v76, 16, v130
	v_and_b32_e32 v77, 0xffff0000, v130
	v_pk_fma_f32 v[70:71], v[70:71], v[74:75], v[76:77]
	v_lshlrev_b32_e32 v74, 16, v136
	v_and_b32_e32 v75, 0xffff0000, v136
	v_lshlrev_b32_e32 v76, 16, v132
	v_and_b32_e32 v77, 0xffff0000, v132
	v_pk_fma_f32 v[74:75], v[66:67], v[74:75], v[76:77]
	v_lshlrev_b32_e32 v66, 16, v135
	v_and_b32_e32 v67, 0xffff0000, v135
	v_lshlrev_b32_e32 v76, 16, v131
	v_and_b32_e32 v77, 0xffff0000, v131
	v_pk_fma_f32 v[72:73], v[72:73], v[66:67], v[76:77]
	v_lshlrev_b32_e32 v66, 16, v137
	v_and_b32_e32 v67, 0xffff0000, v137
	v_lshlrev_b32_e32 v76, 16, v133
	v_and_b32_e32 v77, 0xffff0000, v133
	v_pk_fma_f32 v[76:77], v[68:69], v[66:67], v[76:77]
	v_cvt_pk_bf16_f32 v66, v70, v71
	v_cvt_pk_bf16_f32 v67, v72, v73
	v_cvt_pk_bf16_f32 v68, v74, v75
	v_cvt_pk_bf16_f32 v69, v76, v77
	global_store_dwordx4 v[78:79], v[66:69], off offset:256
	s_nop 1
	v_add_u32_e32 v66, 0x80, v214
	v_ashrrev_i32_e32 v67, 31, v66
	v_lshlrev_b64 v[68:69], 13, v[66:67]
	v_lshl_add_u64 v[68:69], v[216:217], 0, v[68:69]
	v_lshlrev_b64 v[134:135], 12, v[66:67]
	v_lshl_add_u64 v[66:67], v[212:213], 0, v[134:135]
	global_load_dwordx4 v[102:105], v[68:69], off
	global_load_dwordx4 v[106:109], v[66:67], off
	global_load_dwordx4 v[110:113], v[68:69], off offset:256
	global_load_dwordx4 v[114:117], v[66:67], off offset:256
	v_add_u32_e32 v66, 0x90, v214
	v_ashrrev_i32_e32 v67, 31, v66
	v_lshlrev_b64 v[68:69], 13, v[66:67]
	v_lshl_add_u64 v[68:69], v[216:217], 0, v[68:69]
	v_lshlrev_b64 v[136:137], 12, v[66:67]
	v_lshl_add_u64 v[66:67], v[212:213], 0, v[136:137]
	global_load_dwordx4 v[118:121], v[68:69], off
	global_load_dwordx4 v[122:125], v[66:67], off
	global_load_dwordx4 v[126:129], v[68:69], off offset:256
	global_load_dwordx4 v[130:133], v[66:67], off offset:256
	v_add_u32_e32 v66, 0xa0, v214
	v_ashrrev_i32_e32 v67, 31, v66
	v_lshlrev_b64 v[68:69], 13, v[66:67]
	v_lshl_add_u64 v[68:69], v[216:217], 0, v[68:69]
	v_lshlrev_b64 v[100:101], 12, v[66:67]
	v_lshl_add_u64 v[66:67], v[212:213], 0, v[100:101]
	global_load_dwordx4 v[94:97], v[68:69], off
	global_load_dwordx4 v[90:93], v[66:67], off
	global_load_dwordx4 v[82:85], v[68:69], off offset:256
	global_load_dwordx4 v[86:89], v[66:67], off offset:256
	v_add_u32_e32 v66, 0xb0, v214
	v_ashrrev_i32_e32 v67, 31, v66
	v_lshlrev_b64 v[68:69], 13, v[66:67]
	v_lshlrev_b64 v[98:99], 12, v[66:67]
	v_lshl_add_u64 v[68:69], v[216:217], 0, v[68:69]
	v_lshl_add_u64 v[70:71], v[212:213], 0, v[98:99]
	global_load_dwordx4 v[78:81], v[68:69], off
	global_load_dwordx4 v[74:77], v[70:71], off
	s_nop 0
	global_load_dwordx4 v[66:69], v[68:69], off offset:256
	s_nop 0
	global_load_dwordx4 v[70:73], v[70:71], off offset:256
	s_waitcnt vmcnt(15)
	v_lshlrev_b32_e32 v138, 16, v102
	v_and_b32_e32 v139, 0xffff0000, v102
	s_waitcnt vmcnt(14)
	v_lshlrev_b32_e32 v140, 16, v106
	v_and_b32_e32 v141, 0xffff0000, v106
	v_pk_fma_f32 v[62:63], v[62:63], v[138:139], v[140:141]
	v_lshlrev_b32_e32 v138, 16, v104
	v_and_b32_e32 v139, 0xffff0000, v104
	v_lshlrev_b32_e32 v140, 16, v108
	v_and_b32_e32 v141, 0xffff0000, v108
	v_pk_fma_f32 v[138:139], v[58:59], v[138:139], v[140:141]
	v_lshlrev_b32_e32 v58, 16, v103
	v_and_b32_e32 v59, 0xffff0000, v103
	v_lshlrev_b32_e32 v102, 16, v107
	v_and_b32_e32 v103, 0xffff0000, v107
	v_pk_fma_f32 v[64:65], v[64:65], v[58:59], v[102:103]
	v_lshlrev_b32_e32 v58, 16, v105
	v_and_b32_e32 v59, 0xffff0000, v105
	v_lshlrev_b32_e32 v102, 16, v109
	v_and_b32_e32 v103, 0xffff0000, v109
	v_pk_fma_f32 v[102:103], v[60:61], v[58:59], v[102:103]
	v_cvt_pk_bf16_f32 v58, v62, v63
	v_lshl_add_u64 v[62:63], s[42:43], 0, v[134:135]
	v_cvt_pk_bf16_f32 v59, v64, v65
	v_cvt_pk_bf16_f32 v60, v138, v139
	v_cvt_pk_bf16_f32 v61, v102, v103
	v_lshl_add_u64 v[62:63], v[62:63], 0, v[210:211]
	global_store_dwordx4 v[62:63], v[58:61], off
	s_waitcnt vmcnt(14)
; __device__ __forceinline__ void unpack8(const u32x4 w, float* f) { f[0] = bflo(w.x); f[1] = bfhi(w.x); f[2] = bflo(w.y); f[3] = bfhi(w.y); f[4] = bflo(w.z); f[5] = bfhi(w.z); f[6] = bflo(w.w); f[7] = bfhi(w.w); }
; __device__ __forceinline__ u32x4 pack8(const float* f) { u32x4 w; w.x = cvt_pk_bf16(f[0], f[1]); w.y = cvt_pk_bf16(f[2], f[3]); w.z = cvt_pk_bf16(f[4], f[5]); w.w = cvt_pk_bf16(f[6], f[7]); return w; }
;     __device__ __forceinline__ void operator()(const f32x4 (&acc)[2][2][4][2], const pg8::Unit& u, int wr, int wc, int fr, int fq) const {
;     ...
;             for (int m = 0; m < 4; ++m) { const size_t r = (size_t)(row0 + ai * 128 + m * 16);
; #pragma unroll
;                 for (int bj = 0; bj < 2; ++bj) {
;                     float gf[8], pf[8], of[8]; unpack8(gwv[m][bj], gf); unpack8(pwv[m][bj], pf);
;                     const f32x4 v0 = acc[ai][bj][m][0], v1 = acc[ai][bj][m][1];
; #pragma unroll
;                     for (int j = 0; j < 4; ++j) { of[j] = gf[j] * v0[j] + pf[j]; of[4 + j] = gf[4 + j] * v1[j] + pf[4 + j]; }
;                     *(u32x4*)(mg + r * 2048 + col0 + bj * 128) = pack8(of); } }
	s_nop 0
	v_lshlrev_b32_e32 v58, 16, v110
	v_and_b32_e32 v59, 0xffff0000, v110
	s_waitcnt vmcnt(13)
	v_lshlrev_b32_e32 v60, 16, v114
	v_and_b32_e32 v61, 0xffff0000, v114
	v_pk_fma_f32 v[54:55], v[54:55], v[58:59], v[60:61]
	v_lshlrev_b32_e32 v58, 16, v112
	v_and_b32_e32 v59, 0xffff0000, v112
	v_lshlrev_b32_e32 v60, 16, v116
	v_and_b32_e32 v61, 0xffff0000, v116
	v_pk_fma_f32 v[58:59], v[50:51], v[58:59], v[60:61]
	v_lshlrev_b32_e32 v50, 16, v111
	v_and_b32_e32 v51, 0xffff0000, v111
	v_lshlrev_b32_e32 v60, 16, v115
	v_and_b32_e32 v61, 0xffff0000, v115
	v_pk_fma_f32 v[56:57], v[56:57], v[50:51], v[60:61]
	v_lshlrev_b32_e32 v50, 16, v113
	v_and_b32_e32 v51, 0xffff0000, v113
	v_lshlrev_b32_e32 v60, 16, v117
	v_and_b32_e32 v61, 0xffff0000, v117
	v_pk_fma_f32 v[60:61], v[52:53], v[50:51], v[60:61]
	v_cvt_pk_bf16_f32 v50, v54, v55
	v_cvt_pk_bf16_f32 v51, v56, v57
	v_cvt_pk_bf16_f32 v52, v58, v59
	v_cvt_pk_bf16_f32 v53, v60, v61
	global_store_dwordx4 v[62:63], v[50:53], off offset:256
	s_waitcnt vmcnt(13)
	s_nop 0
	v_lshlrev_b32_e32 v50, 16, v118
	v_and_b32_e32 v51, 0xffff0000, v118
	s_waitcnt vmcnt(12)
	v_lshlrev_b32_e32 v52, 16, v122
	v_and_b32_e32 v53, 0xffff0000, v122
	v_pk_fma_f32 v[46:47], v[46:47], v[50:51], v[52:53]
	v_lshlrev_b32_e32 v50, 16, v120
	v_and_b32_e32 v51, 0xffff0000, v120
	v_lshlrev_b32_e32 v52, 16, v124
	v_and_b32_e32 v53, 0xffff0000, v124
	v_pk_fma_f32 v[50:51], v[42:43], v[50:51], v[52:53]
	v_lshlrev_b32_e32 v42, 16, v119
	v_and_b32_e32 v43, 0xffff0000, v119
	v_lshlrev_b32_e32 v52, 16, v123
	v_and_b32_e32 v53, 0xffff0000, v123
	v_pk_fma_f32 v[48:49], v[48:49], v[42:43], v[52:53]
	v_lshlrev_b32_e32 v42, 16, v121
	v_and_b32_e32 v43, 0xffff0000, v121
	v_lshlrev_b32_e32 v52, 16, v125
	v_and_b32_e32 v53, 0xffff0000, v125
	v_pk_fma_f32 v[52:53], v[44:45], v[42:43], v[52:53]
	v_cvt_pk_bf16_f32 v42, v46, v47
	v_lshl_add_u64 v[46:47], s[42:43], 0, v[136:137]
	v_cvt_pk_bf16_f32 v43, v48, v49
	v_cvt_pk_bf16_f32 v44, v50, v51
	v_cvt_pk_bf16_f32 v45, v52, v53
	v_lshl_add_u64 v[46:47], v[46:47], 0, v[210:211]
	global_store_dwordx4 v[46:47], v[42:45], off
	s_waitcnt vmcnt(12)
	s_nop 0
	v_lshlrev_b32_e32 v42, 16, v126
	v_and_b32_e32 v43, 0xffff0000, v126
	s_waitcnt vmcnt(11)
	v_lshlrev_b32_e32 v44, 16, v130
	v_and_b32_e32 v45, 0xffff0000, v130
	v_pk_fma_f32 v[38:39], v[38:39], v[42:43], v[44:45]
	v_lshlrev_b32_e32 v42, 16, v128
	v_and_b32_e32 v43, 0xffff0000, v128
	v_lshlrev_b32_e32 v44, 16, v132
	v_and_b32_e32 v45, 0xffff0000, v132
	v_pk_fma_f32 v[42:43], v[34:35], v[42:43], v[44:45]
	v_lshlrev_b32_e32 v34, 16, v127
	v_and_b32_e32 v35, 0xffff0000, v127
	v_lshlrev_b32_e32 v44, 16, v131
	v_and_b32_e32 v45, 0xffff0000, v131
	v_pk_fma_f32 v[40:41], v[40:41], v[34:35], v[44:45]
	v_lshlrev_b32_e32 v34, 16, v129
	v_and_b32_e32 v35, 0xffff0000, v129
	v_lshlrev_b32_e32 v44, 16, v133
	v_and_b32_e32 v45, 0xffff0000, v133
	v_pk_fma_f32 v[44:45], v[36:37], v[34:35], v[44:45]
	v_cvt_pk_bf16_f32 v34, v38, v39
	v_cvt_pk_bf16_f32 v35, v40, v41
	v_cvt_pk_bf16_f32 v36, v42, v43
	v_cvt_pk_bf16_f32 v37, v44, v45
	global_store_dwordx4 v[46:47], v[34:37], off offset:256
	s_waitcnt vmcnt(11)
	s_nop 0
	v_lshlrev_b32_e32 v34, 16, v94
	v_and_b32_e32 v35, 0xffff0000, v94
	s_waitcnt vmcnt(10)
; __device__ __forceinline__ void unpack8(const u32x4 w, float* f) { f[0] = bflo(w.x); f[1] = bfhi(w.x); f[2] = bflo(w.y); f[3] = bfhi(w.y); f[4] = bflo(w.z); f[5] = bfhi(w.z); f[6] = bflo(w.w); f[7] = bfhi(w.w); }
; __device__ __forceinline__ u32x4 pack8(const float* f) { u32x4 w; w.x = cvt_pk_bf16(f[0], f[1]); w.y = cvt_pk_bf16(f[2], f[3]); w.z = cvt_pk_bf16(f[4], f[5]); w.w = cvt_pk_bf16(f[6], f[7]); return w; }
; #define PG8_BAR __builtin_amdgcn_s_barrier()
; template <class Epi, class Sched, bool ALIGN_EPI = false, bool SP2 = false>
; __device__ __forceinline__ void gemm_phase(LAS unsigned char* lds, const Gemm g, const Sched& S, const Epi& E, const int tid_) {
;     ...
;         if (!has_next) break;
; #pragma unroll
;         for (int a = 0; a < 2; ++a)
; #pragma unroll
;             for (int b = 0; b < 2; ++b)
; #pragma unroll
;                 for (int m = 0; m < 4; ++m)
; #pragma unroll
;                     for (int n = 0; n < 2; ++n) acc[a][b][m][n] = (f32x4){0.f, 0.f, 0.f, 0.f};
;         cur = nxt; cA = nA; cB = nB; ++ui;
;         if constexpr (ALIGN_EPI) { if (wr == 1) PG8_BAR; }
;     __device__ __forceinline__ void operator()(const f32x4 (&acc)[2][2][4][2], const pg8::Unit& u, int wr, int wc, int fr, int fq) const {
;     ...
;             for (int m = 0; m < 4; ++m) { const size_t r = (size_t)(row0 + ai * 128 + m * 16);
; #pragma unroll
;                 for (int bj = 0; bj < 2; ++bj) {
;                     float gf[8], pf[8], of[8]; unpack8(gwv[m][bj], gf); unpack8(pwv[m][bj], pf);
;                     const f32x4 v0 = acc[ai][bj][m][0], v1 = acc[ai][bj][m][1];
; #pragma unroll
;                     for (int j = 0; j < 4; ++j) { of[j] = gf[j] * v0[j] + pf[j]; of[4 + j] = gf[4 + j] * v1[j] + pf[4 + j]; }
;                     *(u32x4*)(mg + r * 2048 + col0 + bj * 128) = pack8(of); } }
	v_lshlrev_b32_e32 v36, 16, v90
	v_and_b32_e32 v37, 0xffff0000, v90
	v_pk_fma_f32 v[30:31], v[30:31], v[34:35], v[36:37]
	v_lshlrev_b32_e32 v34, 16, v96
	v_and_b32_e32 v35, 0xffff0000, v96
	v_lshlrev_b32_e32 v36, 16, v92
	v_and_b32_e32 v37, 0xffff0000, v92
	v_pk_fma_f32 v[34:35], v[26:27], v[34:35], v[36:37]
	v_lshlrev_b32_e32 v26, 16, v95
	v_and_b32_e32 v27, 0xffff0000, v95
	v_lshlrev_b32_e32 v36, 16, v91
	v_and_b32_e32 v37, 0xffff0000, v91
	v_pk_fma_f32 v[32:33], v[32:33], v[26:27], v[36:37]
	v_lshlrev_b32_e32 v26, 16, v97
	v_and_b32_e32 v27, 0xffff0000, v97
	v_lshlrev_b32_e32 v36, 16, v93
	v_and_b32_e32 v37, 0xffff0000, v93
	v_pk_fma_f32 v[36:37], v[28:29], v[26:27], v[36:37]
	v_cvt_pk_bf16_f32 v26, v30, v31
	v_lshl_add_u64 v[30:31], s[42:43], 0, v[100:101]
	v_cvt_pk_bf16_f32 v27, v32, v33
	v_cvt_pk_bf16_f32 v28, v34, v35
	v_cvt_pk_bf16_f32 v29, v36, v37
	v_lshl_add_u64 v[30:31], v[30:31], 0, v[210:211]
	global_store_dwordx4 v[30:31], v[26:29], off
	s_waitcnt vmcnt(10)
	s_nop 0
	v_lshlrev_b32_e32 v26, 16, v82
	v_and_b32_e32 v27, 0xffff0000, v82
	s_waitcnt vmcnt(9)
	v_lshlrev_b32_e32 v28, 16, v86
	v_and_b32_e32 v29, 0xffff0000, v86
	v_pk_fma_f32 v[22:23], v[22:23], v[26:27], v[28:29]
	v_lshlrev_b32_e32 v26, 16, v84
	v_and_b32_e32 v27, 0xffff0000, v84
	v_lshlrev_b32_e32 v28, 16, v88
	v_and_b32_e32 v29, 0xffff0000, v88
	v_pk_fma_f32 v[26:27], v[18:19], v[26:27], v[28:29]
	v_lshlrev_b32_e32 v18, 16, v83
	v_and_b32_e32 v19, 0xffff0000, v83
	v_lshlrev_b32_e32 v28, 16, v87
	v_and_b32_e32 v29, 0xffff0000, v87
	v_pk_fma_f32 v[24:25], v[24:25], v[18:19], v[28:29]
	v_lshlrev_b32_e32 v18, 16, v85
	v_and_b32_e32 v19, 0xffff0000, v85
	v_lshlrev_b32_e32 v28, 16, v89
	v_and_b32_e32 v29, 0xffff0000, v89
	v_pk_fma_f32 v[28:29], v[20:21], v[18:19], v[28:29]
	v_cvt_pk_bf16_f32 v18, v22, v23
	v_cvt_pk_bf16_f32 v19, v24, v25
	v_cvt_pk_bf16_f32 v20, v26, v27
	v_cvt_pk_bf16_f32 v21, v28, v29
	global_store_dwordx4 v[30:31], v[18:21], off offset:256
	s_waitcnt vmcnt(9)
	s_nop 0
	v_lshlrev_b32_e32 v18, 16, v78
	v_and_b32_e32 v19, 0xffff0000, v78
	s_waitcnt vmcnt(8)
	v_lshlrev_b32_e32 v20, 16, v74
	v_and_b32_e32 v21, 0xffff0000, v74
	v_pk_fma_f32 v[14:15], v[14:15], v[18:19], v[20:21]
	v_lshlrev_b32_e32 v18, 16, v80
	v_and_b32_e32 v19, 0xffff0000, v80
	v_lshlrev_b32_e32 v20, 16, v76
	v_and_b32_e32 v21, 0xffff0000, v76
	v_pk_fma_f32 v[18:19], v[10:11], v[18:19], v[20:21]
	v_lshlrev_b32_e32 v10, 16, v79
	v_and_b32_e32 v11, 0xffff0000, v79
	v_lshlrev_b32_e32 v20, 16, v75
	v_and_b32_e32 v21, 0xffff0000, v75
	v_pk_fma_f32 v[16:17], v[16:17], v[10:11], v[20:21]
	v_lshlrev_b32_e32 v10, 16, v81
	v_and_b32_e32 v11, 0xffff0000, v81
	v_lshlrev_b32_e32 v20, 16, v77
	v_and_b32_e32 v21, 0xffff0000, v77
	v_pk_fma_f32 v[20:21], v[12:13], v[10:11], v[20:21]
	v_cvt_pk_bf16_f32 v10, v14, v15
	v_lshl_add_u64 v[14:15], s[42:43], 0, v[98:99]
	v_cvt_pk_bf16_f32 v11, v16, v17
	v_cvt_pk_bf16_f32 v12, v18, v19
	v_cvt_pk_bf16_f32 v13, v20, v21
	v_lshl_add_u64 v[14:15], v[14:15], 0, v[210:211]
	global_store_dwordx4 v[14:15], v[10:13], off
	s_waitcnt vmcnt(8)
	s_nop 0
	v_lshlrev_b32_e32 v10, 16, v66
	v_and_b32_e32 v11, 0xffff0000, v66
	s_waitcnt vmcnt(7)
	v_lshlrev_b32_e32 v12, 16, v70
	v_and_b32_e32 v13, 0xffff0000, v70
	v_pk_fma_f32 v[6:7], v[6:7], v[10:11], v[12:13]
	v_lshlrev_b32_e32 v10, 16, v68
	v_and_b32_e32 v11, 0xffff0000, v68
	v_lshlrev_b32_e32 v12, 16, v72
	v_and_b32_e32 v13, 0xffff0000, v72
	v_pk_fma_f32 v[10:11], v[2:3], v[10:11], v[12:13]
	v_lshlrev_b32_e32 v2, 16, v67
	v_and_b32_e32 v3, 0xffff0000, v67
	v_lshlrev_b32_e32 v12, 16, v71
	v_and_b32_e32 v13, 0xffff0000, v71
	v_pk_fma_f32 v[8:9], v[8:9], v[2:3], v[12:13]
	v_lshlrev_b32_e32 v2, 16, v69
	v_and_b32_e32 v3, 0xffff0000, v69
	v_lshlrev_b32_e32 v12, 16, v73
	v_and_b32_e32 v13, 0xffff0000, v73
	v_pk_fma_f32 v[12:13], v[4:5], v[2:3], v[12:13]
	v_cvt_pk_bf16_f32 v2, v6, v7
	v_cvt_pk_bf16_f32 v3, v8, v9
	v_cvt_pk_bf16_f32 v4, v10, v11
	v_cvt_pk_bf16_f32 v5, v12, v13
	global_store_dwordx4 v[14:15], v[2:5], off offset:256
	s_cbranch_vccnz .LBB0_112
	s_andn2_b64 vcc, exec, s[8:9]
	s_cbranch_vccnz .LBB0_111
	s_nop 0
	s_branch .LBB0_111

; #define PG8_STAGE(bufoff, gbase, voff) do { _Pragma("unroll") for (int _i = 0; _i < 2; ++_i) \
;         __builtin_amdgcn_global_load_lds((const unsigned*)((const char*)(gbase) + (voff)[_i]), (LAS unsigned*)(lds + (bufoff) + ldsw + _i * 8192), 16, 0, 0); } while (0)
; #define PG8_LDA(dst, b, h) do { _Pragma("unroll") for (int m = 0; m < 4; ++m) _Pragma("unroll") for (int k = 0; k < 2; ++k) dst[m][k] = *(const LAS bf16x8*)(lds + PG8_SA(b, h) + aoff + m * 2048 + k * 1024); } while (0)
; #define PG8_LDB(dst, b, h) do { _Pragma("unroll") for (int n = 0; n < 2; ++n) _Pragma("unroll") for (int k = 0; k < 2; ++k) dst[n][k] = *(const LAS bf16x8*)(lds + PG8_SB(b, h) + boff + n * 2048 + k * 1024); } while (0)
; #define PG8_MMA(ai, bj, At, Bt) do { __builtin_amdgcn_s_setprio(1); _Pragma("unroll") for (int m = 0; m < 4; ++m) _Pragma("unroll") for (int n = 0; n < 2; ++n) _Pragma("unroll") for (int k = 0; k < 2; ++k) \
;         acc[ai][bj][m][n] = __builtin_amdgcn_mfma_f32_16x16x32_bf16(Bt[n][k], At[m][k], acc[ai][bj][m][n], 0, 0, 0); __builtin_amdgcn_s_setprio(0); } while (0)
; #define PG8_WAIT_V(n) asm volatile("s_waitcnt vmcnt(" #n ")" ::: "memory")
; #define PG8_BAR __builtin_amdgcn_s_barrier()
; template <class Epi, class Sched, bool ALIGN_EPI = false, bool SP2 = false>
; __device__ __forceinline__ void gemm_phase(LAS unsigned char* lds, const Gemm g, const Sched& S, const Epi& E, const int tid_) {
;     ...
;         for (int t = 0; t < nt; t += 2) {
;             const bool last = (t == nt - 2);
;             const char* a1 = cA + (size_t)(t + 1) * kstep;
;             const char* a2 = last ? nA : cA + (size_t)(t + 2) * kstep; const char* b2 = last ? nB : cB + (size_t)(t + 2) * kstep;
;             const char* a3 = a2 + kstep; const char* b3 = b2 + kstep;
;             if (last && has_next) S.a_ready(nxt);
;             if constexpr (SP2) {
;             PG8_LDB(B0, 0, 0); PG8_LDB(B1, 0, 1); PG8_SCHED; PG8_LDA(At, 0, 0); PG8_STAGE(PG8_SA(1, 1), a1 + hstep, voffA);
;             PG8_WAIT_V(8); PG8_WAIT_L(0); PG8_BAR; PG8_MMA(0, 0, At, B0); PG8_MMA(0, 1, At, B1); PG8_BAR; PG8_SCHED;
;             PG8_LDA(At, 0, 1); PG8_STAGE(PG8_SB(0, 0), b2, voffB); PG8_STAGE(PG8_SB(0, 1), b2 + hstep, voffB); PG8_STAGE(PG8_SA(0, 0), a2, voffA);
;             PG8_WAIT_V(8); PG8_WAIT_L(0); PG8_BAR; PG8_MMA(1, 0, At, B0); PG8_MMA(1, 1, At, B1); PG8_BAR; PG8_SCHED;
.LBB0_253:
	s_add_u32 s58, s54, 0xfff80080
	s_addc_u32 s59, s55, -1
	s_add_i32 s74, 0, 0x10000
	s_cmp_eq_u32 s73, 28
	s_cselect_b32 s61, s20, s59
	s_cselect_b32 s60, s21, s58
	s_cselect_b32 s59, s43, s72
	s_cselect_b32 s58, s47, s49
	s_add_i32 s76, 0, 0x14000
	v_add_u32_e32 v156, s74, v145
	v_add_u32_e32 v172, s76, v145
	ds_read_b128 v[140:143], v156
	ds_read_b128 v[148:151], v156 offset:1024
	ds_read_b128 v[152:155], v156 offset:2048
	ds_read_b128 v[156:159], v156 offset:3072
	ds_read_b128 v[160:163], v172
	ds_read_b128 v[164:167], v172 offset:1024
	ds_read_b128 v[168:171], v172 offset:2048
	ds_read_b128 v[172:175], v172 offset:3072
	s_add_i32 m0, s57, 0xc000
	ds_read_b128 v[176:179], v147
	ds_read_b128 v[180:183], v147 offset:1024
	ds_read_b128 v[200:203], v147 offset:2048
	ds_read_b128 v[204:207], v147 offset:3072
	ds_read_b128 v[208:211], v147 offset:4096
	ds_read_b128 v[212:215], v147 offset:5120
	ds_read_b128 v[216:219], v147 offset:6144
	ds_read_b128 v[220:223], v147 offset:7168
	global_load_lds_dwordx4 v136, s[54:55]
	s_add_i32 m0, s57, 0xe000
	s_nop 0
	global_load_lds_dwordx4 v138, s[54:55]
	s_waitcnt vmcnt(8)
	s_waitcnt lgkmcnt(0)
	s_barrier
	s_setprio 1
	s_waitcnt lgkmcnt(0)
	v_mfma_f32_16x16x32_bf16 v[126:129], v[140:143], v[176:179], v[126:129]
	v_mfma_f32_16x16x32_bf16 v[122:125], v[152:155], v[176:179], v[122:125]
	v_mfma_f32_16x16x32_bf16 v[110:113], v[140:143], v[200:203], v[110:113]
	v_mfma_f32_16x16x32_bf16 v[106:109], v[152:155], v[200:203], v[106:109]
	v_mfma_f32_16x16x32_bf16 v[94:97], v[140:143], v[208:211], v[94:97]
	v_mfma_f32_16x16x32_bf16 v[90:93], v[152:155], v[208:211], v[90:93]
	v_mfma_f32_16x16x32_bf16 v[78:81], v[140:143], v[216:219], v[78:81]
	v_mfma_f32_16x16x32_bf16 v[74:77], v[152:155], v[216:219], v[74:77]
	v_mfma_f32_16x16x32_bf16 v[126:129], v[148:151], v[180:183], v[126:129]
	v_mfma_f32_16x16x32_bf16 v[122:125], v[156:159], v[180:183], v[122:125]
	v_mfma_f32_16x16x32_bf16 v[110:113], v[148:151], v[204:207], v[110:113]
	v_mfma_f32_16x16x32_bf16 v[106:109], v[156:159], v[204:207], v[106:109]
	v_mfma_f32_16x16x32_bf16 v[94:97], v[148:151], v[212:215], v[94:97]
	v_mfma_f32_16x16x32_bf16 v[90:93], v[156:159], v[212:215], v[90:93]
	v_mfma_f32_16x16x32_bf16 v[78:81], v[148:151], v[220:223], v[78:81]
	v_mfma_f32_16x16x32_bf16 v[74:77], v[156:159], v[220:223], v[74:77]
	s_setprio 0
	s_setprio 1
	v_mfma_f32_16x16x32_bf16 v[118:121], v[160:163], v[176:179], v[118:121]
	v_mfma_f32_16x16x32_bf16 v[114:117], v[168:171], v[176:179], v[114:117]
	v_mfma_f32_16x16x32_bf16 v[102:105], v[160:163], v[200:203], v[102:105]
	v_mfma_f32_16x16x32_bf16 v[98:101], v[168:171], v[200:203], v[98:101]
	v_mfma_f32_16x16x32_bf16 v[86:89], v[160:163], v[208:211], v[86:89]
	v_mfma_f32_16x16x32_bf16 v[82:85], v[168:171], v[208:211], v[82:85]
	v_mfma_f32_16x16x32_bf16 v[70:73], v[160:163], v[216:219], v[70:73]
	v_mfma_f32_16x16x32_bf16 v[66:69], v[168:171], v[216:219], v[66:69]
	v_mfma_f32_16x16x32_bf16 v[118:121], v[164:167], v[180:183], v[118:121]
	v_mfma_f32_16x16x32_bf16 v[114:117], v[172:175], v[180:183], v[114:117]
	v_mfma_f32_16x16x32_bf16 v[102:105], v[164:167], v[204:207], v[102:105]
	v_mfma_f32_16x16x32_bf16 v[98:101], v[172:175], v[204:207], v[98:101]
	v_mfma_f32_16x16x32_bf16 v[86:89], v[164:167], v[212:215], v[86:89]
	v_mfma_f32_16x16x32_bf16 v[82:85], v[172:175], v[212:215], v[82:85]
	v_mfma_f32_16x16x32_bf16 v[70:73], v[164:167], v[220:223], v[70:73]
	v_mfma_f32_16x16x32_bf16 v[66:69], v[172:175], v[220:223], v[66:69]
	s_setprio 0
	s_barrier
	s_add_i32 s74, s74, s62
	s_mov_b32 m0, s74
	ds_read_b128 v[176:179], v147 offset:16384
	ds_read_b128 v[180:183], v147 offset:17408
	ds_read_b128 v[200:203], v147 offset:18432
	ds_read_b128 v[204:207], v147 offset:19456
	ds_read_b128 v[208:211], v147 offset:20480
	ds_read_b128 v[212:215], v147 offset:21504
	ds_read_b128 v[216:219], v147 offset:22528
	ds_read_b128 v[220:223], v147 offset:23552
	global_load_lds_dwordx4 v0, s[58:59]
	s_add_i32 m0, s74, 0x2000
	s_add_u32 s74, s58, 0x80000
	v_lshl_add_u64 v[224:225], s[58:59], 0, v[134:135]
	s_addc_u32 s75, s59, 0
	s_add_i32 s76, s76, s62
	global_load_lds_dwordx4 v134, s[58:59]
	s_mov_b32 m0, s76
	v_lshl_add_u64 v[242:243], s[60:61], 0, v[132:133]
	global_load_lds_dwordx4 v0, s[74:75]
	s_add_i32 m0, s76, 0x2000
	s_nop 0
	global_load_lds_dwordx4 v134, s[74:75]
	v_lshl_add_u64 v[236:237], s[60:61], 0, v[130:131]
	s_mov_b32 m0, s57
	s_nop 0
	global_load_lds_dwordx4 v130, s[60:61]
	s_mov_b32 m0, s63
	s_nop 0
	global_load_lds_dwordx4 v132, s[60:61]
	s_waitcnt vmcnt(8)
	s_waitcnt lgkmcnt(0)
	s_barrier
; #define PG8_STAGE(bufoff, gbase, voff) do { _Pragma("unroll") for (int _i = 0; _i < 2; ++_i) \
;         __builtin_amdgcn_global_load_lds((const unsigned*)((const char*)(gbase) + (voff)[_i]), (LAS unsigned*)(lds + (bufoff) + ldsw + _i * 8192), 16, 0, 0); } while (0)
; #define PG8_LDA(dst, b, h) do { _Pragma("unroll") for (int m = 0; m < 4; ++m) _Pragma("unroll") for (int k = 0; k < 2; ++k) dst[m][k] = *(const LAS bf16x8*)(lds + PG8_SA(b, h) + aoff + m * 2048 + k * 1024); } while (0)
; #define PG8_LDB(dst, b, h) do { _Pragma("unroll") for (int n = 0; n < 2; ++n) _Pragma("unroll") for (int k = 0; k < 2; ++k) dst[n][k] = *(const LAS bf16x8*)(lds + PG8_SB(b, h) + boff + n * 2048 + k * 1024); } while (0)
; #define PG8_MMA(ai, bj, At, Bt) do { __builtin_amdgcn_s_setprio(1); _Pragma("unroll") for (int m = 0; m < 4; ++m) _Pragma("unroll") for (int n = 0; n < 2; ++n) _Pragma("unroll") for (int k = 0; k < 2; ++k) \
;         acc[ai][bj][m][n] = __builtin_amdgcn_mfma_f32_16x16x32_bf16(Bt[n][k], At[m][k], acc[ai][bj][m][n], 0, 0, 0); __builtin_amdgcn_s_setprio(0); } while (0)
; #define PG8_WAIT_V(n) asm volatile("s_waitcnt vmcnt(" #n ")" ::: "memory")
; #define PG8_WAIT_L(n) asm volatile("s_waitcnt lgkmcnt(" #n ")" ::: "memory")
; #define PG8_BAR __builtin_amdgcn_s_barrier()
; #define PG8_SCHED __builtin_amdgcn_sched_barrier(0)
; template <class Epi, class Sched, bool ALIGN_EPI = false, bool SP2 = false>
; __device__ __forceinline__ void gemm_phase(LAS unsigned char* lds, const Gemm g, const Sched& S, const Epi& E, const int tid_) {
;     ...
;             PG8_WAIT_V(8); PG8_WAIT_L(0); PG8_BAR; PG8_MMA(1, 0, At, B0); PG8_MMA(1, 1, At, B1); PG8_BAR; PG8_SCHED;
;             PG8_LDB(B0, 1, 0); PG8_LDB(B1, 1, 1); PG8_SCHED; PG8_LDA(At, 1, 0); PG8_STAGE(PG8_SA(0, 1), a2 + hstep, voffA);
;             PG8_WAIT_V(8); PG8_WAIT_L(0); PG8_BAR; PG8_MMA(0, 0, At, B0); PG8_MMA(0, 1, At, B1); PG8_BAR; PG8_SCHED;
;             PG8_LDA(At, 1, 1); PG8_STAGE(PG8_SB(1, 0), b3, voffB); PG8_STAGE(PG8_SB(1, 1), b3 + hstep, voffB); PG8_STAGE(PG8_SA(1, 0), a3, voffA);
;             PG8_WAIT_V(8); PG8_WAIT_L(0); PG8_BAR; PG8_MMA(1, 0, At, B0); PG8_MMA(1, 1, At, B1); PG8_BAR; PG8_SCHED;
	s_setprio 1
	s_waitcnt lgkmcnt(0)
	v_mfma_f32_16x16x32_bf16 v[62:65], v[140:143], v[176:179], v[62:65]
	v_mfma_f32_16x16x32_bf16 v[58:61], v[152:155], v[176:179], v[58:61]
	v_mfma_f32_16x16x32_bf16 v[46:49], v[140:143], v[200:203], v[46:49]
	v_mfma_f32_16x16x32_bf16 v[42:45], v[152:155], v[200:203], v[42:45]
	v_mfma_f32_16x16x32_bf16 v[30:33], v[140:143], v[208:211], v[30:33]
	v_mfma_f32_16x16x32_bf16 v[26:29], v[152:155], v[208:211], v[26:29]
	v_mfma_f32_16x16x32_bf16 v[14:17], v[140:143], v[216:219], v[14:17]
	v_mfma_f32_16x16x32_bf16 v[10:13], v[152:155], v[216:219], v[10:13]
	v_mfma_f32_16x16x32_bf16 v[62:65], v[148:151], v[180:183], v[62:65]
	v_mfma_f32_16x16x32_bf16 v[58:61], v[156:159], v[180:183], v[58:61]
	v_mfma_f32_16x16x32_bf16 v[46:49], v[148:151], v[204:207], v[46:49]
	v_mfma_f32_16x16x32_bf16 v[42:45], v[156:159], v[204:207], v[42:45]
	v_mfma_f32_16x16x32_bf16 v[30:33], v[148:151], v[212:215], v[30:33]
	v_mfma_f32_16x16x32_bf16 v[26:29], v[156:159], v[212:215], v[26:29]
	v_mfma_f32_16x16x32_bf16 v[14:17], v[148:151], v[220:223], v[14:17]
	v_mfma_f32_16x16x32_bf16 v[10:13], v[156:159], v[220:223], v[10:13]
	s_setprio 0
	s_setprio 1
	v_mfma_f32_16x16x32_bf16 v[54:57], v[160:163], v[176:179], v[54:57]
	v_mfma_f32_16x16x32_bf16 v[50:53], v[168:171], v[176:179], v[50:53]
	v_mfma_f32_16x16x32_bf16 v[38:41], v[160:163], v[200:203], v[38:41]
	v_mfma_f32_16x16x32_bf16 v[34:37], v[168:171], v[200:203], v[34:37]
	v_mfma_f32_16x16x32_bf16 v[22:25], v[160:163], v[208:211], v[22:25]
	v_mfma_f32_16x16x32_bf16 v[18:21], v[168:171], v[208:211], v[18:21]
	v_mfma_f32_16x16x32_bf16 v[6:9], v[160:163], v[216:219], v[6:9]
	v_mfma_f32_16x16x32_bf16 v[2:5], v[168:171], v[216:219], v[2:5]
	v_mfma_f32_16x16x32_bf16 v[54:57], v[164:167], v[180:183], v[54:57]
	v_mfma_f32_16x16x32_bf16 v[50:53], v[172:175], v[180:183], v[50:53]
	v_mfma_f32_16x16x32_bf16 v[38:41], v[164:167], v[204:207], v[38:41]
	v_mfma_f32_16x16x32_bf16 v[34:37], v[172:175], v[204:207], v[34:37]
	v_mfma_f32_16x16x32_bf16 v[22:25], v[164:167], v[212:215], v[22:25]
	v_mfma_f32_16x16x32_bf16 v[18:21], v[172:175], v[212:215], v[18:21]
	v_mfma_f32_16x16x32_bf16 v[6:9], v[164:167], v[220:223], v[6:9]
	v_mfma_f32_16x16x32_bf16 v[2:5], v[172:175], v[220:223], v[2:5]
	s_setprio 0
	s_barrier
	s_add_i32 s74, 0, 0x18000
	s_add_i32 s75, 0, 0x1c000
	v_add_u32_e32 v156, s74, v145
	v_add_u32_e32 v172, s75, v145
	ds_read_b128 v[140:143], v156
	ds_read_b128 v[148:151], v156 offset:1024
	ds_read_b128 v[152:155], v156 offset:2048
	ds_read_b128 v[156:159], v156 offset:3072
	ds_read_b128 v[160:163], v172
	ds_read_b128 v[164:167], v172 offset:1024
	ds_read_b128 v[168:171], v172 offset:2048
	ds_read_b128 v[172:175], v172 offset:3072
	s_add_u32 s60, s60, 0x80000
	s_addc_u32 s61, s61, 0
	s_mov_b32 m0, s64
	ds_read_b128 v[176:179], v147 offset:32768
	ds_read_b128 v[180:183], v147 offset:33792
	ds_read_b128 v[200:203], v147 offset:34816
	ds_read_b128 v[204:207], v147 offset:35840
	ds_read_b128 v[208:211], v147 offset:36864
	ds_read_b128 v[212:215], v147 offset:37888
	ds_read_b128 v[216:219], v147 offset:38912
	ds_read_b128 v[220:223], v147 offset:39936
	global_load_lds_dwordx4 v130, s[60:61]
	s_mov_b32 m0, s65
	s_nop 0
	global_load_lds_dwordx4 v132, s[60:61]
	s_waitcnt vmcnt(8)
	s_waitcnt lgkmcnt(0)
	s_barrier
	s_setprio 1
	s_waitcnt lgkmcnt(0)
	v_mfma_f32_16x16x32_bf16 v[126:129], v[140:143], v[176:179], v[126:129]
	v_mfma_f32_16x16x32_bf16 v[122:125], v[152:155], v[176:179], v[122:125]
	v_mfma_f32_16x16x32_bf16 v[110:113], v[140:143], v[200:203], v[110:113]
	v_mfma_f32_16x16x32_bf16 v[106:109], v[152:155], v[200:203], v[106:109]
	v_mfma_f32_16x16x32_bf16 v[94:97], v[140:143], v[208:211], v[94:97]
	v_mfma_f32_16x16x32_bf16 v[90:93], v[152:155], v[208:211], v[90:93]
	v_mfma_f32_16x16x32_bf16 v[78:81], v[140:143], v[216:219], v[78:81]
	v_mfma_f32_16x16x32_bf16 v[74:77], v[152:155], v[216:219], v[74:77]
	v_mfma_f32_16x16x32_bf16 v[126:129], v[148:151], v[180:183], v[126:129]
	v_mfma_f32_16x16x32_bf16 v[122:125], v[156:159], v[180:183], v[122:125]
	v_mfma_f32_16x16x32_bf16 v[110:113], v[148:151], v[204:207], v[110:113]
	v_mfma_f32_16x16x32_bf16 v[106:109], v[156:159], v[204:207], v[106:109]
	v_mfma_f32_16x16x32_bf16 v[94:97], v[148:151], v[212:215], v[94:97]
	v_mfma_f32_16x16x32_bf16 v[90:93], v[156:159], v[212:215], v[90:93]
	v_mfma_f32_16x16x32_bf16 v[78:81], v[148:151], v[220:223], v[78:81]
	v_mfma_f32_16x16x32_bf16 v[74:77], v[156:159], v[220:223], v[74:77]
	s_setprio 0
	s_setprio 1
	v_mfma_f32_16x16x32_bf16 v[118:121], v[160:163], v[176:179], v[118:121]
	v_mfma_f32_16x16x32_bf16 v[114:117], v[168:171], v[176:179], v[114:117]
	v_mfma_f32_16x16x32_bf16 v[102:105], v[160:163], v[200:203], v[102:105]
	v_mfma_f32_16x16x32_bf16 v[98:101], v[168:171], v[200:203], v[98:101]
	v_mfma_f32_16x16x32_bf16 v[86:89], v[160:163], v[208:211], v[86:89]
	v_mfma_f32_16x16x32_bf16 v[82:85], v[168:171], v[208:211], v[82:85]
	v_mfma_f32_16x16x32_bf16 v[70:73], v[160:163], v[216:219], v[70:73]
	v_mfma_f32_16x16x32_bf16 v[66:69], v[168:171], v[216:219], v[66:69]
	v_mfma_f32_16x16x32_bf16 v[118:121], v[164:167], v[180:183], v[118:121]
	v_mfma_f32_16x16x32_bf16 v[114:117], v[172:175], v[180:183], v[114:117]
	v_mfma_f32_16x16x32_bf16 v[102:105], v[164:167], v[204:207], v[102:105]
	v_mfma_f32_16x16x32_bf16 v[98:101], v[172:175], v[204:207], v[98:101]
	v_mfma_f32_16x16x32_bf16 v[86:89], v[164:167], v[212:215], v[86:89]
	v_mfma_f32_16x16x32_bf16 v[82:85], v[172:175], v[212:215], v[82:85]
	v_mfma_f32_16x16x32_bf16 v[70:73], v[164:167], v[220:223], v[70:73]
	v_mfma_f32_16x16x32_bf16 v[66:69], v[172:175], v[220:223], v[66:69]
	s_setprio 0
	s_barrier
; #define PG8_STAGE(bufoff, gbase, voff) do { _Pragma("unroll") for (int _i = 0; _i < 2; ++_i) \
;         __builtin_amdgcn_global_load_lds((const unsigned*)((const char*)(gbase) + (voff)[_i]), (LAS unsigned*)(lds + (bufoff) + ldsw + _i * 8192), 16, 0, 0); } while (0)
; #define PG8_LDA(dst, b, h) do { _Pragma("unroll") for (int m = 0; m < 4; ++m) _Pragma("unroll") for (int k = 0; k < 2; ++k) dst[m][k] = *(const LAS bf16x8*)(lds + PG8_SA(b, h) + aoff + m * 2048 + k * 1024); } while (0)
; #define PG8_MMA(ai, bj, At, Bt) do { __builtin_amdgcn_s_setprio(1); _Pragma("unroll") for (int m = 0; m < 4; ++m) _Pragma("unroll") for (int n = 0; n < 2; ++n) _Pragma("unroll") for (int k = 0; k < 2; ++k) \
;         acc[ai][bj][m][n] = __builtin_amdgcn_mfma_f32_16x16x32_bf16(Bt[n][k], At[m][k], acc[ai][bj][m][n], 0, 0, 0); __builtin_amdgcn_s_setprio(0); } while (0)
; #define PG8_WAIT_V(n) asm volatile("s_waitcnt vmcnt(" #n ")" ::: "memory")
; #define PG8_WAIT_L(n) asm volatile("s_waitcnt lgkmcnt(" #n ")" ::: "memory")
; #define PG8_BAR __builtin_amdgcn_s_barrier()
; #define PG8_SCHED __builtin_amdgcn_sched_barrier(0)
; template <class Epi, class Sched, bool ALIGN_EPI = false, bool SP2 = false>
; __device__ __forceinline__ void gemm_phase(LAS unsigned char* lds, const Gemm g, const Sched& S, const Epi& E, const int tid_) {
;     ...
;             PG8_LDA(At, 1, 1); PG8_STAGE(PG8_SB(1, 0), b3, voffB); PG8_STAGE(PG8_SB(1, 1), b3 + hstep, voffB); PG8_STAGE(PG8_SA(1, 0), a3, voffA);
;             PG8_WAIT_V(8); PG8_WAIT_L(0); PG8_BAR; PG8_MMA(1, 0, At, B0); PG8_MMA(1, 1, At, B1); PG8_BAR; PG8_SCHED;
;     ...
;         }
;         if constexpr (ALIGN_EPI) { if (wr == 0) PG8_BAR; }
	s_add_i32 s60, s74, s62
	s_add_i32 m0, s60, 0xffffff80
	ds_read_b128 v[176:179], v147 offset:49152
	ds_read_b128 v[180:183], v147 offset:50176
	ds_read_b128 v[200:203], v147 offset:51200
	ds_read_b128 v[204:207], v147 offset:52224
	ds_read_b128 v[208:211], v147 offset:53248
	ds_read_b128 v[212:215], v147 offset:54272
	ds_read_b128 v[216:219], v147 offset:55296
	ds_read_b128 v[220:223], v147 offset:56320
	global_load_lds_dwordx4 v0, s[58:59] offset:128
	s_add_i32 m0, s60, 0x2000
	s_add_u32 s58, s58, 0x80080
	v_lshl_add_u64 v[184:185], v[224:225], 0, s[96:97]
	s_addc_u32 s59, s59, 0
	s_add_i32 s60, s75, s62
	global_load_lds_dwordx4 v[184:185], off
	s_mov_b32 m0, s60
	s_nop 0
	global_load_lds_dwordx4 v0, s[58:59]
	s_add_i32 m0, s60, 0x2000
	s_nop 0
	global_load_lds_dwordx4 v134, s[58:59]
	v_lshl_add_u64 v[184:185], v[236:237], 0, s[96:97]
	s_mov_b32 m0, s67
	s_nop 0
	global_load_lds_dwordx4 v[184:185], off
	v_lshl_add_u64 v[184:185], v[242:243], 0, s[96:97]
	s_mov_b32 m0, s68
	s_nop 0
	global_load_lds_dwordx4 v[184:185], off
	s_waitcnt vmcnt(8)
	s_waitcnt lgkmcnt(0)
	s_barrier
	s_setprio 1
	s_waitcnt lgkmcnt(0)
	v_mfma_f32_16x16x32_bf16 v[62:65], v[140:143], v[176:179], v[62:65]
	v_mfma_f32_16x16x32_bf16 v[58:61], v[152:155], v[176:179], v[58:61]
	v_mfma_f32_16x16x32_bf16 v[46:49], v[140:143], v[200:203], v[46:49]
	v_mfma_f32_16x16x32_bf16 v[42:45], v[152:155], v[200:203], v[42:45]
	v_mfma_f32_16x16x32_bf16 v[30:33], v[140:143], v[208:211], v[30:33]
	v_mfma_f32_16x16x32_bf16 v[26:29], v[152:155], v[208:211], v[26:29]
	v_mfma_f32_16x16x32_bf16 v[14:17], v[140:143], v[216:219], v[14:17]
	v_mfma_f32_16x16x32_bf16 v[10:13], v[152:155], v[216:219], v[10:13]
	v_mfma_f32_16x16x32_bf16 v[62:65], v[148:151], v[180:183], v[62:65]
	v_mfma_f32_16x16x32_bf16 v[58:61], v[156:159], v[180:183], v[58:61]
	v_mfma_f32_16x16x32_bf16 v[46:49], v[148:151], v[204:207], v[46:49]
	v_mfma_f32_16x16x32_bf16 v[42:45], v[156:159], v[204:207], v[42:45]
	v_mfma_f32_16x16x32_bf16 v[30:33], v[148:151], v[212:215], v[30:33]
	v_mfma_f32_16x16x32_bf16 v[26:29], v[156:159], v[212:215], v[26:29]
	v_mfma_f32_16x16x32_bf16 v[14:17], v[148:151], v[220:223], v[14:17]
	v_mfma_f32_16x16x32_bf16 v[10:13], v[156:159], v[220:223], v[10:13]
	s_setprio 0
	s_setprio 1
	v_mfma_f32_16x16x32_bf16 v[54:57], v[160:163], v[176:179], v[54:57]
	v_mfma_f32_16x16x32_bf16 v[50:53], v[168:171], v[176:179], v[50:53]
	v_mfma_f32_16x16x32_bf16 v[38:41], v[160:163], v[200:203], v[38:41]
	v_mfma_f32_16x16x32_bf16 v[34:37], v[168:171], v[200:203], v[34:37]
	v_mfma_f32_16x16x32_bf16 v[22:25], v[160:163], v[208:211], v[22:25]
	v_mfma_f32_16x16x32_bf16 v[18:21], v[168:171], v[208:211], v[18:21]
	v_mfma_f32_16x16x32_bf16 v[6:9], v[160:163], v[216:219], v[6:9]
	v_mfma_f32_16x16x32_bf16 v[2:5], v[168:171], v[216:219], v[2:5]
	v_mfma_f32_16x16x32_bf16 v[54:57], v[164:167], v[180:183], v[54:57]
	v_mfma_f32_16x16x32_bf16 v[50:53], v[172:175], v[180:183], v[50:53]
	v_mfma_f32_16x16x32_bf16 v[38:41], v[164:167], v[204:207], v[38:41]
	v_mfma_f32_16x16x32_bf16 v[34:37], v[172:175], v[204:207], v[34:37]
	v_mfma_f32_16x16x32_bf16 v[22:25], v[164:167], v[212:215], v[22:25]
	v_mfma_f32_16x16x32_bf16 v[18:21], v[172:175], v[212:215], v[18:21]
	v_mfma_f32_16x16x32_bf16 v[6:9], v[164:167], v[220:223], v[6:9]
	v_mfma_f32_16x16x32_bf16 v[2:5], v[172:175], v[220:223], v[2:5]
	s_setprio 0
	s_barrier
	s_add_i32 s73, s73, 2
	s_add_u32 s54, s54, 0x100
	s_addc_u32 s55, s55, 0
	s_add_u32 s49, s49, 0x100
	s_addc_u32 s72, s72, 0
	s_cmp_gt_u32 s73, 29
	s_cbranch_scc0 .LBB0_253
	s_andn2_b64 vcc, s[10:11], s[40:41]
	s_cbranch_vccz .LBB0_256
	s_barrier

; __device__ __forceinline__ unsigned cvt_pk_bf16(float lo, float hi) { f32x2 v = {lo, hi}; bf16x2_t r = __builtin_convertvector(v, bf16x2_t); return __builtin_bit_cast(unsigned, r); }
; #define PG8_BAR __builtin_amdgcn_s_barrier()
; template <class Epi, class Sched, bool ALIGN_EPI = false, bool SP2 = false>
; __device__ __forceinline__ void gemm_phase(LAS unsigned char* lds, const Gemm g, const Sched& S, const Epi& E, const int tid_) {
;     ...
;         if (!has_next) break;
; #pragma unroll
;         for (int a = 0; a < 2; ++a)
; #pragma unroll
;             for (int b = 0; b < 2; ++b)
; #pragma unroll
;                 for (int m = 0; m < 4; ++m)
; #pragma unroll
;                     for (int n = 0; n < 2; ++n) acc[a][b][m][n] = (f32x4){0.f, 0.f, 0.f, 0.f};
;         cur = nxt; cA = nA; cB = nB; ++ui;
;         if constexpr (ALIGN_EPI) { if (wr == 1) PG8_BAR; }
;     __device__ __forceinline__ void operator()(const f32x4 (&acc)[2][2][4][2], const pg8::Unit& u, int wr, int wc, int fr, int fq) const {
;     ...
;                     u32x4 w; w.x = cvt_pk_bf16(v0[0], v0[1]); w.y = cvt_pk_bf16(v0[2], v0[3]); w.z = cvt_pk_bf16(v1[0], v1[1]); w.w = cvt_pk_bf16(v1[2], v1[3]);
;                     *(u32x4*)(rowp + bj * 128) = w; } }
.LBB0_334:
	v_cvt_pk_bf16_f32 v6, v6, v7
	v_cvt_pk_bf16_f32 v7, v8, v9
	v_cvt_pk_bf16_f32 v8, v2, v3
	v_cvt_pk_bf16_f32 v9, v4, v5
	s_andn2_b64 vcc, exec, s[40:41]
	s_mov_b64 s[20:21], -1
	global_store_dwordx4 v[18:19], v[6:9], off offset:256
	s_cbranch_vccnz .LBB0_249
	s_andn2_b64 vcc, exec, s[8:9]
	s_cbranch_vccnz .LBB0_248
	s_nop 0
	s_branch .LBB0_248

; #define PG8_STAGE(bufoff, gbase, voff) do { _Pragma("unroll") for (int _i = 0; _i < 2; ++_i) \
;         __builtin_amdgcn_global_load_lds((const unsigned*)((const char*)(gbase) + (voff)[_i]), (LAS unsigned*)(lds + (bufoff) + ldsw + _i * 8192), 16, 0, 0); } while (0)
; #define PG8_LDA(dst, b, h) do { _Pragma("unroll") for (int m = 0; m < 4; ++m) _Pragma("unroll") for (int k = 0; k < 2; ++k) dst[m][k] = *(const LAS bf16x8*)(lds + PG8_SA(b, h) + aoff + m * 2048 + k * 1024); } while (0)
; #define PG8_LDB(dst, b, h) do { _Pragma("unroll") for (int n = 0; n < 2; ++n) _Pragma("unroll") for (int k = 0; k < 2; ++k) dst[n][k] = *(const LAS bf16x8*)(lds + PG8_SB(b, h) + boff + n * 2048 + k * 1024); } while (0)
; #define PG8_MMA(ai, bj, At, Bt) do { __builtin_amdgcn_s_setprio(1); _Pragma("unroll") for (int m = 0; m < 4; ++m) _Pragma("unroll") for (int n = 0; n < 2; ++n) _Pragma("unroll") for (int k = 0; k < 2; ++k) \
;         acc[ai][bj][m][n] = __builtin_amdgcn_mfma_f32_16x16x32_bf16(Bt[n][k], At[m][k], acc[ai][bj][m][n], 0, 0, 0); __builtin_amdgcn_s_setprio(0); } while (0)
; #define PG8_WAIT_V(n) asm volatile("s_waitcnt vmcnt(" #n ")" ::: "memory")
; #define PG8_BAR __builtin_amdgcn_s_barrier()
; template <class Epi, class Sched, bool ALIGN_EPI = false, bool SP2 = false>
; __device__ __forceinline__ void gemm_phase(LAS unsigned char* lds, const Gemm g, const Sched& S, const Epi& E, const int tid_) {
;     ...
;         for (int t = 0; t < nt; t += 2) {
;             const bool last = (t == nt - 2);
;             const char* a1 = cA + (size_t)(t + 1) * kstep;
;             const char* a2 = last ? nA : cA + (size_t)(t + 2) * kstep; const char* b2 = last ? nB : cB + (size_t)(t + 2) * kstep;
;             const char* a3 = a2 + kstep; const char* b3 = b2 + kstep;
;             if (last && has_next) S.a_ready(nxt);
;             if constexpr (SP2) {
;             PG8_LDB(B0, 0, 0); PG8_LDB(B1, 0, 1); PG8_SCHED; PG8_LDA(At, 0, 0); PG8_STAGE(PG8_SA(1, 1), a1 + hstep, voffA);
;             PG8_WAIT_V(8); PG8_WAIT_L(0); PG8_BAR; PG8_MMA(0, 0, At, B0); PG8_MMA(0, 1, At, B1); PG8_BAR; PG8_SCHED;
;             PG8_LDA(At, 0, 1); PG8_STAGE(PG8_SB(0, 0), b2, voffB); PG8_STAGE(PG8_SB(0, 1), b2 + hstep, voffB); PG8_STAGE(PG8_SA(0, 0), a2, voffA);
;             PG8_WAIT_V(8); PG8_WAIT_L(0); PG8_BAR; PG8_MMA(1, 0, At, B0); PG8_MMA(1, 1, At, B1); PG8_BAR; PG8_SCHED;
.LBB0_359:
	s_add_u32 s48, s46, 0x100
	s_addc_u32 s49, s47, 0
	s_add_i32 s68, 0, 0x10000
	s_cmpk_eq_i32 s67, 0x7c
	s_cselect_b32 s53, s17, s49
	s_cselect_b32 s52, s21, s48
	s_cselect_b32 s51, s15, s66
	s_cselect_b32 s50, s64, s65
	s_add_i32 s69, 0, 0x14000
	v_add_u32_e32 v148, s68, v157
	v_add_u32_e32 v168, s69, v157
	ds_read_b128 v[130:133], v148
	ds_read_b128 v[134:137], v148 offset:1024
	ds_read_b128 v[138:141], v148 offset:2048
	ds_read_b128 v[148:151], v148 offset:3072
	ds_read_b128 v[152:155], v168
	ds_read_b128 v[160:163], v168 offset:1024
	ds_read_b128 v[164:167], v168 offset:2048
	ds_read_b128 v[168:171], v168 offset:3072
	s_add_i32 m0, s45, 0xc000
	ds_read_b128 v[172:175], v159
	ds_read_b128 v[176:179], v159 offset:1024
	ds_read_b128 v[180:183], v159 offset:2048
	ds_read_b128 v[200:203], v159 offset:3072
	ds_read_b128 v[204:207], v159 offset:4096
	ds_read_b128 v[208:211], v159 offset:5120
	ds_read_b128 v[212:215], v159 offset:6144
	ds_read_b128 v[216:219], v159 offset:7168
	global_load_lds_dwordx4 v144, s[46:47]
	s_add_i32 m0, s45, 0xe000
	s_nop 0
	global_load_lds_dwordx4 v146, s[46:47]
	s_waitcnt vmcnt(8)
	s_waitcnt lgkmcnt(0)
	s_barrier
	s_setprio 1
	s_waitcnt lgkmcnt(0)
	v_mfma_f32_16x16x32_bf16 v[126:129], v[130:133], v[172:175], v[126:129]
	v_mfma_f32_16x16x32_bf16 v[122:125], v[138:141], v[172:175], v[122:125]
	v_mfma_f32_16x16x32_bf16 v[118:121], v[130:133], v[180:183], v[118:121]
	v_mfma_f32_16x16x32_bf16 v[106:109], v[138:141], v[180:183], v[106:109]
	v_mfma_f32_16x16x32_bf16 v[102:105], v[130:133], v[204:207], v[102:105]
	v_mfma_f32_16x16x32_bf16 v[90:93], v[138:141], v[204:207], v[90:93]
	v_mfma_f32_16x16x32_bf16 v[86:89], v[130:133], v[212:215], v[86:89]
	v_mfma_f32_16x16x32_bf16 v[74:77], v[138:141], v[212:215], v[74:77]
	v_mfma_f32_16x16x32_bf16 v[126:129], v[134:137], v[176:179], v[126:129]
	v_mfma_f32_16x16x32_bf16 v[122:125], v[148:151], v[176:179], v[122:125]
	v_mfma_f32_16x16x32_bf16 v[118:121], v[134:137], v[200:203], v[118:121]
	v_mfma_f32_16x16x32_bf16 v[106:109], v[148:151], v[200:203], v[106:109]
	v_mfma_f32_16x16x32_bf16 v[102:105], v[134:137], v[208:211], v[102:105]
	v_mfma_f32_16x16x32_bf16 v[90:93], v[148:151], v[208:211], v[90:93]
	v_mfma_f32_16x16x32_bf16 v[86:89], v[134:137], v[216:219], v[86:89]
	v_mfma_f32_16x16x32_bf16 v[74:77], v[148:151], v[216:219], v[74:77]
	s_setprio 0
	s_setprio 1
	v_mfma_f32_16x16x32_bf16 v[114:117], v[152:155], v[172:175], v[114:117]
	v_mfma_f32_16x16x32_bf16 v[110:113], v[164:167], v[172:175], v[110:113]
	v_mfma_f32_16x16x32_bf16 v[98:101], v[152:155], v[180:183], v[98:101]
	v_mfma_f32_16x16x32_bf16 v[94:97], v[164:167], v[180:183], v[94:97]
	v_mfma_f32_16x16x32_bf16 v[82:85], v[152:155], v[204:207], v[82:85]
	v_mfma_f32_16x16x32_bf16 v[78:81], v[164:167], v[204:207], v[78:81]
	v_mfma_f32_16x16x32_bf16 v[70:73], v[152:155], v[212:215], v[70:73]
	v_mfma_f32_16x16x32_bf16 v[66:69], v[164:167], v[212:215], v[66:69]
	v_mfma_f32_16x16x32_bf16 v[114:117], v[160:163], v[176:179], v[114:117]
	v_mfma_f32_16x16x32_bf16 v[110:113], v[168:171], v[176:179], v[110:113]
	v_mfma_f32_16x16x32_bf16 v[98:101], v[160:163], v[200:203], v[98:101]
	v_mfma_f32_16x16x32_bf16 v[94:97], v[168:171], v[200:203], v[94:97]
	v_mfma_f32_16x16x32_bf16 v[82:85], v[160:163], v[208:211], v[82:85]
	v_mfma_f32_16x16x32_bf16 v[78:81], v[168:171], v[208:211], v[78:81]
	v_mfma_f32_16x16x32_bf16 v[70:73], v[160:163], v[216:219], v[70:73]
	v_mfma_f32_16x16x32_bf16 v[66:69], v[168:171], v[216:219], v[66:69]
	s_setprio 0
	s_barrier
	s_add_i32 s46, s68, s55
	s_mov_b32 m0, s46
	ds_read_b128 v[172:175], v159 offset:16384
	ds_read_b128 v[176:179], v159 offset:17408
	ds_read_b128 v[180:183], v159 offset:18432
	ds_read_b128 v[200:203], v159 offset:19456
	ds_read_b128 v[204:207], v159 offset:20480
	ds_read_b128 v[208:211], v159 offset:21504
	ds_read_b128 v[212:215], v159 offset:22528
	ds_read_b128 v[216:219], v159 offset:23552
	global_load_lds_dwordx4 v0, s[50:51]
	s_add_i32 m0, s46, 0x2000
	s_add_u32 s46, s50, 0x200000
	v_lshl_add_u64 v[192:193], s[50:51], 0, v[142:143]
	s_addc_u32 s47, s51, 0
	s_add_i32 s68, s69, s55
	global_load_lds_dwordx4 v142, s[50:51]
	s_mov_b32 m0, s68
	s_nop 0
	global_load_lds_dwordx4 v0, s[46:47]
	s_add_i32 m0, s68, 0x2000
	s_nop 0
	global_load_lds_dwordx4 v142, s[46:47]
	s_mov_b32 m0, s45
	s_nop 0
	global_load_lds_dwordx4 v0, s[52:53]
	s_mov_b32 m0, s56
	s_nop 0
	global_load_lds_dwordx4 v142, s[52:53]
	s_waitcnt vmcnt(8)
	s_waitcnt lgkmcnt(0)
	s_barrier
	s_setprio 1
	s_waitcnt lgkmcnt(0)
	v_mfma_f32_16x16x32_bf16 v[62:65], v[130:133], v[172:175], v[62:65]
	v_mfma_f32_16x16x32_bf16 v[58:61], v[138:141], v[172:175], v[58:61]
	v_mfma_f32_16x16x32_bf16 v[54:57], v[130:133], v[180:183], v[54:57]
	v_mfma_f32_16x16x32_bf16 v[42:45], v[138:141], v[180:183], v[42:45]
	v_mfma_f32_16x16x32_bf16 v[38:41], v[130:133], v[204:207], v[38:41]
	v_mfma_f32_16x16x32_bf16 v[26:29], v[138:141], v[204:207], v[26:29]
	v_mfma_f32_16x16x32_bf16 v[22:25], v[130:133], v[212:215], v[22:25]
	v_mfma_f32_16x16x32_bf16 v[10:13], v[138:141], v[212:215], v[10:13]
	v_mfma_f32_16x16x32_bf16 v[62:65], v[134:137], v[176:179], v[62:65]
	v_mfma_f32_16x16x32_bf16 v[58:61], v[148:151], v[176:179], v[58:61]
	v_mfma_f32_16x16x32_bf16 v[54:57], v[134:137], v[200:203], v[54:57]
	v_mfma_f32_16x16x32_bf16 v[42:45], v[148:151], v[200:203], v[42:45]
	v_mfma_f32_16x16x32_bf16 v[38:41], v[134:137], v[208:211], v[38:41]
	v_mfma_f32_16x16x32_bf16 v[26:29], v[148:151], v[208:211], v[26:29]
	v_mfma_f32_16x16x32_bf16 v[22:25], v[134:137], v[216:219], v[22:25]
	v_mfma_f32_16x16x32_bf16 v[10:13], v[148:151], v[216:219], v[10:13]
	s_setprio 0
	s_setprio 1
	v_mfma_f32_16x16x32_bf16 v[50:53], v[152:155], v[172:175], v[50:53]
	v_mfma_f32_16x16x32_bf16 v[46:49], v[164:167], v[172:175], v[46:49]
	v_mfma_f32_16x16x32_bf16 v[34:37], v[152:155], v[180:183], v[34:37]
	v_mfma_f32_16x16x32_bf16 v[30:33], v[164:167], v[180:183], v[30:33]
	v_mfma_f32_16x16x32_bf16 v[18:21], v[152:155], v[204:207], v[18:21]
	v_mfma_f32_16x16x32_bf16 v[14:17], v[164:167], v[204:207], v[14:17]
	v_mfma_f32_16x16x32_bf16 v[6:9], v[152:155], v[212:215], v[6:9]
	v_mfma_f32_16x16x32_bf16 v[2:5], v[164:167], v[212:215], v[2:5]
	v_mfma_f32_16x16x32_bf16 v[50:53], v[160:163], v[176:179], v[50:53]
	v_mfma_f32_16x16x32_bf16 v[46:49], v[168:171], v[176:179], v[46:49]
	v_mfma_f32_16x16x32_bf16 v[34:37], v[160:163], v[200:203], v[34:37]
	v_mfma_f32_16x16x32_bf16 v[30:33], v[168:171], v[200:203], v[30:33]
	v_mfma_f32_16x16x32_bf16 v[18:21], v[160:163], v[208:211], v[18:21]
	v_mfma_f32_16x16x32_bf16 v[14:17], v[168:171], v[208:211], v[14:17]
	v_mfma_f32_16x16x32_bf16 v[6:9], v[160:163], v[216:219], v[6:9]
	v_mfma_f32_16x16x32_bf16 v[2:5], v[168:171], v[216:219], v[2:5]
	s_setprio 0
	s_barrier
; #define PG8_STAGE(bufoff, gbase, voff) do { _Pragma("unroll") for (int _i = 0; _i < 2; ++_i) \
;         __builtin_amdgcn_global_load_lds((const unsigned*)((const char*)(gbase) + (voff)[_i]), (LAS unsigned*)(lds + (bufoff) + ldsw + _i * 8192), 16, 0, 0); } while (0)
; #define PG8_BAR __builtin_amdgcn_s_barrier()
; template <class Epi, class Sched, bool ALIGN_EPI = false, bool SP2 = false>
; __device__ __forceinline__ void gemm_phase(LAS unsigned char* lds, const Gemm g, const Sched& S, const Epi& E, const int tid_) {
;     ...
;             PG8_LDB(B0, 1, 0); PG8_LDB(B1, 1, 1); PG8_SCHED; PG8_LDA(At, 1, 0); PG8_STAGE(PG8_SA(0, 1), a2 + hstep, voffA);
;             PG8_WAIT_V(8); PG8_WAIT_L(0); PG8_BAR; PG8_MMA(0, 0, At, B0); PG8_MMA(0, 1, At, B1); PG8_BAR; PG8_SCHED;
;             PG8_LDA(At, 1, 1); PG8_STAGE(PG8_SB(1, 0), b3, voffB); PG8_STAGE(PG8_SB(1, 1), b3 + hstep, voffB); PG8_STAGE(PG8_SA(1, 0), a3, voffA);
;             PG8_WAIT_V(8); PG8_WAIT_L(0); PG8_BAR; PG8_MMA(1, 0, At, B0); PG8_MMA(1, 1, At, B1); PG8_BAR; PG8_SCHED;
;             } else {
;             PG8_LDB(B0, 0, 0); PG8_SCHED; PG8_LDA(At, 0, 0); PG8_STAGE(PG8_SA(1, 1), a1 + hstep, voffA);
;             PG8_WAIT_L(8); PG8_BAR; PG8_WAIT_L(0); PG8_MMA(0, 0, At, B0); PG8_BAR; PG8_SCHED;
;             PG8_LDB(B1, 0, 1); PG8_STAGE(PG8_SB(0, 0), b2, voffB);
;             PG8_BAR; PG8_WAIT_L(0); PG8_MMA(0, 1, At, B1); PG8_BAR;
;             PG8_LDA(At, 0, 1); PG8_STAGE(PG8_SA(0, 0), a2, voffA);
;             PG8_BAR; PG8_WAIT_L(0); PG8_MMA(1, 0, At, B0); PG8_BAR; PG8_SCHED;
;             PG8_STAGE(PG8_SB(0, 1), b2 + hstep, voffB);
;             PG8_WAIT_V(6); PG8_BAR; PG8_MMA(1, 1, At, B1); PG8_BAR;
;             PG8_LDB(B0, 1, 0); PG8_SCHED; PG8_LDA(At, 1, 0); PG8_STAGE(PG8_SA(0, 1), a2 + hstep, voffA);
;             PG8_WAIT_L(8); PG8_BAR; PG8_WAIT_L(0); PG8_MMA(0, 0, At, B0); PG8_BAR; PG8_SCHED;
;             PG8_LDB(B1, 1, 1); PG8_STAGE(PG8_SB(1, 0), b3, voffB);
;             PG8_BAR; PG8_WAIT_L(0); PG8_MMA(0, 1, At, B1); PG8_BAR;
;             PG8_LDA(At, 1, 1); PG8_STAGE(PG8_SA(1, 0), a3, voffA);
;             PG8_BAR; PG8_WAIT_L(0); PG8_MMA(1, 0, At, B0); PG8_BAR; PG8_SCHED;
;             PG8_STAGE(PG8_SB(1, 1), b3 + hstep, voffB);
;             PG8_WAIT_V(6); PG8_BAR; PG8_MMA(1, 1, At, B1); PG8_BAR;
;             }
;         }
;         if constexpr (ALIGN_EPI) { if (wr == 0) PG8_BAR; }
	s_add_i32 s68, 0, 0x18000
	s_add_i32 s69, 0, 0x1c000
	v_add_u32_e32 v148, s68, v157
	v_add_u32_e32 v168, s69, v157
	ds_read_b128 v[130:133], v148
	ds_read_b128 v[134:137], v148 offset:1024
	ds_read_b128 v[138:141], v148 offset:2048
	ds_read_b128 v[148:151], v148 offset:3072
	ds_read_b128 v[152:155], v168
	ds_read_b128 v[160:163], v168 offset:1024
	ds_read_b128 v[164:167], v168 offset:2048
	ds_read_b128 v[168:171], v168 offset:3072
	s_add_u32 s46, s52, 0x200000
	s_addc_u32 s47, s53, 0
	s_mov_b32 m0, s57
	ds_read_b128 v[172:175], v159 offset:32768
	ds_read_b128 v[176:179], v159 offset:33792
	ds_read_b128 v[180:183], v159 offset:34816
	ds_read_b128 v[200:203], v159 offset:35840
	ds_read_b128 v[204:207], v159 offset:36864
	ds_read_b128 v[208:211], v159 offset:37888
	ds_read_b128 v[212:215], v159 offset:38912
	ds_read_b128 v[216:219], v159 offset:39936
	global_load_lds_dwordx4 v0, s[46:47]
	s_mov_b32 m0, s58
	s_nop 0
	global_load_lds_dwordx4 v142, s[46:47]
	s_waitcnt vmcnt(8)
	s_waitcnt lgkmcnt(0)
	s_barrier
	s_setprio 1
	s_waitcnt lgkmcnt(0)
	v_mfma_f32_16x16x32_bf16 v[126:129], v[130:133], v[172:175], v[126:129]
	v_mfma_f32_16x16x32_bf16 v[122:125], v[138:141], v[172:175], v[122:125]
	v_mfma_f32_16x16x32_bf16 v[118:121], v[130:133], v[180:183], v[118:121]
	v_mfma_f32_16x16x32_bf16 v[106:109], v[138:141], v[180:183], v[106:109]
	v_mfma_f32_16x16x32_bf16 v[102:105], v[130:133], v[204:207], v[102:105]
	v_mfma_f32_16x16x32_bf16 v[90:93], v[138:141], v[204:207], v[90:93]
	v_mfma_f32_16x16x32_bf16 v[86:89], v[130:133], v[212:215], v[86:89]
	v_mfma_f32_16x16x32_bf16 v[74:77], v[138:141], v[212:215], v[74:77]
	v_mfma_f32_16x16x32_bf16 v[126:129], v[134:137], v[176:179], v[126:129]
	v_mfma_f32_16x16x32_bf16 v[122:125], v[148:151], v[176:179], v[122:125]
	v_mfma_f32_16x16x32_bf16 v[118:121], v[134:137], v[200:203], v[118:121]
	v_mfma_f32_16x16x32_bf16 v[106:109], v[148:151], v[200:203], v[106:109]
	v_mfma_f32_16x16x32_bf16 v[102:105], v[134:137], v[208:211], v[102:105]
	v_mfma_f32_16x16x32_bf16 v[90:93], v[148:151], v[208:211], v[90:93]
	v_mfma_f32_16x16x32_bf16 v[86:89], v[134:137], v[216:219], v[86:89]
	v_mfma_f32_16x16x32_bf16 v[74:77], v[148:151], v[216:219], v[74:77]
	s_setprio 0
	s_setprio 1
	v_mfma_f32_16x16x32_bf16 v[114:117], v[152:155], v[172:175], v[114:117]
	v_mfma_f32_16x16x32_bf16 v[110:113], v[164:167], v[172:175], v[110:113]
	v_mfma_f32_16x16x32_bf16 v[98:101], v[152:155], v[180:183], v[98:101]
	v_mfma_f32_16x16x32_bf16 v[94:97], v[164:167], v[180:183], v[94:97]
	v_mfma_f32_16x16x32_bf16 v[82:85], v[152:155], v[204:207], v[82:85]
	v_mfma_f32_16x16x32_bf16 v[78:81], v[164:167], v[204:207], v[78:81]
	v_mfma_f32_16x16x32_bf16 v[70:73], v[152:155], v[212:215], v[70:73]
	v_mfma_f32_16x16x32_bf16 v[66:69], v[164:167], v[212:215], v[66:69]
	v_mfma_f32_16x16x32_bf16 v[114:117], v[160:163], v[176:179], v[114:117]
	v_mfma_f32_16x16x32_bf16 v[110:113], v[168:171], v[176:179], v[110:113]
	v_mfma_f32_16x16x32_bf16 v[98:101], v[160:163], v[200:203], v[98:101]
	v_mfma_f32_16x16x32_bf16 v[94:97], v[168:171], v[200:203], v[94:97]
	v_mfma_f32_16x16x32_bf16 v[82:85], v[160:163], v[208:211], v[82:85]
	v_mfma_f32_16x16x32_bf16 v[78:81], v[168:171], v[208:211], v[78:81]
	v_mfma_f32_16x16x32_bf16 v[70:73], v[160:163], v[216:219], v[70:73]
	v_mfma_f32_16x16x32_bf16 v[66:69], v[168:171], v[216:219], v[66:69]
	s_setprio 0
	s_barrier
	s_add_i32 s46, s68, s55
	s_add_i32 m0, s46, 0xffffff80
	ds_read_b128 v[172:175], v159 offset:49152
	ds_read_b128 v[176:179], v159 offset:50176
	ds_read_b128 v[180:183], v159 offset:51200
	ds_read_b128 v[200:203], v159 offset:52224
	ds_read_b128 v[204:207], v159 offset:53248
	ds_read_b128 v[208:211], v159 offset:54272
	ds_read_b128 v[212:215], v159 offset:55296
	ds_read_b128 v[216:219], v159 offset:56320
	global_load_lds_dwordx4 v0, s[50:51] offset:128
	s_add_i32 m0, s46, 0x2000
	s_add_u32 s46, s50, 0x200080
	v_lshl_add_u64 v[184:185], v[192:193], 0, s[96:97]
	s_addc_u32 s47, s51, 0
	s_add_i32 s50, s69, s55
	global_load_lds_dwordx4 v[184:185], off
	s_mov_b32 m0, s50
	s_nop 0
	global_load_lds_dwordx4 v0, s[46:47]
	s_add_i32 m0, s50, 0x2000
	s_nop 0
	global_load_lds_dwordx4 v142, s[46:47]
	s_add_i32 m0, s60, 0xffffff80
	s_nop 0
	global_load_lds_dwordx4 v0, s[52:53] offset:128
	s_add_i32 m0, s61, 0xffffff80
	s_nop 0
	global_load_lds_dwordx4 v142, s[52:53] offset:128
	s_waitcnt vmcnt(8)
	s_waitcnt lgkmcnt(0)
	s_barrier
	s_setprio 1
	s_waitcnt lgkmcnt(0)
	v_mfma_f32_16x16x32_bf16 v[62:65], v[130:133], v[172:175], v[62:65]
	v_mfma_f32_16x16x32_bf16 v[58:61], v[138:141], v[172:175], v[58:61]
	v_mfma_f32_16x16x32_bf16 v[54:57], v[130:133], v[180:183], v[54:57]
	v_mfma_f32_16x16x32_bf16 v[42:45], v[138:141], v[180:183], v[42:45]
	v_mfma_f32_16x16x32_bf16 v[38:41], v[130:133], v[204:207], v[38:41]
	v_mfma_f32_16x16x32_bf16 v[26:29], v[138:141], v[204:207], v[26:29]
	v_mfma_f32_16x16x32_bf16 v[22:25], v[130:133], v[212:215], v[22:25]
	v_mfma_f32_16x16x32_bf16 v[10:13], v[138:141], v[212:215], v[10:13]
	v_mfma_f32_16x16x32_bf16 v[62:65], v[134:137], v[176:179], v[62:65]
	v_mfma_f32_16x16x32_bf16 v[58:61], v[148:151], v[176:179], v[58:61]
	v_mfma_f32_16x16x32_bf16 v[54:57], v[134:137], v[200:203], v[54:57]
	v_mfma_f32_16x16x32_bf16 v[42:45], v[148:151], v[200:203], v[42:45]
	v_mfma_f32_16x16x32_bf16 v[38:41], v[134:137], v[208:211], v[38:41]
	v_mfma_f32_16x16x32_bf16 v[26:29], v[148:151], v[208:211], v[26:29]
	v_mfma_f32_16x16x32_bf16 v[22:25], v[134:137], v[216:219], v[22:25]
	v_mfma_f32_16x16x32_bf16 v[10:13], v[148:151], v[216:219], v[10:13]
	s_setprio 0
	s_setprio 1
	v_mfma_f32_16x16x32_bf16 v[50:53], v[152:155], v[172:175], v[50:53]
	v_mfma_f32_16x16x32_bf16 v[46:49], v[164:167], v[172:175], v[46:49]
	v_mfma_f32_16x16x32_bf16 v[34:37], v[152:155], v[180:183], v[34:37]
	v_mfma_f32_16x16x32_bf16 v[30:33], v[164:167], v[180:183], v[30:33]
	v_mfma_f32_16x16x32_bf16 v[18:21], v[152:155], v[204:207], v[18:21]
	v_mfma_f32_16x16x32_bf16 v[14:17], v[164:167], v[204:207], v[14:17]
	v_mfma_f32_16x16x32_bf16 v[6:9], v[152:155], v[212:215], v[6:9]
	v_mfma_f32_16x16x32_bf16 v[2:5], v[164:167], v[212:215], v[2:5]
	v_mfma_f32_16x16x32_bf16 v[50:53], v[160:163], v[176:179], v[50:53]
	v_mfma_f32_16x16x32_bf16 v[46:49], v[168:171], v[176:179], v[46:49]
	v_mfma_f32_16x16x32_bf16 v[34:37], v[160:163], v[200:203], v[34:37]
	v_mfma_f32_16x16x32_bf16 v[30:33], v[168:171], v[200:203], v[30:33]
	v_mfma_f32_16x16x32_bf16 v[18:21], v[160:163], v[208:211], v[18:21]
	v_mfma_f32_16x16x32_bf16 v[14:17], v[168:171], v[208:211], v[14:17]
	v_mfma_f32_16x16x32_bf16 v[6:9], v[160:163], v[216:219], v[6:9]
	v_mfma_f32_16x16x32_bf16 v[2:5], v[168:171], v[216:219], v[2:5]
	s_setprio 0
	s_barrier
	s_add_i32 s67, s67, 2
	s_add_u32 s65, s65, 0x100
	s_addc_u32 s66, s66, 0
	s_cmpk_gt_u32 s67, 0x7d
	s_mov_b64 s[46:47], s[48:49]
	s_cbranch_scc0 .LBB0_359
	s_andn2_b64 vcc, s[12:13], s[40:41]
	s_cbranch_vccz .LBB0_362
	s_barrier
;     __device__ __forceinline__ void operator()(const f32x4 (&acc)[2][2][4][2], const pg8::Unit& u, int wr, int wc, int fr, int fq) const {
;         const int row0 = u.pm * 256 + wr * 64 + fr, col0 = u.pn * 256 + wc * 32 + 4 * fq;
; #pragma unroll
;         for (int ai = 0; ai < 2; ++ai) {
;             f32x4 r[4][2][2];
; #pragma unroll
;             for (int m = 0; m < 4; ++m) { const size_t off = (size_t)(row0 + ai * 128 + m * 16) * 2048 + col0;
; #pragma unroll
;                 for (int bj = 0; bj < 2; ++bj)
; #pragma unroll
;                     for (int n = 0; n < 2; ++n) r[m][bj][n] = *(const f32x4*)(res + off + bj * 128 + n * 16); }
;             asm volatile("" ::: "memory");
; #pragma unroll
;             for (int m = 0; m < 4; ++m) { const size_t off = (size_t)(row0 + ai * 128 + m * 16) * 2048 + col0;
; #pragma unroll
;                 for (int bj = 0; bj < 2; ++bj)
; #pragma unroll
;                     for (int n = 0; n < 2; ++n) *(f32x4*)(out + off + bj * 128 + n * 16) = r[m][bj][n] + acc[ai][bj][m][n]; }
;             asm volatile("" ::: "memory");
;         }
.LBB0_362:
	v_lshl_or_b32 v132, s20, 8, v158
	v_lshl_add_u32 v130, s44, 8, v156
	v_ashrrev_i32_e32 v133, 31, v132
	v_lshlrev_b64 v[148:149], 2, v[132:133]
	v_ashrrev_i32_e32 v131, 31, v130
	v_lshl_add_u64 v[150:151], s[8:9], 0, v[148:149]
	v_lshlrev_b64 v[152:153], 13, v[130:131]
	v_lshl_add_u64 v[132:133], v[150:151], 0, v[152:153]
	global_load_dwordx4 v[160:163], v[132:133], off
	global_load_dwordx4 v[164:167], v[132:133], off offset:64
	global_load_dwordx4 v[168:171], v[132:133], off offset:512
	global_load_dwordx4 v[172:175], v[132:133], off offset:576
	v_or_b32_e32 v132, 16, v130
	v_ashrrev_i32_e32 v133, 31, v132
	v_lshlrev_b64 v[184:185], 13, v[132:133]
	v_lshl_add_u64 v[132:133], v[150:151], 0, v[184:185]
	global_load_dwordx4 v[176:179], v[132:133], off
	global_load_dwordx4 v[180:183], v[132:133], off offset:64
	global_load_dwordx4 v[200:203], v[132:133], off offset:512
	global_load_dwordx4 v[204:207], v[132:133], off offset:576
	v_or_b32_e32 v132, 32, v130
	v_ashrrev_i32_e32 v133, 31, v132
	v_or_b32_e32 v130, 48, v130
	v_lshlrev_b64 v[192:193], 13, v[132:133]
	v_ashrrev_i32_e32 v131, 31, v130
	v_lshl_add_u64 v[132:133], v[150:151], 0, v[192:193]
	v_lshlrev_b64 v[154:155], 13, v[130:131]
	global_load_dwordx4 v[208:211], v[132:133], off
	global_load_dwordx4 v[212:215], v[132:133], off offset:64
	global_load_dwordx4 v[216:219], v[132:133], off offset:512
	global_load_dwordx4 v[220:223], v[132:133], off offset:576
	v_lshl_add_u64 v[130:131], v[150:151], 0, v[154:155]
	global_load_dwordx4 v[242:245], v[130:131], off
	global_load_dwordx4 v[138:141], v[130:131], off offset:64
	global_load_dwordx4 v[134:137], v[130:131], off offset:512
	s_nop 0
	global_load_dwordx4 v[130:133], v[130:131], off offset:576
	s_mov_b64 s[20:21], 0x100000
	s_andn2_b64 vcc, exec, s[40:41]
	s_waitcnt vmcnt(0)
	v_pk_add_f32 v[126:127], v[126:127], v[160:161]
	v_lshl_add_u64 v[160:161], s[8:9], 0, v[152:153]
	v_lshl_add_u64 v[160:161], v[160:161], 0, v[148:149]
	v_pk_add_f32 v[116:117], v[116:117], v[170:171]
	v_pk_add_f32 v[114:115], v[114:115], v[168:169]
	global_store_dwordx4 v[160:161], v[114:117], off offset:512
	v_pk_add_f32 v[112:113], v[112:113], v[174:175]
	v_pk_add_f32 v[100:101], v[100:101], v[202:203]
	v_lshl_add_u64 v[114:115], s[8:9], 0, v[184:185]
	v_lshl_add_u64 v[114:115], v[114:115], 0, v[148:149]
	v_pk_add_f32 v[98:99], v[98:99], v[200:201]
	global_store_dwordx4 v[114:115], v[98:101], off offset:512
	v_pk_add_f32 v[110:111], v[110:111], v[172:173]
	v_pk_add_f32 v[96:97], v[96:97], v[206:207]
	v_lshl_add_u64 v[98:99], s[8:9], 0, v[192:193]
	v_lshl_add_u64 v[98:99], v[98:99], 0, v[148:149]
	v_pk_add_f32 v[84:85], v[84:85], v[218:219]
	v_pk_add_f32 v[82:83], v[82:83], v[216:217]
	v_pk_add_f32 v[94:95], v[94:95], v[204:205]
	global_store_dwordx4 v[98:99], v[82:85], off offset:512
	v_pk_add_f32 v[80:81], v[80:81], v[222:223]
	v_pk_add_f32 v[78:79], v[78:79], v[220:221]
	v_lshl_add_u64 v[82:83], s[8:9], 0, v[154:155]
	v_pk_add_f32 v[128:129], v[128:129], v[162:163]
	v_pk_add_f32 v[124:125], v[124:125], v[166:167]
	v_pk_add_f32 v[122:123], v[122:123], v[164:165]
	global_store_dwordx4 v[160:161], v[110:113], off offset:576
	v_pk_add_f32 v[108:109], v[108:109], v[182:183]
	v_pk_add_f32 v[106:107], v[106:107], v[180:181]
	v_pk_add_f32 v[112:113], v[120:121], v[178:179]
	v_pk_add_f32 v[110:111], v[118:119], v[176:177]
	global_store_dwordx4 v[114:115], v[94:97], off offset:576
	v_pk_add_f32 v[92:93], v[92:93], v[214:215]
	v_pk_add_f32 v[90:91], v[90:91], v[212:213]
	v_pk_add_f32 v[96:97], v[104:105], v[210:211]
	v_pk_add_f32 v[94:95], v[102:103], v[208:209]
	global_store_dwordx4 v[98:99], v[78:81], off offset:576
	v_lshl_add_u64 v[82:83], v[82:83], 0, v[148:149]
	v_pk_add_f32 v[76:77], v[76:77], v[140:141]
	v_pk_add_f32 v[80:81], v[88:89], v[244:245]
	v_pk_add_f32 v[78:79], v[86:87], v[242:243]
	v_pk_add_f32 v[74:75], v[74:75], v[138:139]
	v_pk_add_f32 v[72:73], v[72:73], v[136:137]
	v_pk_add_f32 v[70:71], v[70:71], v[134:135]
	v_pk_add_f32 v[68:69], v[68:69], v[132:133]
	v_pk_add_f32 v[66:67], v[66:67], v[130:131]
	global_store_dwordx4 v[160:161], v[126:129], off
	global_store_dwordx4 v[160:161], v[122:125], off offset:64
	global_store_dwordx4 v[114:115], v[110:113], off
	global_store_dwordx4 v[114:115], v[106:109], off offset:64
	global_store_dwordx4 v[98:99], v[94:97], off
	global_store_dwordx4 v[98:99], v[90:93], off offset:64
	global_store_dwordx4 v[82:83], v[78:81], off
	global_store_dwordx4 v[82:83], v[74:77], off offset:64
	global_store_dwordx4 v[82:83], v[70:73], off offset:512
	global_store_dwordx4 v[82:83], v[66:69], off offset:576
	v_lshl_add_u64 v[132:133], v[152:153], 0, s[20:21]
	s_mov_b64 s[20:21], 0x120000
	v_lshl_add_u64 v[66:67], v[150:151], 0, v[132:133]
	global_load_dwordx4 v[80:83], v[66:67], off
	global_load_dwordx4 v[84:87], v[66:67], off offset:64
	global_load_dwordx4 v[88:91], v[66:67], off offset:512
	global_load_dwordx4 v[92:95], v[66:67], off offset:576
	v_lshl_add_u64 v[134:135], v[152:153], 0, s[20:21]
	v_lshl_add_u64 v[66:67], v[150:151], 0, v[134:135]
	s_mov_b64 s[20:21], 0x140000
	global_load_dwordx4 v[96:99], v[66:67], off
	global_load_dwordx4 v[100:103], v[66:67], off offset:64
	global_load_dwordx4 v[104:107], v[66:67], off offset:512
	global_load_dwordx4 v[108:111], v[66:67], off offset:576
	v_lshl_add_u64 v[136:137], v[152:153], 0, s[20:21]
	s_mov_b64 s[20:21], 0x160000
	v_lshl_add_u64 v[66:67], v[150:151], 0, v[136:137]
	v_lshl_add_u64 v[78:79], v[152:153], 0, s[20:21]
	global_load_dwordx4 v[112:115], v[66:67], off
	global_load_dwordx4 v[116:119], v[66:67], off offset:64
	global_load_dwordx4 v[120:123], v[66:67], off offset:512
	global_load_dwordx4 v[124:127], v[66:67], off offset:576
	v_lshl_add_u64 v[66:67], v[150:151], 0, v[78:79]
	global_load_dwordx4 v[128:131], v[66:67], off
	global_load_dwordx4 v[74:77], v[66:67], off offset:64
	global_load_dwordx4 v[70:73], v[66:67], off offset:512
	s_nop 0
	global_load_dwordx4 v[66:69], v[66:67], off offset:576
	s_mov_b64 s[20:21], -1
	s_waitcnt vmcnt(15)
; #define PG8_WAIT_V(n) asm volatile("s_waitcnt vmcnt(" #n ")" ::: "memory")
; #define PG8_BAR __builtin_amdgcn_s_barrier()
; template <class Epi, class Sched, bool ALIGN_EPI = false, bool SP2 = false>
; __device__ __forceinline__ void gemm_phase(LAS unsigned char* lds, const Gemm g, const Sched& S, const Epi& E, const int tid_) {
;     ...
;         if (!has_next) break;
; #pragma unroll
;         for (int a = 0; a < 2; ++a)
; #pragma unroll
;             for (int b = 0; b < 2; ++b)
; #pragma unroll
;                 for (int m = 0; m < 4; ++m)
; #pragma unroll
;                     for (int n = 0; n < 2; ++n) acc[a][b][m][n] = (f32x4){0.f, 0.f, 0.f, 0.f};
;         cur = nxt; cA = nA; cB = nB; ++ui;
;         if constexpr (ALIGN_EPI) { if (wr == 1) PG8_BAR; }
;     }
;     PG8_WAIT_V(0);
;     if constexpr (!ALIGN_EPI) { if (wr == 0) PG8_BAR; }
;     __device__ __forceinline__ void operator()(const f32x4 (&acc)[2][2][4][2], const pg8::Unit& u, int wr, int wc, int fr, int fq) const {
;     ...
;             for (int m = 0; m < 4; ++m) { const size_t off = (size_t)(row0 + ai * 128 + m * 16) * 2048 + col0;
; #pragma unroll
;                 for (int bj = 0; bj < 2; ++bj)
; #pragma unroll
;                     for (int n = 0; n < 2; ++n) *(f32x4*)(out + off + bj * 128 + n * 16) = r[m][bj][n] + acc[ai][bj][m][n]; }
;             asm volatile("" ::: "memory");
;         }
	v_pk_add_f32 v[62:63], v[62:63], v[80:81]
	v_lshl_add_u64 v[80:81], s[8:9], 0, v[132:133]
	v_lshl_add_u64 v[80:81], v[80:81], 0, v[148:149]
	s_waitcnt vmcnt(13)
	v_pk_add_f32 v[52:53], v[52:53], v[90:91]
	v_pk_add_f32 v[50:51], v[50:51], v[88:89]
	global_store_dwordx4 v[80:81], v[50:53], off offset:512
	s_waitcnt vmcnt(10)
	v_pk_add_f32 v[36:37], v[36:37], v[106:107]
	v_pk_add_f32 v[34:35], v[34:35], v[104:105]
	v_lshl_add_u64 v[50:51], s[8:9], 0, v[134:135]
	v_lshl_add_u64 v[50:51], v[50:51], 0, v[148:149]
	global_store_dwordx4 v[50:51], v[34:37], off offset:512
	s_waitcnt vmcnt(7)
	v_pk_add_f32 v[20:21], v[20:21], v[122:123]
	v_pk_add_f32 v[18:19], v[18:19], v[120:121]
	v_lshl_add_u64 v[34:35], s[8:9], 0, v[136:137]
	v_lshl_add_u64 v[34:35], v[34:35], 0, v[148:149]
	v_pk_add_f32 v[48:49], v[48:49], v[94:95]
	v_pk_add_f32 v[46:47], v[46:47], v[92:93]
	v_pk_add_f32 v[32:33], v[32:33], v[110:111]
	v_pk_add_f32 v[30:31], v[30:31], v[108:109]
	global_store_dwordx4 v[34:35], v[18:21], off offset:512
	s_waitcnt vmcnt(7)
	v_pk_add_f32 v[16:17], v[16:17], v[126:127]
	v_pk_add_f32 v[14:15], v[14:15], v[124:125]
	v_lshl_add_u64 v[18:19], s[8:9], 0, v[78:79]
	v_pk_add_f32 v[64:65], v[64:65], v[82:83]
	v_pk_add_f32 v[60:61], v[60:61], v[86:87]
	v_pk_add_f32 v[58:59], v[58:59], v[84:85]
	global_store_dwordx4 v[80:81], v[46:49], off offset:576
	v_pk_add_f32 v[44:45], v[44:45], v[102:103]
	v_pk_add_f32 v[42:43], v[42:43], v[100:101]
	v_pk_add_f32 v[48:49], v[56:57], v[98:99]
	v_pk_add_f32 v[46:47], v[54:55], v[96:97]
	global_store_dwordx4 v[50:51], v[30:33], off offset:576
	v_pk_add_f32 v[28:29], v[28:29], v[118:119]
	v_pk_add_f32 v[26:27], v[26:27], v[116:117]
	v_pk_add_f32 v[32:33], v[40:41], v[114:115]
	v_pk_add_f32 v[30:31], v[38:39], v[112:113]
	global_store_dwordx4 v[34:35], v[14:17], off offset:576
	v_lshl_add_u64 v[18:19], v[18:19], 0, v[148:149]
	s_waitcnt vmcnt(8)
	v_pk_add_f32 v[12:13], v[12:13], v[76:77]
	v_pk_add_f32 v[16:17], v[24:25], v[130:131]
	v_pk_add_f32 v[14:15], v[22:23], v[128:129]
	v_pk_add_f32 v[10:11], v[10:11], v[74:75]
	s_waitcnt vmcnt(7)
	v_pk_add_f32 v[8:9], v[8:9], v[72:73]
	v_pk_add_f32 v[6:7], v[6:7], v[70:71]
	s_waitcnt vmcnt(6)
	v_pk_add_f32 v[4:5], v[4:5], v[68:69]
	v_pk_add_f32 v[2:3], v[2:3], v[66:67]
	global_store_dwordx4 v[80:81], v[62:65], off
	global_store_dwordx4 v[80:81], v[58:61], off offset:64
	global_store_dwordx4 v[50:51], v[46:49], off
	global_store_dwordx4 v[50:51], v[42:45], off offset:64
	global_store_dwordx4 v[34:35], v[30:33], off
	global_store_dwordx4 v[34:35], v[26:29], off offset:64
	global_store_dwordx4 v[18:19], v[14:17], off
	global_store_dwordx4 v[18:19], v[10:13], off offset:64
	global_store_dwordx4 v[18:19], v[6:9], off offset:512
	global_store_dwordx4 v[18:19], v[2:5], off offset:576
	s_cbranch_vccnz .LBB0_351
	s_andn2_b64 vcc, exec, s[10:11]
	s_cbranch_vccnz .LBB0_350
	s_nop 0
	s_branch .LBB0_350
